# v30 + b64 accumulator zeroing + loop-top ds_reads first + 8-byte aligned MFMA blocks (combined)
# baseline (speedup 1.0000x reference)
; #define PG8_STAGEA(bufoff, gbase, voff) PG8_STAGE_X(bufoff, gbase, voff, PG8_AUX_A)
; #define PG8_STAGEB(bufoff, gbase, voff) PG8_STAGE_X(bufoff, gbase, voff, PG8_AUX_B)
; #define PG8_LDA(dst, b, h) do { _Pragma("unroll") for (int m = 0; m < 4; ++m) _Pragma("unroll") for (int k = 0; k < 2; ++k) dst[m][k] = *(const PG8_LAS bf16x8*)(lds + PG8_SA(b, h) + aoff + m * 2048 + k * 1024); } while (0)
; #define PG8_LDB(dst, b, h) do { _Pragma("unroll") for (int n = 0; n < 2; ++n) _Pragma("unroll") for (int k = 0; k < 2; ++k) dst[n][k] = *(const PG8_LAS bf16x8*)(lds + PG8_SB(b, h) + boff + n * 2048 + k * 1024); } while (0)
; #define PG8_MMA(ai, bj, At, Bt) do { __builtin_amdgcn_s_setprio(1); _Pragma("unroll") for (int m = 0; m < 4; ++m) _Pragma("unroll") for (int n = 0; n < 2; ++n) _Pragma("unroll") for (int k = 0; k < 2; ++k) \
;         acc[ai][bj][m][n] = __builtin_amdgcn_mfma_f32_16x16x32_bf16(Bt[n][k], At[m][k], acc[ai][bj][m][n], 0, 0, 0); __builtin_amdgcn_s_setprio(0); } while (0)
; #define PG8_WAIT_V(n) asm volatile("s_waitcnt vmcnt(" #n ")" ::: "memory")
; #define PG8_WAIT_L(n) asm volatile("s_waitcnt lgkmcnt(" #n ")" ::: "memory")
; template <class Epi, class Sched, bool ALIGN_EPI = false, bool SP2 = false>
; __device__ __forceinline__ void gemm_phase(PG8_LAS unsigned char* lds, const Gemm g, const Sched& S, const Epi& E) {
;     ...
;             const char* sA1 = (t + 1 >= ns) ? cA2 : cA; const char* sA2 = (t + 2 >= ns) ? cA2 : cA; const char* sB2 = (t + 2 >= ns) ? cB2 : cB;
;             const char* a1 = sA1 + (size_t)(t + 1) * kstep;
;             const char* a2 = last ? nA : sA2 + (size_t)(t + 2) * kstep; const char* b2 = last ? nB : sB2 + (size_t)(t + 2) * kstep;
;             const char* a3 = a2 + kstep; const char* b3 = b2 + kstep;
;             if (last && has_next) S.a_ready(nxt);
;             if constexpr (SP2) {
;             PG8_LDB(B0, 0, 0); PG8_LDB(B1, 0, 1); PG8_SCHED; PG8_LDA(At, 0, 0); PG8_STAGEA(PG8_SA(1, 1), a1 + hstep, voffA);
;             PG8_WAIT_V(8); PG8_WAIT_L(0); PG8_BAR; PG8_MMA(0, 0, At, B0); PG8_MMA(0, 1, At, B1); PG8_BAR; PG8_SCHED;
;             PG8_LDA(At, 0, 1); PG8_STAGEB(PG8_SB(0, 0), b2, voffB); PG8_STAGEB(PG8_SB(0, 1), b2 + hstep, voffB); PG8_STAGEA(PG8_SA(0, 0), a2, voffA);
;             PG8_WAIT_V(8); PG8_WAIT_L(0); PG8_BAR; PG8_MMA(1, 0, At, B0); PG8_MMA(1, 1, At, B1); PG8_BAR; PG8_SCHED;
.LBB0_94:
	ds_read_b128 v[134:137], v184
	ds_read_b128 v[138:141], v184 offset:1024
	ds_read_b128 v[142:145], v184 offset:2048
	ds_read_b128 v[170:173], v184 offset:3072
	ds_read_b128 v[174:177], v185
	ds_read_b128 v[178:181], v185 offset:1024
	ds_read_b128 v[190:193], v185 offset:2048
	ds_read_b128 v[194:197], v185 offset:3072
	ds_read_b128 v[198:201], v186
	ds_read_b128 v[202:205], v186 offset:1024
	ds_read_b128 v[206:209], v186 offset:2048
	ds_read_b128 v[210:213], v186 offset:3072
	ds_read_b128 v[214:217], v186 offset:4096
	ds_read_b128 v[218:221], v186 offset:5120
	ds_read_b128 v[222:225], v186 offset:6144
	ds_read_b128 v[226:229], v186 offset:7168
	s_add_i32 s71, s73, 2
	s_cmp_gt_u32 s71, 29
	s_cselect_b64 s[34:35], -1, 0
	s_and_b64 vcc, s[34:35], exec
	s_cselect_b32 s83, s60, s78
	s_cselect_b32 s34, s59, s9
	s_cselect_b32 s35, s58, s8
	s_cselect_b32 s82, s61, s79
	s_add_u32 s83, s83, s80
	s_addc_u32 s82, s82, s81
	s_add_u32 s83, s83, 0xfff80080
	s_addc_u32 s82, s82, -1
	s_add_u32 s35, s35, s80
	s_addc_u32 s34, s34, s81
	s_add_u32 s35, s35, 0xfff80080
	s_addc_u32 s34, s34, -1
	s_cmp_eq_u32 s73, 28
	s_cselect_b32 s85, s7, s82
	s_cselect_b32 s84, s26, s83
	s_cselect_b32 s83, s27, s34
	s_cselect_b32 s82, s57, s35
	v_lshl_add_u64 v[230:231], v[130:131], 0, s[80:81]
	s_add_i32 m0, s90, 0xc000
	global_load_lds_dwordx4 v[230:231], off
	v_lshl_add_u64 v[230:231], v[132:133], 0, s[80:81]
	s_add_i32 m0, s90, 0xe000
	s_nop 0
	global_load_lds_dwordx4 v[230:231], off
	s_waitcnt vmcnt(8)
	s_waitcnt lgkmcnt(0)
	s_barrier
	s_setprio 1
	s_waitcnt lgkmcnt(0)
	.p2align 3
	v_mfma_f32_16x16x32_bf16 v[126:129], v[134:137], v[198:201], v[126:129]
	v_mfma_f32_16x16x32_bf16 v[94:97], v[142:145], v[198:201], v[94:97]
	v_mfma_f32_16x16x32_bf16 v[122:125], v[134:137], v[206:209], v[122:125]
	v_mfma_f32_16x16x32_bf16 v[90:93], v[142:145], v[206:209], v[90:93]
	v_mfma_f32_16x16x32_bf16 v[118:121], v[134:137], v[214:217], v[118:121]
	v_mfma_f32_16x16x32_bf16 v[86:89], v[142:145], v[214:217], v[86:89]
	v_mfma_f32_16x16x32_bf16 v[114:117], v[134:137], v[222:225], v[114:117]
	v_mfma_f32_16x16x32_bf16 v[82:85], v[142:145], v[222:225], v[82:85]
	v_mfma_f32_16x16x32_bf16 v[126:129], v[138:141], v[202:205], v[126:129]
	v_mfma_f32_16x16x32_bf16 v[94:97], v[170:173], v[202:205], v[94:97]
	v_mfma_f32_16x16x32_bf16 v[122:125], v[138:141], v[210:213], v[122:125]
	v_mfma_f32_16x16x32_bf16 v[90:93], v[170:173], v[210:213], v[90:93]
	v_mfma_f32_16x16x32_bf16 v[118:121], v[138:141], v[218:221], v[118:121]
	v_mfma_f32_16x16x32_bf16 v[86:89], v[170:173], v[218:221], v[86:89]
	v_mfma_f32_16x16x32_bf16 v[114:117], v[138:141], v[226:229], v[114:117]
	v_mfma_f32_16x16x32_bf16 v[82:85], v[170:173], v[226:229], v[82:85]
	s_setprio 0
	s_setprio 1
	.p2align 3
	v_mfma_f32_16x16x32_bf16 v[62:65], v[174:177], v[198:201], v[62:65]
	v_mfma_f32_16x16x32_bf16 v[30:33], v[190:193], v[198:201], v[30:33]
	v_mfma_f32_16x16x32_bf16 v[58:61], v[174:177], v[206:209], v[58:61]
	v_mfma_f32_16x16x32_bf16 v[26:29], v[190:193], v[206:209], v[26:29]
	v_mfma_f32_16x16x32_bf16 v[54:57], v[174:177], v[214:217], v[54:57]
	v_mfma_f32_16x16x32_bf16 v[22:25], v[190:193], v[214:217], v[22:25]
	v_mfma_f32_16x16x32_bf16 v[50:53], v[174:177], v[222:225], v[50:53]
	v_mfma_f32_16x16x32_bf16 v[18:21], v[190:193], v[222:225], v[18:21]
	v_mfma_f32_16x16x32_bf16 v[62:65], v[178:181], v[202:205], v[62:65]
	v_mfma_f32_16x16x32_bf16 v[30:33], v[194:197], v[202:205], v[30:33]
	v_mfma_f32_16x16x32_bf16 v[58:61], v[178:181], v[210:213], v[58:61]
	v_mfma_f32_16x16x32_bf16 v[26:29], v[194:197], v[210:213], v[26:29]
	v_mfma_f32_16x16x32_bf16 v[54:57], v[178:181], v[218:221], v[54:57]
	v_mfma_f32_16x16x32_bf16 v[22:25], v[194:197], v[218:221], v[22:25]
	v_mfma_f32_16x16x32_bf16 v[50:53], v[178:181], v[226:229], v[50:53]
	v_mfma_f32_16x16x32_bf16 v[18:21], v[194:197], v[226:229], v[18:21]
	s_setprio 0
	s_barrier
	s_add_i32 s34, s97, s87
	v_lshl_add_u64 v[230:231], s[82:83], 0, v[148:149]
	s_mov_b32 m0, s34
	ds_read_b128 v[198:201], v186 offset:16384
	ds_read_b128 v[202:205], v186 offset:17408
	ds_read_b128 v[206:209], v186 offset:18432
	ds_read_b128 v[210:213], v186 offset:19456
	ds_read_b128 v[214:217], v186 offset:20480
	ds_read_b128 v[218:221], v186 offset:21504
	ds_read_b128 v[222:225], v186 offset:22528
	ds_read_b128 v[226:229], v186 offset:23552
	global_load_lds_dwordx4 v[230:231], off
	s_add_i32 m0, s34, 0x2000
	s_add_u32 s34, s82, 0x80000
	v_lshl_add_u64 v[232:233], s[82:83], 0, v[152:153]
	s_addc_u32 s35, s83, 0
	s_add_i32 s73, s11, s87
	global_load_lds_dwordx4 v[232:233], off
	v_lshl_add_u64 v[234:235], s[34:35], 0, v[148:149]
	s_mov_b32 m0, s73
	v_lshl_add_u64 v[236:237], s[84:85], 0, v[150:151]
	global_load_lds_dwordx4 v[234:235], off
	v_lshl_add_u64 v[234:235], s[34:35], 0, v[152:153]
	s_add_i32 m0, s73, 0x2000
	s_nop 0
	global_load_lds_dwordx4 v[234:235], off
	v_lshl_add_u64 v[234:235], s[84:85], 0, v[146:147]
	s_mov_b32 m0, s90
	s_nop 0
	global_load_lds_dwordx4 v[234:235], off
	s_mov_b32 m0, s91
	s_nop 0
	global_load_lds_dwordx4 v[236:237], off
	s_waitcnt vmcnt(8)
	s_waitcnt lgkmcnt(0)
	s_barrier
; #define PG8_STAGEA(bufoff, gbase, voff) PG8_STAGE_X(bufoff, gbase, voff, PG8_AUX_A)
; #define PG8_LDA(dst, b, h) do { _Pragma("unroll") for (int m = 0; m < 4; ++m) _Pragma("unroll") for (int k = 0; k < 2; ++k) dst[m][k] = *(const PG8_LAS bf16x8*)(lds + PG8_SA(b, h) + aoff + m * 2048 + k * 1024); } while (0)
; #define PG8_LDB(dst, b, h) do { _Pragma("unroll") for (int n = 0; n < 2; ++n) _Pragma("unroll") for (int k = 0; k < 2; ++k) dst[n][k] = *(const PG8_LAS bf16x8*)(lds + PG8_SB(b, h) + boff + n * 2048 + k * 1024); } while (0)
; #define PG8_MMA(ai, bj, At, Bt) do { __builtin_amdgcn_s_setprio(1); _Pragma("unroll") for (int m = 0; m < 4; ++m) _Pragma("unroll") for (int n = 0; n < 2; ++n) _Pragma("unroll") for (int k = 0; k < 2; ++k) \
;         acc[ai][bj][m][n] = __builtin_amdgcn_mfma_f32_16x16x32_bf16(Bt[n][k], At[m][k], acc[ai][bj][m][n], 0, 0, 0); __builtin_amdgcn_s_setprio(0); } while (0)
; #define PG8_WAIT_V(n) asm volatile("s_waitcnt vmcnt(" #n ")" ::: "memory")
; #define PG8_WAIT_L(n) asm volatile("s_waitcnt lgkmcnt(" #n ")" ::: "memory")
; #define PG8_BAR __builtin_amdgcn_s_barrier()
; #define PG8_SCHED __builtin_amdgcn_sched_barrier(0)
; template <class Epi, class Sched, bool ALIGN_EPI = false, bool SP2 = false>
; __device__ __forceinline__ void gemm_phase(PG8_LAS unsigned char* lds, const Gemm g, const Sched& S, const Epi& E) {
;     ...
;             PG8_WAIT_V(8); PG8_WAIT_L(0); PG8_BAR; PG8_MMA(1, 0, At, B0); PG8_MMA(1, 1, At, B1); PG8_BAR; PG8_SCHED;
;             PG8_LDB(B0, 1, 0); PG8_LDB(B1, 1, 1); PG8_SCHED; PG8_LDA(At, 1, 0); PG8_STAGEA(PG8_SA(0, 1), a2 + hstep, voffA);
;             PG8_WAIT_V(8); PG8_WAIT_L(0); PG8_BAR; PG8_MMA(0, 0, At, B0); PG8_MMA(0, 1, At, B1); PG8_BAR; PG8_SCHED;
	s_setprio 1
	s_waitcnt lgkmcnt(0)
	.p2align 3
	v_mfma_f32_16x16x32_bf16 v[110:113], v[134:137], v[198:201], v[110:113]
	v_mfma_f32_16x16x32_bf16 v[78:81], v[142:145], v[198:201], v[78:81]
	v_mfma_f32_16x16x32_bf16 v[106:109], v[134:137], v[206:209], v[106:109]
	v_mfma_f32_16x16x32_bf16 v[74:77], v[142:145], v[206:209], v[74:77]
	v_mfma_f32_16x16x32_bf16 v[102:105], v[134:137], v[214:217], v[102:105]
	v_mfma_f32_16x16x32_bf16 v[70:73], v[142:145], v[214:217], v[70:73]
	v_mfma_f32_16x16x32_bf16 v[98:101], v[134:137], v[222:225], v[98:101]
	v_mfma_f32_16x16x32_bf16 v[66:69], v[142:145], v[222:225], v[66:69]
	v_mfma_f32_16x16x32_bf16 v[110:113], v[138:141], v[202:205], v[110:113]
	v_mfma_f32_16x16x32_bf16 v[78:81], v[170:173], v[202:205], v[78:81]
	v_mfma_f32_16x16x32_bf16 v[106:109], v[138:141], v[210:213], v[106:109]
	v_mfma_f32_16x16x32_bf16 v[74:77], v[170:173], v[210:213], v[74:77]
	v_mfma_f32_16x16x32_bf16 v[102:105], v[138:141], v[218:221], v[102:105]
	v_mfma_f32_16x16x32_bf16 v[70:73], v[170:173], v[218:221], v[70:73]
	v_mfma_f32_16x16x32_bf16 v[98:101], v[138:141], v[226:229], v[98:101]
	v_mfma_f32_16x16x32_bf16 v[66:69], v[170:173], v[226:229], v[66:69]
	s_setprio 0
	s_setprio 1
	.p2align 3
	v_mfma_f32_16x16x32_bf16 v[46:49], v[174:177], v[198:201], v[46:49]
	v_mfma_f32_16x16x32_bf16 v[14:17], v[190:193], v[198:201], v[14:17]
	v_mfma_f32_16x16x32_bf16 v[42:45], v[174:177], v[206:209], v[42:45]
	v_mfma_f32_16x16x32_bf16 v[10:13], v[190:193], v[206:209], v[10:13]
	v_mfma_f32_16x16x32_bf16 v[38:41], v[174:177], v[214:217], v[38:41]
	v_mfma_f32_16x16x32_bf16 v[6:9], v[190:193], v[214:217], v[6:9]
	v_mfma_f32_16x16x32_bf16 v[34:37], v[174:177], v[222:225], v[34:37]
	v_mfma_f32_16x16x32_bf16 v[2:5], v[190:193], v[222:225], v[2:5]
	v_mfma_f32_16x16x32_bf16 v[46:49], v[178:181], v[202:205], v[46:49]
	v_mfma_f32_16x16x32_bf16 v[14:17], v[194:197], v[202:205], v[14:17]
	v_mfma_f32_16x16x32_bf16 v[42:45], v[178:181], v[210:213], v[42:45]
	v_mfma_f32_16x16x32_bf16 v[10:13], v[194:197], v[210:213], v[10:13]
	v_mfma_f32_16x16x32_bf16 v[38:41], v[178:181], v[218:221], v[38:41]
	v_mfma_f32_16x16x32_bf16 v[6:9], v[194:197], v[218:221], v[6:9]
	v_mfma_f32_16x16x32_bf16 v[34:37], v[178:181], v[226:229], v[34:37]
	v_mfma_f32_16x16x32_bf16 v[2:5], v[194:197], v[226:229], v[2:5]
	s_setprio 0
	s_barrier
	s_add_i32 s73, 0, 0x18000
	v_add_u32_e32 v154, s73, v182
	s_add_i32 s54, 0, 0x1c000
	ds_read_b128 v[134:137], v154
	ds_read_b128 v[138:141], v154 offset:1024
	ds_read_b128 v[142:145], v154 offset:2048
	ds_read_b128 v[170:173], v154 offset:3072
	v_add_u32_e32 v154, s54, v182
	ds_read_b128 v[174:177], v154
	ds_read_b128 v[178:181], v154 offset:1024
	ds_read_b128 v[190:193], v154 offset:2048
	ds_read_b128 v[194:197], v154 offset:3072
	s_add_u32 s34, s84, 0x80000
	s_addc_u32 s35, s85, 0
	s_mov_b32 m0, s92
	v_lshl_add_u64 v[238:239], s[34:35], 0, v[146:147]
	ds_read_b128 v[198:201], v186 offset:32768
	ds_read_b128 v[202:205], v186 offset:33792
	ds_read_b128 v[206:209], v186 offset:34816
	ds_read_b128 v[210:213], v186 offset:35840
	ds_read_b128 v[214:217], v186 offset:36864
	ds_read_b128 v[218:221], v186 offset:37888
	ds_read_b128 v[222:225], v186 offset:38912
	ds_read_b128 v[226:229], v186 offset:39936
	global_load_lds_dwordx4 v[238:239], off
	v_lshl_add_u64 v[238:239], s[34:35], 0, v[150:151]
	s_mov_b32 m0, s93
	s_nop 0
	global_load_lds_dwordx4 v[238:239], off
	s_waitcnt vmcnt(8)
	s_waitcnt lgkmcnt(0)
	s_barrier
	s_setprio 1
	s_waitcnt lgkmcnt(0)
	.p2align 3
	v_mfma_f32_16x16x32_bf16 v[126:129], v[134:137], v[198:201], v[126:129]
	v_mfma_f32_16x16x32_bf16 v[94:97], v[142:145], v[198:201], v[94:97]
	v_mfma_f32_16x16x32_bf16 v[122:125], v[134:137], v[206:209], v[122:125]
	v_mfma_f32_16x16x32_bf16 v[90:93], v[142:145], v[206:209], v[90:93]
	v_mfma_f32_16x16x32_bf16 v[118:121], v[134:137], v[214:217], v[118:121]
	v_mfma_f32_16x16x32_bf16 v[86:89], v[142:145], v[214:217], v[86:89]
	v_mfma_f32_16x16x32_bf16 v[114:117], v[134:137], v[222:225], v[114:117]
	v_mfma_f32_16x16x32_bf16 v[82:85], v[142:145], v[222:225], v[82:85]
	v_mfma_f32_16x16x32_bf16 v[126:129], v[138:141], v[202:205], v[126:129]
	v_mfma_f32_16x16x32_bf16 v[94:97], v[170:173], v[202:205], v[94:97]
	v_mfma_f32_16x16x32_bf16 v[122:125], v[138:141], v[210:213], v[122:125]
	v_mfma_f32_16x16x32_bf16 v[90:93], v[170:173], v[210:213], v[90:93]
	v_mfma_f32_16x16x32_bf16 v[118:121], v[138:141], v[218:221], v[118:121]
	v_mfma_f32_16x16x32_bf16 v[86:89], v[170:173], v[218:221], v[86:89]
	v_mfma_f32_16x16x32_bf16 v[114:117], v[138:141], v[226:229], v[114:117]
	v_mfma_f32_16x16x32_bf16 v[82:85], v[170:173], v[226:229], v[82:85]
	s_setprio 0
	s_setprio 1
	.p2align 3
	v_mfma_f32_16x16x32_bf16 v[62:65], v[174:177], v[198:201], v[62:65]
	v_mfma_f32_16x16x32_bf16 v[30:33], v[190:193], v[198:201], v[30:33]
	v_mfma_f32_16x16x32_bf16 v[58:61], v[174:177], v[206:209], v[58:61]
	v_mfma_f32_16x16x32_bf16 v[26:29], v[190:193], v[206:209], v[26:29]
	v_mfma_f32_16x16x32_bf16 v[54:57], v[174:177], v[214:217], v[54:57]
	v_mfma_f32_16x16x32_bf16 v[22:25], v[190:193], v[214:217], v[22:25]
	v_mfma_f32_16x16x32_bf16 v[50:53], v[174:177], v[222:225], v[50:53]
	v_mfma_f32_16x16x32_bf16 v[18:21], v[190:193], v[222:225], v[18:21]
	v_mfma_f32_16x16x32_bf16 v[62:65], v[178:181], v[202:205], v[62:65]
	v_mfma_f32_16x16x32_bf16 v[30:33], v[194:197], v[202:205], v[30:33]
	v_mfma_f32_16x16x32_bf16 v[58:61], v[178:181], v[210:213], v[58:61]
	v_mfma_f32_16x16x32_bf16 v[26:29], v[194:197], v[210:213], v[26:29]
	v_mfma_f32_16x16x32_bf16 v[54:57], v[178:181], v[218:221], v[54:57]
	v_mfma_f32_16x16x32_bf16 v[22:25], v[194:197], v[218:221], v[22:25]
	v_mfma_f32_16x16x32_bf16 v[50:53], v[178:181], v[226:229], v[50:53]
	v_mfma_f32_16x16x32_bf16 v[18:21], v[194:197], v[226:229], v[18:21]
	s_setprio 0
	s_barrier
; #define PG8_STAGEA(bufoff, gbase, voff) PG8_STAGE_X(bufoff, gbase, voff, PG8_AUX_A)
; #define PG8_STAGEB(bufoff, gbase, voff) PG8_STAGE_X(bufoff, gbase, voff, PG8_AUX_B)
; #define PG8_LDA(dst, b, h) do { _Pragma("unroll") for (int m = 0; m < 4; ++m) _Pragma("unroll") for (int k = 0; k < 2; ++k) dst[m][k] = *(const PG8_LAS bf16x8*)(lds + PG8_SA(b, h) + aoff + m * 2048 + k * 1024); } while (0)
; #define PG8_MMA(ai, bj, At, Bt) do { __builtin_amdgcn_s_setprio(1); _Pragma("unroll") for (int m = 0; m < 4; ++m) _Pragma("unroll") for (int n = 0; n < 2; ++n) _Pragma("unroll") for (int k = 0; k < 2; ++k) \
;         acc[ai][bj][m][n] = __builtin_amdgcn_mfma_f32_16x16x32_bf16(Bt[n][k], At[m][k], acc[ai][bj][m][n], 0, 0, 0); __builtin_amdgcn_s_setprio(0); } while (0)
; #define PG8_WAIT_V(n) asm volatile("s_waitcnt vmcnt(" #n ")" ::: "memory")
; #define PG8_WAIT_L(n) asm volatile("s_waitcnt lgkmcnt(" #n ")" ::: "memory")
; #define PG8_BAR __builtin_amdgcn_s_barrier()
; #define PG8_SCHED __builtin_amdgcn_sched_barrier(0)
; template <class Epi, class Sched, bool ALIGN_EPI = false, bool SP2 = false>
; __device__ __forceinline__ void gemm_phase(PG8_LAS unsigned char* lds, const Gemm g, const Sched& S, const Epi& E) {
;     ...
;             PG8_LDA(At, 1, 1); PG8_STAGEB(PG8_SB(1, 0), b3, voffB); PG8_STAGEB(PG8_SB(1, 1), b3 + hstep, voffB); PG8_STAGEA(PG8_SA(1, 0), a3, voffA);
;             PG8_WAIT_V(8); PG8_WAIT_L(0); PG8_BAR; PG8_MMA(1, 0, At, B0); PG8_MMA(1, 1, At, B1); PG8_BAR; PG8_SCHED;
;     ...
;         if constexpr (ALIGN_EPI) { if (wr == 0) PG8_BAR; }
	s_add_i32 s34, s73, s87
	v_lshl_add_u64 v[230:231], v[230:231], 0, s[64:65]
	s_mov_b32 m0, s34
	ds_read_b128 v[198:201], v186 offset:49152
	ds_read_b128 v[202:205], v186 offset:50176
	ds_read_b128 v[206:209], v186 offset:51200
	ds_read_b128 v[210:213], v186 offset:52224
	ds_read_b128 v[214:217], v186 offset:53248
	ds_read_b128 v[218:221], v186 offset:54272
	ds_read_b128 v[222:225], v186 offset:55296
	ds_read_b128 v[226:229], v186 offset:56320
	global_load_lds_dwordx4 v[230:231], off
	s_add_i32 m0, s34, 0x2000
	s_add_u32 s34, s82, 0x80080
	v_lshl_add_u64 v[230:231], v[232:233], 0, s[64:65]
	s_addc_u32 s35, s83, 0
	s_add_i32 s54, s54, s87
	global_load_lds_dwordx4 v[230:231], off
	v_lshl_add_u64 v[230:231], s[34:35], 0, v[148:149]
	s_mov_b32 m0, s54
	s_nop 0
	global_load_lds_dwordx4 v[230:231], off
	v_lshl_add_u64 v[230:231], s[34:35], 0, v[152:153]
	s_add_i32 m0, s54, 0x2000
	s_nop 0
	global_load_lds_dwordx4 v[230:231], off
	v_lshl_add_u64 v[230:231], v[234:235], 0, s[64:65]
	s_mov_b32 m0, s95
	s_nop 0
	global_load_lds_dwordx4 v[230:231], off
	v_lshl_add_u64 v[230:231], v[236:237], 0, s[64:65]
	s_mov_b32 m0, s96
	s_nop 0
	global_load_lds_dwordx4 v[230:231], off
	s_waitcnt vmcnt(8)
	s_waitcnt lgkmcnt(0)
	s_barrier
	s_setprio 1
	s_waitcnt lgkmcnt(0)
	.p2align 3
	v_mfma_f32_16x16x32_bf16 v[110:113], v[134:137], v[198:201], v[110:113]
	v_mfma_f32_16x16x32_bf16 v[78:81], v[142:145], v[198:201], v[78:81]
	v_mfma_f32_16x16x32_bf16 v[106:109], v[134:137], v[206:209], v[106:109]
	v_mfma_f32_16x16x32_bf16 v[74:77], v[142:145], v[206:209], v[74:77]
	v_mfma_f32_16x16x32_bf16 v[102:105], v[134:137], v[214:217], v[102:105]
	v_mfma_f32_16x16x32_bf16 v[70:73], v[142:145], v[214:217], v[70:73]
	v_mfma_f32_16x16x32_bf16 v[98:101], v[134:137], v[222:225], v[98:101]
	v_mfma_f32_16x16x32_bf16 v[66:69], v[142:145], v[222:225], v[66:69]
	v_mfma_f32_16x16x32_bf16 v[110:113], v[138:141], v[202:205], v[110:113]
	v_mfma_f32_16x16x32_bf16 v[78:81], v[170:173], v[202:205], v[78:81]
	v_mfma_f32_16x16x32_bf16 v[106:109], v[138:141], v[210:213], v[106:109]
	v_mfma_f32_16x16x32_bf16 v[74:77], v[170:173], v[210:213], v[74:77]
	v_mfma_f32_16x16x32_bf16 v[102:105], v[138:141], v[218:221], v[102:105]
	v_mfma_f32_16x16x32_bf16 v[70:73], v[170:173], v[218:221], v[70:73]
	v_mfma_f32_16x16x32_bf16 v[98:101], v[138:141], v[226:229], v[98:101]
	v_mfma_f32_16x16x32_bf16 v[66:69], v[170:173], v[226:229], v[66:69]
	s_setprio 0
	s_setprio 1
	.p2align 3
	v_mfma_f32_16x16x32_bf16 v[46:49], v[174:177], v[198:201], v[46:49]
	v_mfma_f32_16x16x32_bf16 v[14:17], v[190:193], v[198:201], v[14:17]
	v_mfma_f32_16x16x32_bf16 v[42:45], v[174:177], v[206:209], v[42:45]
	v_mfma_f32_16x16x32_bf16 v[10:13], v[190:193], v[206:209], v[10:13]
	v_mfma_f32_16x16x32_bf16 v[38:41], v[174:177], v[214:217], v[38:41]
	v_mfma_f32_16x16x32_bf16 v[6:9], v[190:193], v[214:217], v[6:9]
	v_mfma_f32_16x16x32_bf16 v[34:37], v[174:177], v[222:225], v[34:37]
	v_mfma_f32_16x16x32_bf16 v[2:5], v[190:193], v[222:225], v[2:5]
	v_mfma_f32_16x16x32_bf16 v[46:49], v[178:181], v[202:205], v[46:49]
	v_mfma_f32_16x16x32_bf16 v[14:17], v[194:197], v[202:205], v[14:17]
	v_mfma_f32_16x16x32_bf16 v[42:45], v[178:181], v[210:213], v[42:45]
	v_mfma_f32_16x16x32_bf16 v[10:13], v[194:197], v[210:213], v[10:13]
	v_mfma_f32_16x16x32_bf16 v[38:41], v[178:181], v[218:221], v[38:41]
	v_mfma_f32_16x16x32_bf16 v[6:9], v[194:197], v[218:221], v[6:9]
	v_mfma_f32_16x16x32_bf16 v[34:37], v[178:181], v[226:229], v[34:37]
	v_mfma_f32_16x16x32_bf16 v[2:5], v[194:197], v[226:229], v[2:5]
	s_setprio 0
	s_barrier
	s_add_u32 s80, s80, 0x100
	s_addc_u32 s81, s81, 0
	s_mov_b32 s73, s71
	s_cbranch_vccz .LBB0_94
	s_and_b64 vcc, exec, s[66:67]
	s_cbranch_vccz .LBB0_97
	s_barrier

; #define PG8_STAGEA(bufoff, gbase, voff) PG8_STAGE_X(bufoff, gbase, voff, PG8_AUX_A)
; #define PG8_STAGEB(bufoff, gbase, voff) PG8_STAGE_X(bufoff, gbase, voff, PG8_AUX_B)
; #define PG8_LDA(dst, b, h) do { _Pragma("unroll") for (int m = 0; m < 4; ++m) _Pragma("unroll") for (int k = 0; k < 2; ++k) dst[m][k] = *(const PG8_LAS bf16x8*)(lds + PG8_SA(b, h) + aoff + m * 2048 + k * 1024); } while (0)
; #define PG8_LDB(dst, b, h) do { _Pragma("unroll") for (int n = 0; n < 2; ++n) _Pragma("unroll") for (int k = 0; k < 2; ++k) dst[n][k] = *(const PG8_LAS bf16x8*)(lds + PG8_SB(b, h) + boff + n * 2048 + k * 1024); } while (0)
; #define PG8_MMA(ai, bj, At, Bt) do { __builtin_amdgcn_s_setprio(1); _Pragma("unroll") for (int m = 0; m < 4; ++m) _Pragma("unroll") for (int n = 0; n < 2; ++n) _Pragma("unroll") for (int k = 0; k < 2; ++k) \
;         acc[ai][bj][m][n] = __builtin_amdgcn_mfma_f32_16x16x32_bf16(Bt[n][k], At[m][k], acc[ai][bj][m][n], 0, 0, 0); __builtin_amdgcn_s_setprio(0); } while (0)
; #define PG8_WAIT_V(n) asm volatile("s_waitcnt vmcnt(" #n ")" ::: "memory")
; #define PG8_WAIT_L(n) asm volatile("s_waitcnt lgkmcnt(" #n ")" ::: "memory")
; template <class Epi, class Sched, bool ALIGN_EPI = false, bool SP2 = false>
; __device__ __forceinline__ void gemm_phase(PG8_LAS unsigned char* lds, const Gemm g, const Sched& S, const Epi& E) {
;     ...
;             const char* sA1 = (t + 1 >= ns) ? cA2 : cA; const char* sA2 = (t + 2 >= ns) ? cA2 : cA; const char* sB2 = (t + 2 >= ns) ? cB2 : cB;
;             const char* a1 = sA1 + (size_t)(t + 1) * kstep;
;             const char* a2 = last ? nA : sA2 + (size_t)(t + 2) * kstep; const char* b2 = last ? nB : sB2 + (size_t)(t + 2) * kstep;
;             const char* a3 = a2 + kstep; const char* b3 = b2 + kstep;
;             if (last && has_next) S.a_ready(nxt);
;             if constexpr (SP2) {
;             PG8_LDB(B0, 0, 0); PG8_LDB(B1, 0, 1); PG8_SCHED; PG8_LDA(At, 0, 0); PG8_STAGEA(PG8_SA(1, 1), a1 + hstep, voffA);
;             PG8_WAIT_V(8); PG8_WAIT_L(0); PG8_BAR; PG8_MMA(0, 0, At, B0); PG8_MMA(0, 1, At, B1); PG8_BAR; PG8_SCHED;
;             PG8_LDA(At, 0, 1); PG8_STAGEB(PG8_SB(0, 0), b2, voffB); PG8_STAGEB(PG8_SB(0, 1), b2 + hstep, voffB); PG8_STAGEA(PG8_SA(0, 0), a2, voffA);
;             PG8_WAIT_V(8); PG8_WAIT_L(0); PG8_BAR; PG8_MMA(1, 0, At, B0); PG8_MMA(1, 1, At, B1); PG8_BAR; PG8_SCHED;
.LBB0_295:
	ds_read_b128 v[156:159], v152
	ds_read_b128 v[160:163], v152 offset:1024
	ds_read_b128 v[164:167], v152 offset:2048
	ds_read_b128 v[168:171], v152 offset:3072
	ds_read_b128 v[172:175], v153
	ds_read_b128 v[176:179], v153 offset:1024
	ds_read_b128 v[180:183], v153 offset:2048
	ds_read_b128 v[184:187], v153 offset:3072
	ds_read_b128 v[188:191], v154
	ds_read_b128 v[192:195], v154 offset:1024
	ds_read_b128 v[196:199], v154 offset:2048
	ds_read_b128 v[200:203], v154 offset:3072
	ds_read_b128 v[204:207], v154 offset:4096
	ds_read_b128 v[208:211], v154 offset:5120
	ds_read_b128 v[212:215], v154 offset:6144
	ds_read_b128 v[216:219], v154 offset:7168
	s_add_i32 s92, s74, 2
	s_cmp_gt_u32 s92, 29
	s_cselect_b64 s[34:35], -1, 0
	s_and_b64 vcc, s[34:35], exec
	s_cselect_b32 s76, s6, s70
	s_cselect_b32 s34, s5, s69
	s_cselect_b32 s35, s4, s68
	s_cselect_b32 s75, s7, s71
	s_add_u32 s76, s76, s72
	s_addc_u32 s75, s75, s73
	s_add_u32 s76, s76, 0xfff80080
	s_addc_u32 s75, s75, -1
	s_add_u32 s35, s35, s72
	s_addc_u32 s34, s34, s73
	s_add_u32 s35, s35, 0xfff80080
	s_addc_u32 s34, s34, -1
	s_cmp_eq_u32 s74, 28
	s_cselect_b32 s74, s91, s35
	s_cselect_b32 s77, s61, s75
	s_cselect_b32 s76, s90, s76
	s_cselect_b32 s75, s59, s34
	v_lshl_add_u64 v[220:221], v[146:147], 0, s[72:73]
	s_add_i32 m0, s67, 0xc000
	global_load_lds_dwordx4 v[220:221], off
	v_lshl_add_u64 v[220:221], v[148:149], 0, s[72:73]
	s_add_i32 m0, s67, 0xe000
	s_nop 0
	global_load_lds_dwordx4 v[220:221], off
	s_waitcnt vmcnt(8)
	s_waitcnt lgkmcnt(0)
	s_barrier
	s_setprio 1
	s_waitcnt lgkmcnt(0)
	.p2align 3
	v_mfma_f32_16x16x32_bf16 v[126:129], v[156:159], v[188:191], v[126:129]
	v_mfma_f32_16x16x32_bf16 v[122:125], v[164:167], v[188:191], v[122:125]
	v_mfma_f32_16x16x32_bf16 v[118:121], v[156:159], v[196:199], v[118:121]
	v_mfma_f32_16x16x32_bf16 v[110:113], v[164:167], v[196:199], v[110:113]
	v_mfma_f32_16x16x32_bf16 v[102:105], v[156:159], v[204:207], v[102:105]
	v_mfma_f32_16x16x32_bf16 v[94:97], v[164:167], v[204:207], v[94:97]
	v_mfma_f32_16x16x32_bf16 v[86:89], v[156:159], v[212:215], v[86:89]
	v_mfma_f32_16x16x32_bf16 v[78:81], v[164:167], v[212:215], v[78:81]
	v_mfma_f32_16x16x32_bf16 v[126:129], v[160:163], v[192:195], v[126:129]
	v_mfma_f32_16x16x32_bf16 v[122:125], v[168:171], v[192:195], v[122:125]
	v_mfma_f32_16x16x32_bf16 v[118:121], v[160:163], v[200:203], v[118:121]
	v_mfma_f32_16x16x32_bf16 v[110:113], v[168:171], v[200:203], v[110:113]
	v_mfma_f32_16x16x32_bf16 v[102:105], v[160:163], v[208:211], v[102:105]
	v_mfma_f32_16x16x32_bf16 v[94:97], v[168:171], v[208:211], v[94:97]
	v_mfma_f32_16x16x32_bf16 v[86:89], v[160:163], v[216:219], v[86:89]
	v_mfma_f32_16x16x32_bf16 v[78:81], v[168:171], v[216:219], v[78:81]
	s_setprio 0
	s_setprio 1
	.p2align 3
	v_mfma_f32_16x16x32_bf16 v[114:117], v[172:175], v[188:191], v[114:117]
	v_mfma_f32_16x16x32_bf16 v[106:109], v[180:183], v[188:191], v[106:109]
	v_mfma_f32_16x16x32_bf16 v[98:101], v[172:175], v[196:199], v[98:101]
	v_mfma_f32_16x16x32_bf16 v[90:93], v[180:183], v[196:199], v[90:93]
	v_mfma_f32_16x16x32_bf16 v[82:85], v[172:175], v[204:207], v[82:85]
	v_mfma_f32_16x16x32_bf16 v[74:77], v[180:183], v[204:207], v[74:77]
	v_mfma_f32_16x16x32_bf16 v[70:73], v[172:175], v[212:215], v[70:73]
	v_mfma_f32_16x16x32_bf16 v[66:69], v[180:183], v[212:215], v[66:69]
	v_mfma_f32_16x16x32_bf16 v[114:117], v[176:179], v[192:195], v[114:117]
	v_mfma_f32_16x16x32_bf16 v[106:109], v[184:187], v[192:195], v[106:109]
	v_mfma_f32_16x16x32_bf16 v[98:101], v[176:179], v[200:203], v[98:101]
	v_mfma_f32_16x16x32_bf16 v[90:93], v[184:187], v[200:203], v[90:93]
	v_mfma_f32_16x16x32_bf16 v[82:85], v[176:179], v[208:211], v[82:85]
	v_mfma_f32_16x16x32_bf16 v[74:77], v[184:187], v[208:211], v[74:77]
	v_mfma_f32_16x16x32_bf16 v[70:73], v[176:179], v[216:219], v[70:73]
	v_mfma_f32_16x16x32_bf16 v[66:69], v[184:187], v[216:219], v[66:69]
	s_setprio 0
	s_barrier
	s_add_i32 s34, s84, s11
	v_lshl_add_u64 v[220:221], s[74:75], 0, v[134:135]
	s_mov_b32 m0, s34
	ds_read_b128 v[188:191], v154 offset:16384
	ds_read_b128 v[192:195], v154 offset:17408
	ds_read_b128 v[196:199], v154 offset:18432
	ds_read_b128 v[200:203], v154 offset:19456
	ds_read_b128 v[204:207], v154 offset:20480
	ds_read_b128 v[208:211], v154 offset:21504
	ds_read_b128 v[212:215], v154 offset:22528
	ds_read_b128 v[216:219], v154 offset:23552
	global_load_lds_dwordx4 v[220:221], off
	s_add_i32 m0, s34, 0x2000
	s_add_u32 s34, s74, 0x80000
	v_lshl_add_u64 v[222:223], s[74:75], 0, v[130:131]
	s_addc_u32 s35, s75, 0
	s_add_i32 s93, s85, s11
	global_load_lds_dwordx4 v[222:223], off
	v_lshl_add_u64 v[224:225], s[34:35], 0, v[134:135]
	s_mov_b32 m0, s93
	v_lshl_add_u64 v[226:227], s[76:77], 0, v[132:133]
	global_load_lds_dwordx4 v[224:225], off
	v_lshl_add_u64 v[224:225], s[34:35], 0, v[130:131]
	s_add_i32 m0, s93, 0x2000
	s_nop 0
	global_load_lds_dwordx4 v[224:225], off
	v_lshl_add_u64 v[224:225], s[76:77], 0, v[136:137]
	s_mov_b32 m0, s67
	s_nop 0
	global_load_lds_dwordx4 v[224:225], off
	s_mov_b32 m0, s78
	s_nop 0
	global_load_lds_dwordx4 v[226:227], off
	s_waitcnt vmcnt(8)
	s_waitcnt lgkmcnt(0)
	s_barrier
; #define PG8_STAGEA(bufoff, gbase, voff) PG8_STAGE_X(bufoff, gbase, voff, PG8_AUX_A)
; #define PG8_LDA(dst, b, h) do { _Pragma("unroll") for (int m = 0; m < 4; ++m) _Pragma("unroll") for (int k = 0; k < 2; ++k) dst[m][k] = *(const PG8_LAS bf16x8*)(lds + PG8_SA(b, h) + aoff + m * 2048 + k * 1024); } while (0)
; #define PG8_LDB(dst, b, h) do { _Pragma("unroll") for (int n = 0; n < 2; ++n) _Pragma("unroll") for (int k = 0; k < 2; ++k) dst[n][k] = *(const PG8_LAS bf16x8*)(lds + PG8_SB(b, h) + boff + n * 2048 + k * 1024); } while (0)
; #define PG8_MMA(ai, bj, At, Bt) do { __builtin_amdgcn_s_setprio(1); _Pragma("unroll") for (int m = 0; m < 4; ++m) _Pragma("unroll") for (int n = 0; n < 2; ++n) _Pragma("unroll") for (int k = 0; k < 2; ++k) \
;         acc[ai][bj][m][n] = __builtin_amdgcn_mfma_f32_16x16x32_bf16(Bt[n][k], At[m][k], acc[ai][bj][m][n], 0, 0, 0); __builtin_amdgcn_s_setprio(0); } while (0)
; #define PG8_WAIT_V(n) asm volatile("s_waitcnt vmcnt(" #n ")" ::: "memory")
; #define PG8_WAIT_L(n) asm volatile("s_waitcnt lgkmcnt(" #n ")" ::: "memory")
; #define PG8_BAR __builtin_amdgcn_s_barrier()
; #define PG8_SCHED __builtin_amdgcn_sched_barrier(0)
; template <class Epi, class Sched, bool ALIGN_EPI = false, bool SP2 = false>
; __device__ __forceinline__ void gemm_phase(PG8_LAS unsigned char* lds, const Gemm g, const Sched& S, const Epi& E) {
;     ...
;             PG8_WAIT_V(8); PG8_WAIT_L(0); PG8_BAR; PG8_MMA(1, 0, At, B0); PG8_MMA(1, 1, At, B1); PG8_BAR; PG8_SCHED;
;             PG8_LDB(B0, 1, 0); PG8_LDB(B1, 1, 1); PG8_SCHED; PG8_LDA(At, 1, 0); PG8_STAGEA(PG8_SA(0, 1), a2 + hstep, voffA);
;             PG8_WAIT_V(8); PG8_WAIT_L(0); PG8_BAR; PG8_MMA(0, 0, At, B0); PG8_MMA(0, 1, At, B1); PG8_BAR; PG8_SCHED;
	s_setprio 1
	s_waitcnt lgkmcnt(0)
	.p2align 3
	v_mfma_f32_16x16x32_bf16 v[62:65], v[156:159], v[188:191], v[62:65]
	v_mfma_f32_16x16x32_bf16 v[58:61], v[164:167], v[188:191], v[58:61]
	v_mfma_f32_16x16x32_bf16 v[54:57], v[156:159], v[196:199], v[54:57]
	v_mfma_f32_16x16x32_bf16 v[46:49], v[164:167], v[196:199], v[46:49]
	v_mfma_f32_16x16x32_bf16 v[38:41], v[156:159], v[204:207], v[38:41]
	v_mfma_f32_16x16x32_bf16 v[30:33], v[164:167], v[204:207], v[30:33]
	v_mfma_f32_16x16x32_bf16 v[22:25], v[156:159], v[212:215], v[22:25]
	v_mfma_f32_16x16x32_bf16 v[14:17], v[164:167], v[212:215], v[14:17]
	v_mfma_f32_16x16x32_bf16 v[62:65], v[160:163], v[192:195], v[62:65]
	v_mfma_f32_16x16x32_bf16 v[58:61], v[168:171], v[192:195], v[58:61]
	v_mfma_f32_16x16x32_bf16 v[54:57], v[160:163], v[200:203], v[54:57]
	v_mfma_f32_16x16x32_bf16 v[46:49], v[168:171], v[200:203], v[46:49]
	v_mfma_f32_16x16x32_bf16 v[38:41], v[160:163], v[208:211], v[38:41]
	v_mfma_f32_16x16x32_bf16 v[30:33], v[168:171], v[208:211], v[30:33]
	v_mfma_f32_16x16x32_bf16 v[22:25], v[160:163], v[216:219], v[22:25]
	v_mfma_f32_16x16x32_bf16 v[14:17], v[168:171], v[216:219], v[14:17]
	s_setprio 0
	s_setprio 1
	.p2align 3
	v_mfma_f32_16x16x32_bf16 v[50:53], v[172:175], v[188:191], v[50:53]
	v_mfma_f32_16x16x32_bf16 v[42:45], v[180:183], v[188:191], v[42:45]
	v_mfma_f32_16x16x32_bf16 v[34:37], v[172:175], v[196:199], v[34:37]
	v_mfma_f32_16x16x32_bf16 v[26:29], v[180:183], v[196:199], v[26:29]
	v_mfma_f32_16x16x32_bf16 v[18:21], v[172:175], v[204:207], v[18:21]
	v_mfma_f32_16x16x32_bf16 v[10:13], v[180:183], v[204:207], v[10:13]
	v_mfma_f32_16x16x32_bf16 v[6:9], v[172:175], v[212:215], v[6:9]
	v_mfma_f32_16x16x32_bf16 v[2:5], v[180:183], v[212:215], v[2:5]
	v_mfma_f32_16x16x32_bf16 v[50:53], v[176:179], v[192:195], v[50:53]
	v_mfma_f32_16x16x32_bf16 v[42:45], v[184:187], v[192:195], v[42:45]
	v_mfma_f32_16x16x32_bf16 v[34:37], v[176:179], v[200:203], v[34:37]
	v_mfma_f32_16x16x32_bf16 v[26:29], v[184:187], v[200:203], v[26:29]
	v_mfma_f32_16x16x32_bf16 v[18:21], v[176:179], v[208:211], v[18:21]
	v_mfma_f32_16x16x32_bf16 v[10:13], v[184:187], v[208:211], v[10:13]
	v_mfma_f32_16x16x32_bf16 v[6:9], v[176:179], v[216:219], v[6:9]
	v_mfma_f32_16x16x32_bf16 v[2:5], v[184:187], v[216:219], v[2:5]
	s_setprio 0
	s_barrier
	s_add_i32 s93, 0, 0x18000
	v_add_u32_e32 v155, s93, v150
	s_add_i32 s94, 0, 0x1c000
	ds_read_b128 v[156:159], v155
	ds_read_b128 v[160:163], v155 offset:1024
	ds_read_b128 v[164:167], v155 offset:2048
	ds_read_b128 v[168:171], v155 offset:3072
	v_add_u32_e32 v155, s94, v150
	ds_read_b128 v[172:175], v155
	ds_read_b128 v[176:179], v155 offset:1024
	ds_read_b128 v[180:183], v155 offset:2048
	ds_read_b128 v[184:187], v155 offset:3072
	s_add_u32 s34, s76, 0x80000
	s_addc_u32 s35, s77, 0
	s_mov_b32 m0, s79
	v_lshl_add_u64 v[228:229], s[34:35], 0, v[136:137]
	ds_read_b128 v[188:191], v154 offset:32768
	ds_read_b128 v[192:195], v154 offset:33792
	ds_read_b128 v[196:199], v154 offset:34816
	ds_read_b128 v[200:203], v154 offset:35840
	ds_read_b128 v[204:207], v154 offset:36864
	ds_read_b128 v[208:211], v154 offset:37888
	ds_read_b128 v[212:215], v154 offset:38912
	ds_read_b128 v[216:219], v154 offset:39936
	global_load_lds_dwordx4 v[228:229], off
	v_lshl_add_u64 v[228:229], s[34:35], 0, v[132:133]
	s_mov_b32 m0, s80
	s_nop 0
	global_load_lds_dwordx4 v[228:229], off
	s_waitcnt vmcnt(8)
	s_waitcnt lgkmcnt(0)
	s_barrier
	s_setprio 1
	s_waitcnt lgkmcnt(0)
	.p2align 3
	v_mfma_f32_16x16x32_bf16 v[126:129], v[156:159], v[188:191], v[126:129]
	v_mfma_f32_16x16x32_bf16 v[122:125], v[164:167], v[188:191], v[122:125]
	v_mfma_f32_16x16x32_bf16 v[118:121], v[156:159], v[196:199], v[118:121]
	v_mfma_f32_16x16x32_bf16 v[110:113], v[164:167], v[196:199], v[110:113]
	v_mfma_f32_16x16x32_bf16 v[102:105], v[156:159], v[204:207], v[102:105]
	v_mfma_f32_16x16x32_bf16 v[94:97], v[164:167], v[204:207], v[94:97]
	v_mfma_f32_16x16x32_bf16 v[86:89], v[156:159], v[212:215], v[86:89]
	v_mfma_f32_16x16x32_bf16 v[78:81], v[164:167], v[212:215], v[78:81]
	v_mfma_f32_16x16x32_bf16 v[126:129], v[160:163], v[192:195], v[126:129]
	v_mfma_f32_16x16x32_bf16 v[122:125], v[168:171], v[192:195], v[122:125]
	v_mfma_f32_16x16x32_bf16 v[118:121], v[160:163], v[200:203], v[118:121]
	v_mfma_f32_16x16x32_bf16 v[110:113], v[168:171], v[200:203], v[110:113]
	v_mfma_f32_16x16x32_bf16 v[102:105], v[160:163], v[208:211], v[102:105]
	v_mfma_f32_16x16x32_bf16 v[94:97], v[168:171], v[208:211], v[94:97]
	v_mfma_f32_16x16x32_bf16 v[86:89], v[160:163], v[216:219], v[86:89]
	v_mfma_f32_16x16x32_bf16 v[78:81], v[168:171], v[216:219], v[78:81]
	s_setprio 0
	s_setprio 1
	.p2align 3
	v_mfma_f32_16x16x32_bf16 v[114:117], v[172:175], v[188:191], v[114:117]
	v_mfma_f32_16x16x32_bf16 v[106:109], v[180:183], v[188:191], v[106:109]
	v_mfma_f32_16x16x32_bf16 v[98:101], v[172:175], v[196:199], v[98:101]
	v_mfma_f32_16x16x32_bf16 v[90:93], v[180:183], v[196:199], v[90:93]
	v_mfma_f32_16x16x32_bf16 v[82:85], v[172:175], v[204:207], v[82:85]
	v_mfma_f32_16x16x32_bf16 v[74:77], v[180:183], v[204:207], v[74:77]
	v_mfma_f32_16x16x32_bf16 v[70:73], v[172:175], v[212:215], v[70:73]
	v_mfma_f32_16x16x32_bf16 v[66:69], v[180:183], v[212:215], v[66:69]
	v_mfma_f32_16x16x32_bf16 v[114:117], v[176:179], v[192:195], v[114:117]
	v_mfma_f32_16x16x32_bf16 v[106:109], v[184:187], v[192:195], v[106:109]
	v_mfma_f32_16x16x32_bf16 v[98:101], v[176:179], v[200:203], v[98:101]
	v_mfma_f32_16x16x32_bf16 v[90:93], v[184:187], v[200:203], v[90:93]
	v_mfma_f32_16x16x32_bf16 v[82:85], v[176:179], v[208:211], v[82:85]
	v_mfma_f32_16x16x32_bf16 v[74:77], v[184:187], v[208:211], v[74:77]
	v_mfma_f32_16x16x32_bf16 v[70:73], v[176:179], v[216:219], v[70:73]
	v_mfma_f32_16x16x32_bf16 v[66:69], v[184:187], v[216:219], v[66:69]
	s_setprio 0
	s_barrier
; #define PG8_STAGEA(bufoff, gbase, voff) PG8_STAGE_X(bufoff, gbase, voff, PG8_AUX_A)
; #define PG8_STAGEB(bufoff, gbase, voff) PG8_STAGE_X(bufoff, gbase, voff, PG8_AUX_B)
; #define PG8_LDA(dst, b, h) do { _Pragma("unroll") for (int m = 0; m < 4; ++m) _Pragma("unroll") for (int k = 0; k < 2; ++k) dst[m][k] = *(const PG8_LAS bf16x8*)(lds + PG8_SA(b, h) + aoff + m * 2048 + k * 1024); } while (0)
; #define PG8_MMA(ai, bj, At, Bt) do { __builtin_amdgcn_s_setprio(1); _Pragma("unroll") for (int m = 0; m < 4; ++m) _Pragma("unroll") for (int n = 0; n < 2; ++n) _Pragma("unroll") for (int k = 0; k < 2; ++k) \
;         acc[ai][bj][m][n] = __builtin_amdgcn_mfma_f32_16x16x32_bf16(Bt[n][k], At[m][k], acc[ai][bj][m][n], 0, 0, 0); __builtin_amdgcn_s_setprio(0); } while (0)
; #define PG8_WAIT_V(n) asm volatile("s_waitcnt vmcnt(" #n ")" ::: "memory")
; #define PG8_WAIT_L(n) asm volatile("s_waitcnt lgkmcnt(" #n ")" ::: "memory")
; #define PG8_BAR __builtin_amdgcn_s_barrier()
; #define PG8_SCHED __builtin_amdgcn_sched_barrier(0)
; template <class Epi, class Sched, bool ALIGN_EPI = false, bool SP2 = false>
; __device__ __forceinline__ void gemm_phase(PG8_LAS unsigned char* lds, const Gemm g, const Sched& S, const Epi& E) {
;     ...
;             PG8_LDA(At, 1, 1); PG8_STAGEB(PG8_SB(1, 0), b3, voffB); PG8_STAGEB(PG8_SB(1, 1), b3 + hstep, voffB); PG8_STAGEA(PG8_SA(1, 0), a3, voffA);
;             PG8_WAIT_V(8); PG8_WAIT_L(0); PG8_BAR; PG8_MMA(1, 0, At, B0); PG8_MMA(1, 1, At, B1); PG8_BAR; PG8_SCHED;
;     ...
;         if constexpr (ALIGN_EPI) { if (wr == 0) PG8_BAR; }
	s_add_i32 s34, s93, s11
	v_lshl_add_u64 v[220:221], v[220:221], 0, s[54:55]
	s_mov_b32 m0, s34
	ds_read_b128 v[188:191], v154 offset:49152
	ds_read_b128 v[192:195], v154 offset:50176
	ds_read_b128 v[196:199], v154 offset:51200
	ds_read_b128 v[200:203], v154 offset:52224
	ds_read_b128 v[204:207], v154 offset:53248
	ds_read_b128 v[208:211], v154 offset:54272
	ds_read_b128 v[212:215], v154 offset:55296
	ds_read_b128 v[216:219], v154 offset:56320
	global_load_lds_dwordx4 v[220:221], off
	s_add_i32 m0, s34, 0x2000
	s_add_u32 s34, s74, 0x80080
	v_lshl_add_u64 v[220:221], v[222:223], 0, s[54:55]
	s_addc_u32 s35, s75, 0
	s_add_i32 s74, s94, s11
	global_load_lds_dwordx4 v[220:221], off
	v_lshl_add_u64 v[220:221], s[34:35], 0, v[134:135]
	s_mov_b32 m0, s74
	s_nop 0
	global_load_lds_dwordx4 v[220:221], off
	v_lshl_add_u64 v[220:221], s[34:35], 0, v[130:131]
	s_add_i32 m0, s74, 0x2000
	s_nop 0
	global_load_lds_dwordx4 v[220:221], off
	v_lshl_add_u64 v[220:221], v[224:225], 0, s[54:55]
	s_mov_b32 m0, s82
	s_nop 0
	global_load_lds_dwordx4 v[220:221], off
	v_lshl_add_u64 v[220:221], v[226:227], 0, s[54:55]
	s_mov_b32 m0, s83
	s_nop 0
	global_load_lds_dwordx4 v[220:221], off
	s_waitcnt vmcnt(8)
	s_waitcnt lgkmcnt(0)
	s_barrier
	s_setprio 1
	s_waitcnt lgkmcnt(0)
	.p2align 3
	v_mfma_f32_16x16x32_bf16 v[62:65], v[156:159], v[188:191], v[62:65]
	v_mfma_f32_16x16x32_bf16 v[58:61], v[164:167], v[188:191], v[58:61]
	v_mfma_f32_16x16x32_bf16 v[54:57], v[156:159], v[196:199], v[54:57]
	v_mfma_f32_16x16x32_bf16 v[46:49], v[164:167], v[196:199], v[46:49]
	v_mfma_f32_16x16x32_bf16 v[38:41], v[156:159], v[204:207], v[38:41]
	v_mfma_f32_16x16x32_bf16 v[30:33], v[164:167], v[204:207], v[30:33]
	v_mfma_f32_16x16x32_bf16 v[22:25], v[156:159], v[212:215], v[22:25]
	v_mfma_f32_16x16x32_bf16 v[14:17], v[164:167], v[212:215], v[14:17]
	v_mfma_f32_16x16x32_bf16 v[62:65], v[160:163], v[192:195], v[62:65]
	v_mfma_f32_16x16x32_bf16 v[58:61], v[168:171], v[192:195], v[58:61]
	v_mfma_f32_16x16x32_bf16 v[54:57], v[160:163], v[200:203], v[54:57]
	v_mfma_f32_16x16x32_bf16 v[46:49], v[168:171], v[200:203], v[46:49]
	v_mfma_f32_16x16x32_bf16 v[38:41], v[160:163], v[208:211], v[38:41]
	v_mfma_f32_16x16x32_bf16 v[30:33], v[168:171], v[208:211], v[30:33]
	v_mfma_f32_16x16x32_bf16 v[22:25], v[160:163], v[216:219], v[22:25]
	v_mfma_f32_16x16x32_bf16 v[14:17], v[168:171], v[216:219], v[14:17]
	s_setprio 0
	s_setprio 1
	.p2align 3
	v_mfma_f32_16x16x32_bf16 v[50:53], v[172:175], v[188:191], v[50:53]
	v_mfma_f32_16x16x32_bf16 v[42:45], v[180:183], v[188:191], v[42:45]
	v_mfma_f32_16x16x32_bf16 v[34:37], v[172:175], v[196:199], v[34:37]
	v_mfma_f32_16x16x32_bf16 v[26:29], v[180:183], v[196:199], v[26:29]
	v_mfma_f32_16x16x32_bf16 v[18:21], v[172:175], v[204:207], v[18:21]
	v_mfma_f32_16x16x32_bf16 v[10:13], v[180:183], v[204:207], v[10:13]
	v_mfma_f32_16x16x32_bf16 v[6:9], v[172:175], v[212:215], v[6:9]
	v_mfma_f32_16x16x32_bf16 v[2:5], v[180:183], v[212:215], v[2:5]
	v_mfma_f32_16x16x32_bf16 v[50:53], v[176:179], v[192:195], v[50:53]
	v_mfma_f32_16x16x32_bf16 v[42:45], v[184:187], v[192:195], v[42:45]
	v_mfma_f32_16x16x32_bf16 v[34:37], v[176:179], v[200:203], v[34:37]
	v_mfma_f32_16x16x32_bf16 v[26:29], v[184:187], v[200:203], v[26:29]
	v_mfma_f32_16x16x32_bf16 v[18:21], v[176:179], v[208:211], v[18:21]
	v_mfma_f32_16x16x32_bf16 v[10:13], v[184:187], v[208:211], v[10:13]
	v_mfma_f32_16x16x32_bf16 v[6:9], v[176:179], v[216:219], v[6:9]
	v_mfma_f32_16x16x32_bf16 v[2:5], v[184:187], v[216:219], v[2:5]
	s_setprio 0
	s_barrier
	s_add_u32 s72, s72, 0x100
	s_addc_u32 s73, s73, 0
	s_mov_b32 s74, s92
	s_cbranch_vccz .LBB0_295
	s_and_b64 vcc, exec, s[56:57]
	s_cbranch_vccz .LBB0_298
	s_barrier

; #define PG8_STAGEA(bufoff, gbase, voff) PG8_STAGE_X(bufoff, gbase, voff, PG8_AUX_A)
; #define PG8_STAGEB(bufoff, gbase, voff) PG8_STAGE_X(bufoff, gbase, voff, PG8_AUX_B)
; #define PG8_LDA(dst, b, h) do { _Pragma("unroll") for (int m = 0; m < 4; ++m) _Pragma("unroll") for (int k = 0; k < 2; ++k) dst[m][k] = *(const PG8_LAS bf16x8*)(lds + PG8_SA(b, h) + aoff + m * 2048 + k * 1024); } while (0)
; #define PG8_LDB(dst, b, h) do { _Pragma("unroll") for (int n = 0; n < 2; ++n) _Pragma("unroll") for (int k = 0; k < 2; ++k) dst[n][k] = *(const PG8_LAS bf16x8*)(lds + PG8_SB(b, h) + boff + n * 2048 + k * 1024); } while (0)
; #define PG8_MMA(ai, bj, At, Bt) do { __builtin_amdgcn_s_setprio(1); _Pragma("unroll") for (int m = 0; m < 4; ++m) _Pragma("unroll") for (int n = 0; n < 2; ++n) _Pragma("unroll") for (int k = 0; k < 2; ++k) \
;         acc[ai][bj][m][n] = __builtin_amdgcn_mfma_f32_16x16x32_bf16(Bt[n][k], At[m][k], acc[ai][bj][m][n], 0, 0, 0); __builtin_amdgcn_s_setprio(0); } while (0)
; #define PG8_WAIT_V(n) asm volatile("s_waitcnt vmcnt(" #n ")" ::: "memory")
; #define PG8_WAIT_L(n) asm volatile("s_waitcnt lgkmcnt(" #n ")" ::: "memory")
; template <class Epi, class Sched, bool ALIGN_EPI = false, bool SP2 = false>
; __device__ __forceinline__ void gemm_phase(PG8_LAS unsigned char* lds, const Gemm g, const Sched& S, const Epi& E) {
;     ...
;             const char* sA1 = (t + 1 >= ns) ? cA2 : cA; const char* sA2 = (t + 2 >= ns) ? cA2 : cA; const char* sB2 = (t + 2 >= ns) ? cB2 : cB;
;             const char* a1 = sA1 + (size_t)(t + 1) * kstep;
;             const char* a2 = last ? nA : sA2 + (size_t)(t + 2) * kstep; const char* b2 = last ? nB : sB2 + (size_t)(t + 2) * kstep;
;             const char* a3 = a2 + kstep; const char* b3 = b2 + kstep;
;             if (last && has_next) S.a_ready(nxt);
;             if constexpr (SP2) {
;             PG8_LDB(B0, 0, 0); PG8_LDB(B1, 0, 1); PG8_SCHED; PG8_LDA(At, 0, 0); PG8_STAGEA(PG8_SA(1, 1), a1 + hstep, voffA);
;             PG8_WAIT_V(8); PG8_WAIT_L(0); PG8_BAR; PG8_MMA(0, 0, At, B0); PG8_MMA(0, 1, At, B1); PG8_BAR; PG8_SCHED;
;             PG8_LDA(At, 0, 1); PG8_STAGEB(PG8_SB(0, 0), b2, voffB); PG8_STAGEB(PG8_SB(0, 1), b2 + hstep, voffB); PG8_STAGEA(PG8_SA(0, 0), a2, voffA);
;             PG8_WAIT_V(8); PG8_WAIT_L(0); PG8_BAR; PG8_MMA(1, 0, At, B0); PG8_MMA(1, 1, At, B1); PG8_BAR; PG8_SCHED;
.LBB0_643:
	ds_read_b128 v[82:85], v166
	ds_read_b128 v[90:93], v166 offset:1024
	ds_read_b128 v[94:97], v166 offset:2048
	ds_read_b128 v[158:161], v166 offset:3072
	ds_read_b128 v[170:173], v167
	ds_read_b128 v[174:177], v167 offset:1024
	ds_read_b128 v[178:181], v167 offset:2048
	ds_read_b128 v[182:185], v167 offset:3072
	ds_read_b128 v[186:189], v168
	ds_read_b128 v[190:193], v168 offset:1024
	ds_read_b128 v[194:197], v168 offset:2048
	ds_read_b128 v[198:201], v168 offset:3072
	ds_read_b128 v[202:205], v168 offset:4096
	ds_read_b128 v[206:209], v168 offset:5120
	ds_read_b128 v[210:213], v168 offset:6144
	ds_read_b128 v[214:217], v168 offset:7168
	s_add_i32 s97, s96, 2
	s_cmp_lt_u32 s96, 30
	s_cselect_b32 s37, s72, s50
	s_cselect_b32 s34, s71, s47
	s_cselect_b32 s35, s70, s46
	s_cselect_b32 s36, s73, s51
	s_add_u32 s37, s37, s74
	s_addc_u32 s36, s36, s75
	s_add_u32 s37, s37, 0xfff80080
	s_addc_u32 s36, s36, -1
	s_add_u32 s35, s35, s74
	s_addc_u32 s34, s34, s75
	s_add_u32 s35, s35, 0xfff80080
	s_addc_u32 s34, s34, -1
	s_cmp_eq_u32 s96, 30
	s_cselect_b32 s83, s61, s36
	s_cselect_b32 s82, s67, s37
	s_cselect_b32 s85, s59, s34
	s_cselect_b32 s84, s95, s35
	s_add_i32 s37, s93, s8
	s_add_i32 m0, s9, 0xc000
	s_add_i32 s36, s9, 0xe000
	s_add_i32 s38, s37, 0x2000
	s_add_u32 s86, s84, 0x80000
	s_addc_u32 s87, s85, 0
	s_add_i32 s39, s94, s8
	s_add_i32 s24, s39, 0x2000
	s_add_i32 s25, 0, 0x18000
	s_add_i32 vcc_hi, 0, 0x1c000
	s_add_u32 s80, s82, 0x80000
	s_addc_u32 s81, s83, 0
	s_add_i32 vcc_lo, s25, s8
	s_add_i32 s34, vcc_lo, 0x2000
	s_add_u32 s78, s84, 0x80080
	s_addc_u32 s79, s85, 0
	s_add_i32 s35, vcc_hi, s8
	s_add_i32 s28, s35, 0x2000
	s_add_u32 s76, s74, 0x100
	s_addc_u32 s77, s75, 0
	s_cmp_gt_u32 s96, 29
	v_lshl_add_u64 v[162:163], v[74:75], 0, s[74:75]
	global_load_lds_dwordx4 v[162:163], off
	v_lshl_add_u64 v[162:163], v[76:77], 0, s[74:75]
	s_mov_b32 m0, s36
	s_nop 0
	global_load_lds_dwordx4 v[162:163], off
	s_waitcnt vmcnt(8)
	s_waitcnt lgkmcnt(0)
	s_barrier
	s_setprio 1
	s_waitcnt lgkmcnt(0)
	.p2align 3
	v_mfma_f32_16x16x32_bf16 v[142:145], v[82:85], v[186:189], v[142:145]
	v_mfma_f32_16x16x32_bf16 v[138:141], v[94:97], v[186:189], v[138:141]
	v_mfma_f32_16x16x32_bf16 v[126:129], v[82:85], v[194:197], v[126:129]
	v_mfma_f32_16x16x32_bf16 v[122:125], v[94:97], v[194:197], v[122:125]
	v_mfma_f32_16x16x32_bf16 v[110:113], v[82:85], v[202:205], v[110:113]
	v_mfma_f32_16x16x32_bf16 v[106:109], v[94:97], v[202:205], v[106:109]
	v_mfma_f32_16x16x32_bf16 v[86:89], v[82:85], v[210:213], v[86:89]
	v_mfma_f32_16x16x32_bf16 v[78:81], v[94:97], v[210:213], v[78:81]
	v_mfma_f32_16x16x32_bf16 v[142:145], v[90:93], v[190:193], v[142:145]
	v_mfma_f32_16x16x32_bf16 v[138:141], v[158:161], v[190:193], v[138:141]
	v_mfma_f32_16x16x32_bf16 v[126:129], v[90:93], v[198:201], v[126:129]
	v_mfma_f32_16x16x32_bf16 v[122:125], v[158:161], v[198:201], v[122:125]
	v_mfma_f32_16x16x32_bf16 v[110:113], v[90:93], v[206:209], v[110:113]
	v_mfma_f32_16x16x32_bf16 v[106:109], v[158:161], v[206:209], v[106:109]
	v_mfma_f32_16x16x32_bf16 v[86:89], v[90:93], v[214:217], v[86:89]
	v_mfma_f32_16x16x32_bf16 v[78:81], v[158:161], v[214:217], v[78:81]
	s_setprio 0
	s_setprio 1
	.p2align 3
	v_mfma_f32_16x16x32_bf16 v[134:137], v[170:173], v[186:189], v[134:137]
	v_mfma_f32_16x16x32_bf16 v[130:133], v[178:181], v[186:189], v[130:133]
	v_mfma_f32_16x16x32_bf16 v[118:121], v[170:173], v[194:197], v[118:121]
	v_mfma_f32_16x16x32_bf16 v[114:117], v[178:181], v[194:197], v[114:117]
	v_mfma_f32_16x16x32_bf16 v[102:105], v[170:173], v[202:205], v[102:105]
	v_mfma_f32_16x16x32_bf16 v[98:101], v[178:181], v[202:205], v[98:101]
	v_mfma_f32_16x16x32_bf16 v[70:73], v[170:173], v[210:213], v[70:73]
	v_mfma_f32_16x16x32_bf16 v[66:69], v[178:181], v[210:213], v[66:69]
	v_mfma_f32_16x16x32_bf16 v[134:137], v[174:177], v[190:193], v[134:137]
	v_mfma_f32_16x16x32_bf16 v[130:133], v[182:185], v[190:193], v[130:133]
	v_mfma_f32_16x16x32_bf16 v[118:121], v[174:177], v[198:201], v[118:121]
	v_mfma_f32_16x16x32_bf16 v[114:117], v[182:185], v[198:201], v[114:117]
	v_mfma_f32_16x16x32_bf16 v[102:105], v[174:177], v[206:209], v[102:105]
	v_mfma_f32_16x16x32_bf16 v[98:101], v[182:185], v[206:209], v[98:101]
	v_mfma_f32_16x16x32_bf16 v[70:73], v[174:177], v[214:217], v[70:73]
	v_mfma_f32_16x16x32_bf16 v[66:69], v[182:185], v[214:217], v[66:69]
	s_setprio 0
	s_barrier
	s_mov_b32 m0, s37
	v_lshl_add_u64 v[162:163], s[84:85], 0, v[146:147]
	ds_read_b128 v[186:189], v168 offset:16384
	ds_read_b128 v[190:193], v168 offset:17408
	ds_read_b128 v[194:197], v168 offset:18432
	ds_read_b128 v[198:201], v168 offset:19456
	ds_read_b128 v[202:205], v168 offset:20480
	ds_read_b128 v[206:209], v168 offset:21504
	ds_read_b128 v[210:213], v168 offset:22528
	ds_read_b128 v[214:217], v168 offset:23552
	global_load_lds_dwordx4 v[162:163], off
	v_lshl_add_u64 v[218:219], s[84:85], 0, v[148:149]
	s_mov_b32 m0, s38
	v_lshl_add_u64 v[220:221], s[86:87], 0, v[146:147]
	global_load_lds_dwordx4 v[218:219], off
	s_mov_b32 m0, s39
	v_lshl_add_u64 v[222:223], s[82:83], 0, v[148:149]
	global_load_lds_dwordx4 v[220:221], off
	v_lshl_add_u64 v[220:221], s[86:87], 0, v[148:149]
	s_mov_b32 m0, s24
	s_nop 0
	global_load_lds_dwordx4 v[220:221], off
	v_lshl_add_u64 v[220:221], s[82:83], 0, v[146:147]
	s_mov_b32 m0, s9
	s_nop 0
	global_load_lds_dwordx4 v[220:221], off
	s_mov_b32 m0, s11
	s_nop 0
	global_load_lds_dwordx4 v[222:223], off
	s_waitcnt vmcnt(8)
	s_waitcnt lgkmcnt(0)
	s_barrier
; #define PG8_STAGEA(bufoff, gbase, voff) PG8_STAGE_X(bufoff, gbase, voff, PG8_AUX_A)
; #define PG8_LDA(dst, b, h) do { _Pragma("unroll") for (int m = 0; m < 4; ++m) _Pragma("unroll") for (int k = 0; k < 2; ++k) dst[m][k] = *(const PG8_LAS bf16x8*)(lds + PG8_SA(b, h) + aoff + m * 2048 + k * 1024); } while (0)
; #define PG8_LDB(dst, b, h) do { _Pragma("unroll") for (int n = 0; n < 2; ++n) _Pragma("unroll") for (int k = 0; k < 2; ++k) dst[n][k] = *(const PG8_LAS bf16x8*)(lds + PG8_SB(b, h) + boff + n * 2048 + k * 1024); } while (0)
; #define PG8_MMA(ai, bj, At, Bt) do { __builtin_amdgcn_s_setprio(1); _Pragma("unroll") for (int m = 0; m < 4; ++m) _Pragma("unroll") for (int n = 0; n < 2; ++n) _Pragma("unroll") for (int k = 0; k < 2; ++k) \
;         acc[ai][bj][m][n] = __builtin_amdgcn_mfma_f32_16x16x32_bf16(Bt[n][k], At[m][k], acc[ai][bj][m][n], 0, 0, 0); __builtin_amdgcn_s_setprio(0); } while (0)
; #define PG8_WAIT_V(n) asm volatile("s_waitcnt vmcnt(" #n ")" ::: "memory")
; #define PG8_WAIT_L(n) asm volatile("s_waitcnt lgkmcnt(" #n ")" ::: "memory")
; #define PG8_BAR __builtin_amdgcn_s_barrier()
; #define PG8_SCHED __builtin_amdgcn_sched_barrier(0)
; template <class Epi, class Sched, bool ALIGN_EPI = false, bool SP2 = false>
; __device__ __forceinline__ void gemm_phase(PG8_LAS unsigned char* lds, const Gemm g, const Sched& S, const Epi& E) {
;     ...
;             PG8_WAIT_V(8); PG8_WAIT_L(0); PG8_BAR; PG8_MMA(1, 0, At, B0); PG8_MMA(1, 1, At, B1); PG8_BAR; PG8_SCHED;
;             PG8_LDB(B0, 1, 0); PG8_LDB(B1, 1, 1); PG8_SCHED; PG8_LDA(At, 1, 0); PG8_STAGEA(PG8_SA(0, 1), a2 + hstep, voffA);
;             PG8_WAIT_V(8); PG8_WAIT_L(0); PG8_BAR; PG8_MMA(0, 0, At, B0); PG8_MMA(0, 1, At, B1); PG8_BAR; PG8_SCHED;
	s_setprio 1
	s_waitcnt lgkmcnt(0)
	.p2align 3
	v_mfma_f32_16x16x32_bf16 v[62:65], v[82:85], v[186:189], v[62:65]
	v_mfma_f32_16x16x32_bf16 v[58:61], v[94:97], v[186:189], v[58:61]
	v_mfma_f32_16x16x32_bf16 v[46:49], v[82:85], v[194:197], v[46:49]
	v_mfma_f32_16x16x32_bf16 v[42:45], v[94:97], v[194:197], v[42:45]
	v_mfma_f32_16x16x32_bf16 v[30:33], v[82:85], v[202:205], v[30:33]
	v_mfma_f32_16x16x32_bf16 v[26:29], v[94:97], v[202:205], v[26:29]
	v_mfma_f32_16x16x32_bf16 v[14:17], v[82:85], v[210:213], v[14:17]
	v_mfma_f32_16x16x32_bf16 v[10:13], v[94:97], v[210:213], v[10:13]
	v_mfma_f32_16x16x32_bf16 v[62:65], v[90:93], v[190:193], v[62:65]
	v_mfma_f32_16x16x32_bf16 v[58:61], v[158:161], v[190:193], v[58:61]
	v_mfma_f32_16x16x32_bf16 v[46:49], v[90:93], v[198:201], v[46:49]
	v_mfma_f32_16x16x32_bf16 v[42:45], v[158:161], v[198:201], v[42:45]
	v_mfma_f32_16x16x32_bf16 v[30:33], v[90:93], v[206:209], v[30:33]
	v_mfma_f32_16x16x32_bf16 v[26:29], v[158:161], v[206:209], v[26:29]
	v_mfma_f32_16x16x32_bf16 v[14:17], v[90:93], v[214:217], v[14:17]
	v_mfma_f32_16x16x32_bf16 v[10:13], v[158:161], v[214:217], v[10:13]
	s_setprio 0
	s_setprio 1
	.p2align 3
	v_mfma_f32_16x16x32_bf16 v[54:57], v[170:173], v[186:189], v[54:57]
	v_mfma_f32_16x16x32_bf16 v[50:53], v[178:181], v[186:189], v[50:53]
	v_mfma_f32_16x16x32_bf16 v[38:41], v[170:173], v[194:197], v[38:41]
	v_mfma_f32_16x16x32_bf16 v[34:37], v[178:181], v[194:197], v[34:37]
	v_mfma_f32_16x16x32_bf16 v[22:25], v[170:173], v[202:205], v[22:25]
	v_mfma_f32_16x16x32_bf16 v[18:21], v[178:181], v[202:205], v[18:21]
	v_mfma_f32_16x16x32_bf16 v[6:9], v[170:173], v[210:213], v[6:9]
	v_mfma_f32_16x16x32_bf16 v[2:5], v[178:181], v[210:213], v[2:5]
	v_mfma_f32_16x16x32_bf16 v[54:57], v[174:177], v[190:193], v[54:57]
	v_mfma_f32_16x16x32_bf16 v[50:53], v[182:185], v[190:193], v[50:53]
	v_mfma_f32_16x16x32_bf16 v[38:41], v[174:177], v[198:201], v[38:41]
	v_mfma_f32_16x16x32_bf16 v[34:37], v[182:185], v[198:201], v[34:37]
	v_mfma_f32_16x16x32_bf16 v[22:25], v[174:177], v[206:209], v[22:25]
	v_mfma_f32_16x16x32_bf16 v[18:21], v[182:185], v[206:209], v[18:21]
	v_mfma_f32_16x16x32_bf16 v[6:9], v[174:177], v[214:217], v[6:9]
	v_mfma_f32_16x16x32_bf16 v[2:5], v[182:185], v[214:217], v[2:5]
	s_setprio 0
	s_barrier
	v_add_u32_e32 v158, s25, v164
	v_add_u32_e32 v182, vcc_hi, v164
	ds_read_b128 v[82:85], v158
	ds_read_b128 v[90:93], v158 offset:1024
	ds_read_b128 v[94:97], v158 offset:2048
	ds_read_b128 v[158:161], v158 offset:3072
	ds_read_b128 v[170:173], v182
	ds_read_b128 v[174:177], v182 offset:1024
	ds_read_b128 v[178:181], v182 offset:2048
	ds_read_b128 v[182:185], v182 offset:3072
	s_mov_b32 m0, s21
	v_lshl_add_u64 v[224:225], s[80:81], 0, v[146:147]
	ds_read_b128 v[186:189], v168 offset:32768
	ds_read_b128 v[190:193], v168 offset:33792
	ds_read_b128 v[194:197], v168 offset:34816
	ds_read_b128 v[198:201], v168 offset:35840
	ds_read_b128 v[202:205], v168 offset:36864
	ds_read_b128 v[206:209], v168 offset:37888
	ds_read_b128 v[210:213], v168 offset:38912
	ds_read_b128 v[214:217], v168 offset:39936
	global_load_lds_dwordx4 v[224:225], off
	v_lshl_add_u64 v[224:225], s[80:81], 0, v[148:149]
	s_mov_b32 m0, s23
	s_nop 0
	global_load_lds_dwordx4 v[224:225], off
	s_waitcnt vmcnt(8)
	s_waitcnt lgkmcnt(0)
	s_barrier
	s_setprio 1
	s_waitcnt lgkmcnt(0)
	.p2align 3
	v_mfma_f32_16x16x32_bf16 v[142:145], v[82:85], v[186:189], v[142:145]
	v_mfma_f32_16x16x32_bf16 v[138:141], v[94:97], v[186:189], v[138:141]
	v_mfma_f32_16x16x32_bf16 v[126:129], v[82:85], v[194:197], v[126:129]
	v_mfma_f32_16x16x32_bf16 v[122:125], v[94:97], v[194:197], v[122:125]
	v_mfma_f32_16x16x32_bf16 v[110:113], v[82:85], v[202:205], v[110:113]
	v_mfma_f32_16x16x32_bf16 v[106:109], v[94:97], v[202:205], v[106:109]
	v_mfma_f32_16x16x32_bf16 v[86:89], v[82:85], v[210:213], v[86:89]
	v_mfma_f32_16x16x32_bf16 v[78:81], v[94:97], v[210:213], v[78:81]
	v_mfma_f32_16x16x32_bf16 v[142:145], v[90:93], v[190:193], v[142:145]
	v_mfma_f32_16x16x32_bf16 v[138:141], v[158:161], v[190:193], v[138:141]
	v_mfma_f32_16x16x32_bf16 v[126:129], v[90:93], v[198:201], v[126:129]
	v_mfma_f32_16x16x32_bf16 v[122:125], v[158:161], v[198:201], v[122:125]
	v_mfma_f32_16x16x32_bf16 v[110:113], v[90:93], v[206:209], v[110:113]
	v_mfma_f32_16x16x32_bf16 v[106:109], v[158:161], v[206:209], v[106:109]
	v_mfma_f32_16x16x32_bf16 v[86:89], v[90:93], v[214:217], v[86:89]
	v_mfma_f32_16x16x32_bf16 v[78:81], v[158:161], v[214:217], v[78:81]
	s_setprio 0
	s_setprio 1
	.p2align 3
	v_mfma_f32_16x16x32_bf16 v[134:137], v[170:173], v[186:189], v[134:137]
	v_mfma_f32_16x16x32_bf16 v[130:133], v[178:181], v[186:189], v[130:133]
	v_mfma_f32_16x16x32_bf16 v[118:121], v[170:173], v[194:197], v[118:121]
	v_mfma_f32_16x16x32_bf16 v[114:117], v[178:181], v[194:197], v[114:117]
	v_mfma_f32_16x16x32_bf16 v[102:105], v[170:173], v[202:205], v[102:105]
	v_mfma_f32_16x16x32_bf16 v[98:101], v[178:181], v[202:205], v[98:101]
	v_mfma_f32_16x16x32_bf16 v[70:73], v[170:173], v[210:213], v[70:73]
	v_mfma_f32_16x16x32_bf16 v[66:69], v[178:181], v[210:213], v[66:69]
	v_mfma_f32_16x16x32_bf16 v[134:137], v[174:177], v[190:193], v[134:137]
	v_mfma_f32_16x16x32_bf16 v[130:133], v[182:185], v[190:193], v[130:133]
	v_mfma_f32_16x16x32_bf16 v[118:121], v[174:177], v[198:201], v[118:121]
	v_mfma_f32_16x16x32_bf16 v[114:117], v[182:185], v[198:201], v[114:117]
	v_mfma_f32_16x16x32_bf16 v[102:105], v[174:177], v[206:209], v[102:105]
	v_mfma_f32_16x16x32_bf16 v[98:101], v[182:185], v[206:209], v[98:101]
	v_mfma_f32_16x16x32_bf16 v[70:73], v[174:177], v[214:217], v[70:73]
	v_mfma_f32_16x16x32_bf16 v[66:69], v[182:185], v[214:217], v[66:69]
	s_setprio 0
	s_barrier
; #define PG8_STAGEA(bufoff, gbase, voff) PG8_STAGE_X(bufoff, gbase, voff, PG8_AUX_A)
; #define PG8_STAGEB(bufoff, gbase, voff) PG8_STAGE_X(bufoff, gbase, voff, PG8_AUX_B)
; #define PG8_LDA(dst, b, h) do { _Pragma("unroll") for (int m = 0; m < 4; ++m) _Pragma("unroll") for (int k = 0; k < 2; ++k) dst[m][k] = *(const PG8_LAS bf16x8*)(lds + PG8_SA(b, h) + aoff + m * 2048 + k * 1024); } while (0)
; #define PG8_MMA(ai, bj, At, Bt) do { __builtin_amdgcn_s_setprio(1); _Pragma("unroll") for (int m = 0; m < 4; ++m) _Pragma("unroll") for (int n = 0; n < 2; ++n) _Pragma("unroll") for (int k = 0; k < 2; ++k) \
;         acc[ai][bj][m][n] = __builtin_amdgcn_mfma_f32_16x16x32_bf16(Bt[n][k], At[m][k], acc[ai][bj][m][n], 0, 0, 0); __builtin_amdgcn_s_setprio(0); } while (0)
; #define PG8_WAIT_V(n) asm volatile("s_waitcnt vmcnt(" #n ")" ::: "memory")
; #define PG8_WAIT_L(n) asm volatile("s_waitcnt lgkmcnt(" #n ")" ::: "memory")
; #define PG8_BAR __builtin_amdgcn_s_barrier()
; #define PG8_SCHED __builtin_amdgcn_sched_barrier(0)
; template <class Epi, class Sched, bool ALIGN_EPI = false, bool SP2 = false>
; __device__ __forceinline__ void gemm_phase(PG8_LAS unsigned char* lds, const Gemm g, const Sched& S, const Epi& E) {
;     ...
;             PG8_LDA(At, 1, 1); PG8_STAGEB(PG8_SB(1, 0), b3, voffB); PG8_STAGEB(PG8_SB(1, 1), b3 + hstep, voffB); PG8_STAGEA(PG8_SA(1, 0), a3, voffA);
;             PG8_WAIT_V(8); PG8_WAIT_L(0); PG8_BAR; PG8_MMA(1, 0, At, B0); PG8_MMA(1, 1, At, B1); PG8_BAR; PG8_SCHED;
;     ...
;         if constexpr (ALIGN_EPI) { if (wr == 0) PG8_BAR; }
	s_mov_b32 m0, vcc_lo
	v_lshl_add_u64 v[162:163], v[162:163], 0, s[54:55]
	ds_read_b128 v[186:189], v168 offset:49152
	ds_read_b128 v[190:193], v168 offset:50176
	ds_read_b128 v[194:197], v168 offset:51200
	ds_read_b128 v[198:201], v168 offset:52224
	ds_read_b128 v[202:205], v168 offset:53248
	ds_read_b128 v[206:209], v168 offset:54272
	ds_read_b128 v[210:213], v168 offset:55296
	ds_read_b128 v[214:217], v168 offset:56320
	global_load_lds_dwordx4 v[162:163], off
	v_lshl_add_u64 v[162:163], v[218:219], 0, s[54:55]
	s_mov_b32 m0, s34
	s_nop 0
	global_load_lds_dwordx4 v[162:163], off
	v_lshl_add_u64 v[162:163], s[78:79], 0, v[146:147]
	s_mov_b32 m0, s35
	s_nop 0
	global_load_lds_dwordx4 v[162:163], off
	v_lshl_add_u64 v[162:163], s[78:79], 0, v[148:149]
	s_mov_b32 m0, s28
	s_nop 0
	global_load_lds_dwordx4 v[162:163], off
	v_lshl_add_u64 v[162:163], v[220:221], 0, s[54:55]
	s_mov_b32 m0, s90
	s_nop 0
	global_load_lds_dwordx4 v[162:163], off
	v_lshl_add_u64 v[162:163], v[222:223], 0, s[54:55]
	s_mov_b32 m0, s91
	s_nop 0
	global_load_lds_dwordx4 v[162:163], off
	s_waitcnt vmcnt(8)
	s_waitcnt lgkmcnt(0)
	s_barrier
	s_setprio 1
	s_waitcnt lgkmcnt(0)
	.p2align 3
	v_mfma_f32_16x16x32_bf16 v[62:65], v[82:85], v[186:189], v[62:65]
	v_mfma_f32_16x16x32_bf16 v[58:61], v[94:97], v[186:189], v[58:61]
	v_mfma_f32_16x16x32_bf16 v[46:49], v[82:85], v[194:197], v[46:49]
	v_mfma_f32_16x16x32_bf16 v[42:45], v[94:97], v[194:197], v[42:45]
	v_mfma_f32_16x16x32_bf16 v[30:33], v[82:85], v[202:205], v[30:33]
	v_mfma_f32_16x16x32_bf16 v[26:29], v[94:97], v[202:205], v[26:29]
	v_mfma_f32_16x16x32_bf16 v[14:17], v[82:85], v[210:213], v[14:17]
	v_mfma_f32_16x16x32_bf16 v[10:13], v[94:97], v[210:213], v[10:13]
	v_mfma_f32_16x16x32_bf16 v[62:65], v[90:93], v[190:193], v[62:65]
	v_mfma_f32_16x16x32_bf16 v[58:61], v[158:161], v[190:193], v[58:61]
	v_mfma_f32_16x16x32_bf16 v[46:49], v[90:93], v[198:201], v[46:49]
	v_mfma_f32_16x16x32_bf16 v[42:45], v[158:161], v[198:201], v[42:45]
	v_mfma_f32_16x16x32_bf16 v[30:33], v[90:93], v[206:209], v[30:33]
	v_mfma_f32_16x16x32_bf16 v[26:29], v[158:161], v[206:209], v[26:29]
	v_mfma_f32_16x16x32_bf16 v[14:17], v[90:93], v[214:217], v[14:17]
	v_mfma_f32_16x16x32_bf16 v[10:13], v[158:161], v[214:217], v[10:13]
	s_setprio 0
	s_setprio 1
	.p2align 3
	v_mfma_f32_16x16x32_bf16 v[54:57], v[170:173], v[186:189], v[54:57]
	v_mfma_f32_16x16x32_bf16 v[50:53], v[178:181], v[186:189], v[50:53]
	v_mfma_f32_16x16x32_bf16 v[38:41], v[170:173], v[194:197], v[38:41]
	v_mfma_f32_16x16x32_bf16 v[34:37], v[178:181], v[194:197], v[34:37]
	v_mfma_f32_16x16x32_bf16 v[22:25], v[170:173], v[202:205], v[22:25]
	v_mfma_f32_16x16x32_bf16 v[18:21], v[178:181], v[202:205], v[18:21]
	v_mfma_f32_16x16x32_bf16 v[6:9], v[170:173], v[210:213], v[6:9]
	v_mfma_f32_16x16x32_bf16 v[2:5], v[178:181], v[210:213], v[2:5]
	v_mfma_f32_16x16x32_bf16 v[54:57], v[174:177], v[190:193], v[54:57]
	v_mfma_f32_16x16x32_bf16 v[50:53], v[182:185], v[190:193], v[50:53]
	v_mfma_f32_16x16x32_bf16 v[38:41], v[174:177], v[198:201], v[38:41]
	v_mfma_f32_16x16x32_bf16 v[34:37], v[182:185], v[198:201], v[34:37]
	v_mfma_f32_16x16x32_bf16 v[22:25], v[174:177], v[206:209], v[22:25]
	v_mfma_f32_16x16x32_bf16 v[18:21], v[182:185], v[206:209], v[18:21]
	v_mfma_f32_16x16x32_bf16 v[6:9], v[174:177], v[214:217], v[6:9]
	v_mfma_f32_16x16x32_bf16 v[2:5], v[182:185], v[214:217], v[2:5]
	s_setprio 0
	s_barrier
	s_mov_b64 s[74:75], s[76:77]
	s_mov_b32 s96, s97
	s_cbranch_scc0 .LBB0_643
	s_and_b64 vcc, exec, s[56:57]
	s_cbranch_vccz .LBB0_646
	s_barrier

; #define PG8_STAGEA(bufoff, gbase, voff) PG8_STAGE_X(bufoff, gbase, voff, PG8_AUX_A)
; #define PG8_STAGEB(bufoff, gbase, voff) PG8_STAGE_X(bufoff, gbase, voff, PG8_AUX_B)
; #define PG8_LDA(dst, b, h) do { _Pragma("unroll") for (int m = 0; m < 4; ++m) _Pragma("unroll") for (int k = 0; k < 2; ++k) dst[m][k] = *(const PG8_LAS bf16x8*)(lds + PG8_SA(b, h) + aoff + m * 2048 + k * 1024); } while (0)
; #define PG8_LDB(dst, b, h) do { _Pragma("unroll") for (int n = 0; n < 2; ++n) _Pragma("unroll") for (int k = 0; k < 2; ++k) dst[n][k] = *(const PG8_LAS bf16x8*)(lds + PG8_SB(b, h) + boff + n * 2048 + k * 1024); } while (0)
; #define PG8_MMA(ai, bj, At, Bt) do { __builtin_amdgcn_s_setprio(1); _Pragma("unroll") for (int m = 0; m < 4; ++m) _Pragma("unroll") for (int n = 0; n < 2; ++n) _Pragma("unroll") for (int k = 0; k < 2; ++k) \
;         acc[ai][bj][m][n] = __builtin_amdgcn_mfma_f32_16x16x32_bf16(Bt[n][k], At[m][k], acc[ai][bj][m][n], 0, 0, 0); __builtin_amdgcn_s_setprio(0); } while (0)
; #define PG8_WAIT_V(n) asm volatile("s_waitcnt vmcnt(" #n ")" ::: "memory")
; #define PG8_WAIT_L(n) asm volatile("s_waitcnt lgkmcnt(" #n ")" ::: "memory")
; template <class Epi, class Sched, bool ALIGN_EPI = false, bool SP2 = false>
; __device__ __forceinline__ void gemm_phase(PG8_LAS unsigned char* lds, const Gemm g, const Sched& S, const Epi& E) {
;     ...
;             const char* sA1 = (t + 1 >= ns) ? cA2 : cA; const char* sA2 = (t + 2 >= ns) ? cA2 : cA; const char* sB2 = (t + 2 >= ns) ? cB2 : cB;
;             const char* a1 = sA1 + (size_t)(t + 1) * kstep;
;             const char* a2 = last ? nA : sA2 + (size_t)(t + 2) * kstep; const char* b2 = last ? nB : sB2 + (size_t)(t + 2) * kstep;
;             const char* a3 = a2 + kstep; const char* b3 = b2 + kstep;
;             if (last && has_next) S.a_ready(nxt);
;             if constexpr (SP2) {
;             PG8_LDB(B0, 0, 0); PG8_LDB(B1, 0, 1); PG8_SCHED; PG8_LDA(At, 0, 0); PG8_STAGEA(PG8_SA(1, 1), a1 + hstep, voffA);
;             PG8_WAIT_V(8); PG8_WAIT_L(0); PG8_BAR; PG8_MMA(0, 0, At, B0); PG8_MMA(0, 1, At, B1); PG8_BAR; PG8_SCHED;
;             PG8_LDA(At, 0, 1); PG8_STAGEB(PG8_SB(0, 0), b2, voffB); PG8_STAGEB(PG8_SB(0, 1), b2 + hstep, voffB); PG8_STAGEA(PG8_SA(0, 0), a2, voffA);
;             PG8_WAIT_V(8); PG8_WAIT_L(0); PG8_BAR; PG8_MMA(1, 0, At, B0); PG8_MMA(1, 1, At, B1); PG8_BAR; PG8_SCHED;
.LBB0_734:
	ds_read_b128 v[150:153], v156
	ds_read_b128 v[162:165], v156 offset:1024
	ds_read_b128 v[166:169], v156 offset:2048
	ds_read_b128 v[170:173], v156 offset:3072
	ds_read_b128 v[174:177], v157
	ds_read_b128 v[178:181], v157 offset:1024
	ds_read_b128 v[182:185], v157 offset:2048
	ds_read_b128 v[186:189], v157 offset:3072
	ds_read_b128 v[190:193], v158
	ds_read_b128 v[194:197], v158 offset:1024
	ds_read_b128 v[198:201], v158 offset:2048
	ds_read_b128 v[202:205], v158 offset:3072
	ds_read_b128 v[206:209], v158 offset:4096
	ds_read_b128 v[210:213], v158 offset:5120
	ds_read_b128 v[214:217], v158 offset:6144
	ds_read_b128 v[218:221], v158 offset:7168
	s_add_i32 s90, s74, 2
	s_cmp_gt_u32 s90, 29
	s_cselect_b64 s[34:35], -1, 0
	s_and_b64 vcc, s[34:35], exec
	s_cselect_b32 s29, s50, s70
	s_cselect_b32 s24, s47, s69
	s_cselect_b32 s25, s46, s68
	s_cselect_b32 s28, s51, s71
	s_add_u32 s29, s29, s72
	s_addc_u32 s28, s28, s73
	s_add_u32 s29, s29, 0xfff80080
	s_addc_u32 s28, s28, -1
	s_add_u32 s25, s25, s72
	s_addc_u32 s24, s24, s73
	s_add_u32 s25, s25, 0xfff80080
	s_addc_u32 s24, s24, -1
	s_cmp_eq_u32 s74, 28
	s_cselect_b32 s74, s87, s25
	s_cselect_b32 s77, s63, s28
	s_cselect_b32 s76, s86, s29
	s_cselect_b32 s75, s61, s24
	v_lshl_add_u64 v[222:223], v[146:147], 0, s[72:73]
	s_add_i32 m0, s21, 0xc000
	global_load_lds_dwordx4 v[222:223], off
	v_lshl_add_u64 v[222:223], v[148:149], 0, s[72:73]
	s_add_i32 m0, s21, 0xe000
	s_nop 0
	global_load_lds_dwordx4 v[222:223], off
	s_waitcnt vmcnt(8)
	s_waitcnt lgkmcnt(0)
	s_barrier
	s_setprio 1
	s_waitcnt lgkmcnt(0)
	.p2align 3
	v_mfma_f32_16x16x32_bf16 v[126:129], v[150:153], v[190:193], v[126:129]
	v_mfma_f32_16x16x32_bf16 v[122:125], v[166:169], v[190:193], v[122:125]
	v_mfma_f32_16x16x32_bf16 v[110:113], v[150:153], v[198:201], v[110:113]
	v_mfma_f32_16x16x32_bf16 v[106:109], v[166:169], v[198:201], v[106:109]
	v_mfma_f32_16x16x32_bf16 v[94:97], v[150:153], v[206:209], v[94:97]
	v_mfma_f32_16x16x32_bf16 v[90:93], v[166:169], v[206:209], v[90:93]
	v_mfma_f32_16x16x32_bf16 v[78:81], v[150:153], v[214:217], v[78:81]
	v_mfma_f32_16x16x32_bf16 v[74:77], v[166:169], v[214:217], v[74:77]
	v_mfma_f32_16x16x32_bf16 v[126:129], v[162:165], v[194:197], v[126:129]
	v_mfma_f32_16x16x32_bf16 v[122:125], v[170:173], v[194:197], v[122:125]
	v_mfma_f32_16x16x32_bf16 v[110:113], v[162:165], v[202:205], v[110:113]
	v_mfma_f32_16x16x32_bf16 v[106:109], v[170:173], v[202:205], v[106:109]
	v_mfma_f32_16x16x32_bf16 v[94:97], v[162:165], v[210:213], v[94:97]
	v_mfma_f32_16x16x32_bf16 v[90:93], v[170:173], v[210:213], v[90:93]
	v_mfma_f32_16x16x32_bf16 v[78:81], v[162:165], v[218:221], v[78:81]
	v_mfma_f32_16x16x32_bf16 v[74:77], v[170:173], v[218:221], v[74:77]
	s_setprio 0
	s_setprio 1
	.p2align 3
	v_mfma_f32_16x16x32_bf16 v[118:121], v[174:177], v[190:193], v[118:121]
	v_mfma_f32_16x16x32_bf16 v[114:117], v[182:185], v[190:193], v[114:117]
	v_mfma_f32_16x16x32_bf16 v[102:105], v[174:177], v[198:201], v[102:105]
	v_mfma_f32_16x16x32_bf16 v[98:101], v[182:185], v[198:201], v[98:101]
	v_mfma_f32_16x16x32_bf16 v[86:89], v[174:177], v[206:209], v[86:89]
	v_mfma_f32_16x16x32_bf16 v[82:85], v[182:185], v[206:209], v[82:85]
	v_mfma_f32_16x16x32_bf16 v[70:73], v[174:177], v[214:217], v[70:73]
	v_mfma_f32_16x16x32_bf16 v[66:69], v[182:185], v[214:217], v[66:69]
	v_mfma_f32_16x16x32_bf16 v[118:121], v[178:181], v[194:197], v[118:121]
	v_mfma_f32_16x16x32_bf16 v[114:117], v[186:189], v[194:197], v[114:117]
	v_mfma_f32_16x16x32_bf16 v[102:105], v[178:181], v[202:205], v[102:105]
	v_mfma_f32_16x16x32_bf16 v[98:101], v[186:189], v[202:205], v[98:101]
	v_mfma_f32_16x16x32_bf16 v[86:89], v[178:181], v[210:213], v[86:89]
	v_mfma_f32_16x16x32_bf16 v[82:85], v[186:189], v[210:213], v[82:85]
	v_mfma_f32_16x16x32_bf16 v[70:73], v[178:181], v[218:221], v[70:73]
	v_mfma_f32_16x16x32_bf16 v[66:69], v[186:189], v[218:221], v[66:69]
	s_setprio 0
	s_barrier
	s_add_i32 s24, s81, s9
	v_lshl_add_u64 v[222:223], s[74:75], 0, v[134:135]
	s_mov_b32 m0, s24
	ds_read_b128 v[190:193], v158 offset:16384
	ds_read_b128 v[194:197], v158 offset:17408
	ds_read_b128 v[198:201], v158 offset:18432
	ds_read_b128 v[202:205], v158 offset:19456
	ds_read_b128 v[206:209], v158 offset:20480
	ds_read_b128 v[210:213], v158 offset:21504
	ds_read_b128 v[214:217], v158 offset:22528
	ds_read_b128 v[218:221], v158 offset:23552
	global_load_lds_dwordx4 v[222:223], off
	s_add_i32 m0, s24, 0x2000
	s_add_u32 s34, s74, 0x80000
	v_lshl_add_u64 v[224:225], s[74:75], 0, v[130:131]
	s_addc_u32 s35, s75, 0
	s_add_i32 s24, s82, s9
	global_load_lds_dwordx4 v[224:225], off
	v_lshl_add_u64 v[226:227], s[34:35], 0, v[134:135]
	s_mov_b32 m0, s24
	v_lshl_add_u64 v[228:229], s[76:77], 0, v[132:133]
	global_load_lds_dwordx4 v[226:227], off
	v_lshl_add_u64 v[226:227], s[34:35], 0, v[130:131]
	s_add_i32 m0, s24, 0x2000
	s_nop 0
	global_load_lds_dwordx4 v[226:227], off
	v_lshl_add_u64 v[226:227], s[76:77], 0, v[136:137]
	s_mov_b32 m0, s21
	s_nop 0
	global_load_lds_dwordx4 v[226:227], off
	s_mov_b32 m0, s23
	s_nop 0
	global_load_lds_dwordx4 v[228:229], off
	s_waitcnt vmcnt(8)
	s_waitcnt lgkmcnt(0)
	s_barrier
; #define PG8_STAGEA(bufoff, gbase, voff) PG8_STAGE_X(bufoff, gbase, voff, PG8_AUX_A)
; #define PG8_LDA(dst, b, h) do { _Pragma("unroll") for (int m = 0; m < 4; ++m) _Pragma("unroll") for (int k = 0; k < 2; ++k) dst[m][k] = *(const PG8_LAS bf16x8*)(lds + PG8_SA(b, h) + aoff + m * 2048 + k * 1024); } while (0)
; #define PG8_LDB(dst, b, h) do { _Pragma("unroll") for (int n = 0; n < 2; ++n) _Pragma("unroll") for (int k = 0; k < 2; ++k) dst[n][k] = *(const PG8_LAS bf16x8*)(lds + PG8_SB(b, h) + boff + n * 2048 + k * 1024); } while (0)
; #define PG8_MMA(ai, bj, At, Bt) do { __builtin_amdgcn_s_setprio(1); _Pragma("unroll") for (int m = 0; m < 4; ++m) _Pragma("unroll") for (int n = 0; n < 2; ++n) _Pragma("unroll") for (int k = 0; k < 2; ++k) \
;         acc[ai][bj][m][n] = __builtin_amdgcn_mfma_f32_16x16x32_bf16(Bt[n][k], At[m][k], acc[ai][bj][m][n], 0, 0, 0); __builtin_amdgcn_s_setprio(0); } while (0)
; #define PG8_WAIT_V(n) asm volatile("s_waitcnt vmcnt(" #n ")" ::: "memory")
; #define PG8_WAIT_L(n) asm volatile("s_waitcnt lgkmcnt(" #n ")" ::: "memory")
; #define PG8_BAR __builtin_amdgcn_s_barrier()
; #define PG8_SCHED __builtin_amdgcn_sched_barrier(0)
; template <class Epi, class Sched, bool ALIGN_EPI = false, bool SP2 = false>
; __device__ __forceinline__ void gemm_phase(PG8_LAS unsigned char* lds, const Gemm g, const Sched& S, const Epi& E) {
;     ...
;             PG8_WAIT_V(8); PG8_WAIT_L(0); PG8_BAR; PG8_MMA(1, 0, At, B0); PG8_MMA(1, 1, At, B1); PG8_BAR; PG8_SCHED;
;             PG8_LDB(B0, 1, 0); PG8_LDB(B1, 1, 1); PG8_SCHED; PG8_LDA(At, 1, 0); PG8_STAGEA(PG8_SA(0, 1), a2 + hstep, voffA);
;             PG8_WAIT_V(8); PG8_WAIT_L(0); PG8_BAR; PG8_MMA(0, 0, At, B0); PG8_MMA(0, 1, At, B1); PG8_BAR; PG8_SCHED;
	s_setprio 1
	s_waitcnt lgkmcnt(0)
	.p2align 3
	v_mfma_f32_16x16x32_bf16 v[62:65], v[150:153], v[190:193], v[62:65]
	v_mfma_f32_16x16x32_bf16 v[58:61], v[166:169], v[190:193], v[58:61]
	v_mfma_f32_16x16x32_bf16 v[46:49], v[150:153], v[198:201], v[46:49]
	v_mfma_f32_16x16x32_bf16 v[42:45], v[166:169], v[198:201], v[42:45]
	v_mfma_f32_16x16x32_bf16 v[30:33], v[150:153], v[206:209], v[30:33]
	v_mfma_f32_16x16x32_bf16 v[26:29], v[166:169], v[206:209], v[26:29]
	v_mfma_f32_16x16x32_bf16 v[14:17], v[150:153], v[214:217], v[14:17]
	v_mfma_f32_16x16x32_bf16 v[10:13], v[166:169], v[214:217], v[10:13]
	v_mfma_f32_16x16x32_bf16 v[62:65], v[162:165], v[194:197], v[62:65]
	v_mfma_f32_16x16x32_bf16 v[58:61], v[170:173], v[194:197], v[58:61]
	v_mfma_f32_16x16x32_bf16 v[46:49], v[162:165], v[202:205], v[46:49]
	v_mfma_f32_16x16x32_bf16 v[42:45], v[170:173], v[202:205], v[42:45]
	v_mfma_f32_16x16x32_bf16 v[30:33], v[162:165], v[210:213], v[30:33]
	v_mfma_f32_16x16x32_bf16 v[26:29], v[170:173], v[210:213], v[26:29]
	v_mfma_f32_16x16x32_bf16 v[14:17], v[162:165], v[218:221], v[14:17]
	v_mfma_f32_16x16x32_bf16 v[10:13], v[170:173], v[218:221], v[10:13]
	s_setprio 0
	s_setprio 1
	.p2align 3
	v_mfma_f32_16x16x32_bf16 v[54:57], v[174:177], v[190:193], v[54:57]
	v_mfma_f32_16x16x32_bf16 v[50:53], v[182:185], v[190:193], v[50:53]
	v_mfma_f32_16x16x32_bf16 v[38:41], v[174:177], v[198:201], v[38:41]
	v_mfma_f32_16x16x32_bf16 v[34:37], v[182:185], v[198:201], v[34:37]
	v_mfma_f32_16x16x32_bf16 v[22:25], v[174:177], v[206:209], v[22:25]
	v_mfma_f32_16x16x32_bf16 v[18:21], v[182:185], v[206:209], v[18:21]
	v_mfma_f32_16x16x32_bf16 v[6:9], v[174:177], v[214:217], v[6:9]
	v_mfma_f32_16x16x32_bf16 v[2:5], v[182:185], v[214:217], v[2:5]
	v_mfma_f32_16x16x32_bf16 v[54:57], v[178:181], v[194:197], v[54:57]
	v_mfma_f32_16x16x32_bf16 v[50:53], v[186:189], v[194:197], v[50:53]
	v_mfma_f32_16x16x32_bf16 v[38:41], v[178:181], v[202:205], v[38:41]
	v_mfma_f32_16x16x32_bf16 v[34:37], v[186:189], v[202:205], v[34:37]
	v_mfma_f32_16x16x32_bf16 v[22:25], v[178:181], v[210:213], v[22:25]
	v_mfma_f32_16x16x32_bf16 v[18:21], v[186:189], v[210:213], v[18:21]
	v_mfma_f32_16x16x32_bf16 v[6:9], v[178:181], v[218:221], v[6:9]
	v_mfma_f32_16x16x32_bf16 v[2:5], v[186:189], v[218:221], v[2:5]
	s_setprio 0
	s_barrier
	s_add_i32 s24, 0, 0x18000
	v_add_u32_e32 v161, s24, v154
	s_add_i32 s25, 0, 0x1c000
	ds_read_b128 v[150:153], v161
	ds_read_b128 v[162:165], v161 offset:1024
	ds_read_b128 v[166:169], v161 offset:2048
	ds_read_b128 v[170:173], v161 offset:3072
	v_add_u32_e32 v161, s25, v154
	ds_read_b128 v[174:177], v161
	ds_read_b128 v[178:181], v161 offset:1024
	ds_read_b128 v[182:185], v161 offset:2048
	ds_read_b128 v[186:189], v161 offset:3072
	s_add_u32 s34, s76, 0x80000
	s_addc_u32 s35, s77, 0
	s_mov_b32 m0, s26
	v_lshl_add_u64 v[230:231], s[34:35], 0, v[136:137]
	ds_read_b128 v[190:193], v158 offset:32768
	ds_read_b128 v[194:197], v158 offset:33792
	ds_read_b128 v[198:201], v158 offset:34816
	ds_read_b128 v[202:205], v158 offset:35840
	ds_read_b128 v[206:209], v158 offset:36864
	ds_read_b128 v[210:213], v158 offset:37888
	ds_read_b128 v[214:217], v158 offset:38912
	ds_read_b128 v[218:221], v158 offset:39936
	global_load_lds_dwordx4 v[230:231], off
	v_lshl_add_u64 v[230:231], s[34:35], 0, v[132:133]
	s_mov_b32 m0, s27
	s_nop 0
	global_load_lds_dwordx4 v[230:231], off
	s_waitcnt vmcnt(8)
	s_waitcnt lgkmcnt(0)
	s_barrier
	s_setprio 1
	s_waitcnt lgkmcnt(0)
	.p2align 3
	v_mfma_f32_16x16x32_bf16 v[126:129], v[150:153], v[190:193], v[126:129]
	v_mfma_f32_16x16x32_bf16 v[122:125], v[166:169], v[190:193], v[122:125]
	v_mfma_f32_16x16x32_bf16 v[110:113], v[150:153], v[198:201], v[110:113]
	v_mfma_f32_16x16x32_bf16 v[106:109], v[166:169], v[198:201], v[106:109]
	v_mfma_f32_16x16x32_bf16 v[94:97], v[150:153], v[206:209], v[94:97]
	v_mfma_f32_16x16x32_bf16 v[90:93], v[166:169], v[206:209], v[90:93]
	v_mfma_f32_16x16x32_bf16 v[78:81], v[150:153], v[214:217], v[78:81]
	v_mfma_f32_16x16x32_bf16 v[74:77], v[166:169], v[214:217], v[74:77]
	v_mfma_f32_16x16x32_bf16 v[126:129], v[162:165], v[194:197], v[126:129]
	v_mfma_f32_16x16x32_bf16 v[122:125], v[170:173], v[194:197], v[122:125]
	v_mfma_f32_16x16x32_bf16 v[110:113], v[162:165], v[202:205], v[110:113]
	v_mfma_f32_16x16x32_bf16 v[106:109], v[170:173], v[202:205], v[106:109]
	v_mfma_f32_16x16x32_bf16 v[94:97], v[162:165], v[210:213], v[94:97]
	v_mfma_f32_16x16x32_bf16 v[90:93], v[170:173], v[210:213], v[90:93]
	v_mfma_f32_16x16x32_bf16 v[78:81], v[162:165], v[218:221], v[78:81]
	v_mfma_f32_16x16x32_bf16 v[74:77], v[170:173], v[218:221], v[74:77]
	s_setprio 0
	s_setprio 1
	.p2align 3
	v_mfma_f32_16x16x32_bf16 v[118:121], v[174:177], v[190:193], v[118:121]
	v_mfma_f32_16x16x32_bf16 v[114:117], v[182:185], v[190:193], v[114:117]
	v_mfma_f32_16x16x32_bf16 v[102:105], v[174:177], v[198:201], v[102:105]
	v_mfma_f32_16x16x32_bf16 v[98:101], v[182:185], v[198:201], v[98:101]
	v_mfma_f32_16x16x32_bf16 v[86:89], v[174:177], v[206:209], v[86:89]
	v_mfma_f32_16x16x32_bf16 v[82:85], v[182:185], v[206:209], v[82:85]
	v_mfma_f32_16x16x32_bf16 v[70:73], v[174:177], v[214:217], v[70:73]
	v_mfma_f32_16x16x32_bf16 v[66:69], v[182:185], v[214:217], v[66:69]
	v_mfma_f32_16x16x32_bf16 v[118:121], v[178:181], v[194:197], v[118:121]
	v_mfma_f32_16x16x32_bf16 v[114:117], v[186:189], v[194:197], v[114:117]
	v_mfma_f32_16x16x32_bf16 v[102:105], v[178:181], v[202:205], v[102:105]
	v_mfma_f32_16x16x32_bf16 v[98:101], v[186:189], v[202:205], v[98:101]
	v_mfma_f32_16x16x32_bf16 v[86:89], v[178:181], v[210:213], v[86:89]
	v_mfma_f32_16x16x32_bf16 v[82:85], v[186:189], v[210:213], v[82:85]
	v_mfma_f32_16x16x32_bf16 v[70:73], v[178:181], v[218:221], v[70:73]
	v_mfma_f32_16x16x32_bf16 v[66:69], v[186:189], v[218:221], v[66:69]
	s_setprio 0
	s_barrier
; #define PG8_STAGEA(bufoff, gbase, voff) PG8_STAGE_X(bufoff, gbase, voff, PG8_AUX_A)
; #define PG8_STAGEB(bufoff, gbase, voff) PG8_STAGE_X(bufoff, gbase, voff, PG8_AUX_B)
; #define PG8_LDA(dst, b, h) do { _Pragma("unroll") for (int m = 0; m < 4; ++m) _Pragma("unroll") for (int k = 0; k < 2; ++k) dst[m][k] = *(const PG8_LAS bf16x8*)(lds + PG8_SA(b, h) + aoff + m * 2048 + k * 1024); } while (0)
; #define PG8_MMA(ai, bj, At, Bt) do { __builtin_amdgcn_s_setprio(1); _Pragma("unroll") for (int m = 0; m < 4; ++m) _Pragma("unroll") for (int n = 0; n < 2; ++n) _Pragma("unroll") for (int k = 0; k < 2; ++k) \
;         acc[ai][bj][m][n] = __builtin_amdgcn_mfma_f32_16x16x32_bf16(Bt[n][k], At[m][k], acc[ai][bj][m][n], 0, 0, 0); __builtin_amdgcn_s_setprio(0); } while (0)
; #define PG8_WAIT_V(n) asm volatile("s_waitcnt vmcnt(" #n ")" ::: "memory")
; #define PG8_WAIT_L(n) asm volatile("s_waitcnt lgkmcnt(" #n ")" ::: "memory")
; #define PG8_BAR __builtin_amdgcn_s_barrier()
; #define PG8_SCHED __builtin_amdgcn_sched_barrier(0)
; template <class Epi, class Sched, bool ALIGN_EPI = false, bool SP2 = false>
; __device__ __forceinline__ void gemm_phase(PG8_LAS unsigned char* lds, const Gemm g, const Sched& S, const Epi& E) {
;     ...
;             PG8_LDA(At, 1, 1); PG8_STAGEB(PG8_SB(1, 0), b3, voffB); PG8_STAGEB(PG8_SB(1, 1), b3 + hstep, voffB); PG8_STAGEA(PG8_SA(1, 0), a3, voffA);
;             PG8_WAIT_V(8); PG8_WAIT_L(0); PG8_BAR; PG8_MMA(1, 0, At, B0); PG8_MMA(1, 1, At, B1); PG8_BAR; PG8_SCHED;
;     ...
;         if constexpr (ALIGN_EPI) { if (wr == 0) PG8_BAR; }
	s_add_i32 s24, s24, s9
	v_lshl_add_u64 v[222:223], v[222:223], 0, s[54:55]
	s_mov_b32 m0, s24
	ds_read_b128 v[190:193], v158 offset:49152
	ds_read_b128 v[194:197], v158 offset:50176
	ds_read_b128 v[198:201], v158 offset:51200
	ds_read_b128 v[202:205], v158 offset:52224
	ds_read_b128 v[206:209], v158 offset:53248
	ds_read_b128 v[210:213], v158 offset:54272
	ds_read_b128 v[214:217], v158 offset:55296
	ds_read_b128 v[218:221], v158 offset:56320
	global_load_lds_dwordx4 v[222:223], off
	s_add_i32 m0, s24, 0x2000
	s_add_u32 s34, s74, 0x80080
	v_lshl_add_u64 v[222:223], v[224:225], 0, s[54:55]
	s_addc_u32 s35, s75, 0
	s_add_i32 s24, s25, s9
	global_load_lds_dwordx4 v[222:223], off
	v_lshl_add_u64 v[222:223], s[34:35], 0, v[134:135]
	s_mov_b32 m0, s24
	s_nop 0
	global_load_lds_dwordx4 v[222:223], off
	v_lshl_add_u64 v[222:223], s[34:35], 0, v[130:131]
	s_add_i32 m0, s24, 0x2000
	s_nop 0
	global_load_lds_dwordx4 v[222:223], off
	v_lshl_add_u64 v[222:223], v[226:227], 0, s[54:55]
	s_mov_b32 m0, s79
	s_nop 0
	global_load_lds_dwordx4 v[222:223], off
	v_lshl_add_u64 v[222:223], v[228:229], 0, s[54:55]
	s_mov_b32 m0, s80
	s_nop 0
	global_load_lds_dwordx4 v[222:223], off
	s_waitcnt vmcnt(8)
	s_waitcnt lgkmcnt(0)
	s_barrier
	s_setprio 1
	s_waitcnt lgkmcnt(0)
	.p2align 3
	v_mfma_f32_16x16x32_bf16 v[62:65], v[150:153], v[190:193], v[62:65]
	v_mfma_f32_16x16x32_bf16 v[58:61], v[166:169], v[190:193], v[58:61]
	v_mfma_f32_16x16x32_bf16 v[46:49], v[150:153], v[198:201], v[46:49]
	v_mfma_f32_16x16x32_bf16 v[42:45], v[166:169], v[198:201], v[42:45]
	v_mfma_f32_16x16x32_bf16 v[30:33], v[150:153], v[206:209], v[30:33]
	v_mfma_f32_16x16x32_bf16 v[26:29], v[166:169], v[206:209], v[26:29]
	v_mfma_f32_16x16x32_bf16 v[14:17], v[150:153], v[214:217], v[14:17]
	v_mfma_f32_16x16x32_bf16 v[10:13], v[166:169], v[214:217], v[10:13]
	v_mfma_f32_16x16x32_bf16 v[62:65], v[162:165], v[194:197], v[62:65]
	v_mfma_f32_16x16x32_bf16 v[58:61], v[170:173], v[194:197], v[58:61]
	v_mfma_f32_16x16x32_bf16 v[46:49], v[162:165], v[202:205], v[46:49]
	v_mfma_f32_16x16x32_bf16 v[42:45], v[170:173], v[202:205], v[42:45]
	v_mfma_f32_16x16x32_bf16 v[30:33], v[162:165], v[210:213], v[30:33]
	v_mfma_f32_16x16x32_bf16 v[26:29], v[170:173], v[210:213], v[26:29]
	v_mfma_f32_16x16x32_bf16 v[14:17], v[162:165], v[218:221], v[14:17]
	v_mfma_f32_16x16x32_bf16 v[10:13], v[170:173], v[218:221], v[10:13]
	s_setprio 0
	s_setprio 1
	.p2align 3
	v_mfma_f32_16x16x32_bf16 v[54:57], v[174:177], v[190:193], v[54:57]
	v_mfma_f32_16x16x32_bf16 v[50:53], v[182:185], v[190:193], v[50:53]
	v_mfma_f32_16x16x32_bf16 v[38:41], v[174:177], v[198:201], v[38:41]
	v_mfma_f32_16x16x32_bf16 v[34:37], v[182:185], v[198:201], v[34:37]
	v_mfma_f32_16x16x32_bf16 v[22:25], v[174:177], v[206:209], v[22:25]
	v_mfma_f32_16x16x32_bf16 v[18:21], v[182:185], v[206:209], v[18:21]
	v_mfma_f32_16x16x32_bf16 v[6:9], v[174:177], v[214:217], v[6:9]
	v_mfma_f32_16x16x32_bf16 v[2:5], v[182:185], v[214:217], v[2:5]
	v_mfma_f32_16x16x32_bf16 v[54:57], v[178:181], v[194:197], v[54:57]
	v_mfma_f32_16x16x32_bf16 v[50:53], v[186:189], v[194:197], v[50:53]
	v_mfma_f32_16x16x32_bf16 v[38:41], v[178:181], v[202:205], v[38:41]
	v_mfma_f32_16x16x32_bf16 v[34:37], v[186:189], v[202:205], v[34:37]
	v_mfma_f32_16x16x32_bf16 v[22:25], v[178:181], v[210:213], v[22:25]
	v_mfma_f32_16x16x32_bf16 v[18:21], v[186:189], v[210:213], v[18:21]
	v_mfma_f32_16x16x32_bf16 v[6:9], v[178:181], v[218:221], v[6:9]
	v_mfma_f32_16x16x32_bf16 v[2:5], v[186:189], v[218:221], v[2:5]
	s_setprio 0
	s_barrier
	s_add_u32 s72, s72, 0x100
	s_addc_u32 s73, s73, 0
	s_mov_b32 s74, s90
	s_cbranch_vccz .LBB0_734
	s_and_b64 vcc, exec, s[56:57]
	s_cbranch_vccz .LBB0_737
	s_barrier

; #define PG8_STAGEA(bufoff, gbase, voff) PG8_STAGE_X(bufoff, gbase, voff, PG8_AUX_A)
; #define PG8_STAGEB(bufoff, gbase, voff) PG8_STAGE_X(bufoff, gbase, voff, PG8_AUX_B)
; #define PG8_LDA(dst, b, h) do { _Pragma("unroll") for (int m = 0; m < 4; ++m) _Pragma("unroll") for (int k = 0; k < 2; ++k) dst[m][k] = *(const PG8_LAS bf16x8*)(lds + PG8_SA(b, h) + aoff + m * 2048 + k * 1024); } while (0)
; #define PG8_LDB(dst, b, h) do { _Pragma("unroll") for (int n = 0; n < 2; ++n) _Pragma("unroll") for (int k = 0; k < 2; ++k) dst[n][k] = *(const PG8_LAS bf16x8*)(lds + PG8_SB(b, h) + boff + n * 2048 + k * 1024); } while (0)
; #define PG8_MMA(ai, bj, At, Bt) do { __builtin_amdgcn_s_setprio(1); _Pragma("unroll") for (int m = 0; m < 4; ++m) _Pragma("unroll") for (int n = 0; n < 2; ++n) _Pragma("unroll") for (int k = 0; k < 2; ++k) \
;         acc[ai][bj][m][n] = __builtin_amdgcn_mfma_f32_16x16x32_bf16(Bt[n][k], At[m][k], acc[ai][bj][m][n], 0, 0, 0); __builtin_amdgcn_s_setprio(0); } while (0)
; #define PG8_WAIT_V(n) asm volatile("s_waitcnt vmcnt(" #n ")" ::: "memory")
; #define PG8_WAIT_L(n) asm volatile("s_waitcnt lgkmcnt(" #n ")" ::: "memory")
; template <class Epi, class Sched, bool ALIGN_EPI = false, bool SP2 = false>
; __device__ __forceinline__ void gemm_phase(PG8_LAS unsigned char* lds, const Gemm g, const Sched& S, const Epi& E) {
;     ...
;             const char* sA1 = (t + 1 >= ns) ? cA2 : cA; const char* sA2 = (t + 2 >= ns) ? cA2 : cA; const char* sB2 = (t + 2 >= ns) ? cB2 : cB;
;             const char* a1 = sA1 + (size_t)(t + 1) * kstep;
;             const char* a2 = last ? nA : sA2 + (size_t)(t + 2) * kstep; const char* b2 = last ? nB : sB2 + (size_t)(t + 2) * kstep;
;             const char* a3 = a2 + kstep; const char* b3 = b2 + kstep;
;             if (last && has_next) S.a_ready(nxt);
;             if constexpr (SP2) {
;             PG8_LDB(B0, 0, 0); PG8_LDB(B1, 0, 1); PG8_SCHED; PG8_LDA(At, 0, 0); PG8_STAGEA(PG8_SA(1, 1), a1 + hstep, voffA);
;             PG8_WAIT_V(8); PG8_WAIT_L(0); PG8_BAR; PG8_MMA(0, 0, At, B0); PG8_MMA(0, 1, At, B1); PG8_BAR; PG8_SCHED;
;             PG8_LDA(At, 0, 1); PG8_STAGEB(PG8_SB(0, 0), b2, voffB); PG8_STAGEB(PG8_SB(0, 1), b2 + hstep, voffB); PG8_STAGEA(PG8_SA(0, 0), a2, voffA);
;             PG8_WAIT_V(8); PG8_WAIT_L(0); PG8_BAR; PG8_MMA(1, 0, At, B0); PG8_MMA(1, 1, At, B1); PG8_BAR; PG8_SCHED;
.LBB0_750:
	ds_read_b128 v[152:155], v148
	ds_read_b128 v[156:159], v148 offset:1024
	ds_read_b128 v[160:163], v148 offset:2048
	ds_read_b128 v[164:167], v148 offset:3072
	ds_read_b128 v[168:171], v149
	ds_read_b128 v[172:175], v149 offset:1024
	ds_read_b128 v[176:179], v149 offset:2048
	ds_read_b128 v[180:183], v149 offset:3072
	ds_read_b128 v[184:187], v150
	ds_read_b128 v[188:191], v150 offset:1024
	ds_read_b128 v[192:195], v150 offset:2048
	ds_read_b128 v[196:199], v150 offset:3072
	ds_read_b128 v[200:203], v150 offset:4096
	ds_read_b128 v[204:207], v150 offset:5120
	ds_read_b128 v[208:211], v150 offset:6144
	ds_read_b128 v[212:215], v150 offset:7168
	s_add_i32 s91, s70, 2
	s_cmp_gt_u32 s91, 29
	s_cselect_b64 s[34:35], -1, 0
	s_and_b64 vcc, s[34:35], exec
	s_cselect_b32 s29, s4, s66
	s_cselect_b32 s24, s3, s65
	s_cselect_b32 s25, s2, s64
	s_cselect_b32 s28, s5, s67
	s_add_u32 s29, s29, s68
	s_addc_u32 s28, s28, s69
	s_add_u32 s29, s29, 0xfff80080
	s_addc_u32 s28, s28, -1
	s_add_u32 s25, s25, s68
	s_addc_u32 s24, s24, s69
	s_add_u32 s25, s25, 0xfff80080
	s_addc_u32 s24, s24, -1
	s_cmp_eq_u32 s70, 28
	s_cselect_b32 s70, s90, s25
	s_cselect_b32 s73, s55, s28
	s_cselect_b32 s72, s87, s29
	s_cselect_b32 s71, s53, s24
	v_lshl_add_u64 v[216:217], v[142:143], 0, s[68:69]
	s_add_i32 m0, s63, 0xc000
	global_load_lds_dwordx4 v[216:217], off
	v_lshl_add_u64 v[216:217], v[144:145], 0, s[68:69]
	s_add_i32 m0, s63, 0xe000
	s_nop 0
	global_load_lds_dwordx4 v[216:217], off
	s_waitcnt vmcnt(8)
	s_waitcnt lgkmcnt(0)
	s_barrier
	s_setprio 1
	s_waitcnt lgkmcnt(0)
	.p2align 3
	v_mfma_f32_16x16x32_bf16 v[126:129], v[152:155], v[184:187], v[126:129]
	v_mfma_f32_16x16x32_bf16 v[122:125], v[160:163], v[184:187], v[122:125]
	v_mfma_f32_16x16x32_bf16 v[118:121], v[152:155], v[192:195], v[118:121]
	v_mfma_f32_16x16x32_bf16 v[110:113], v[160:163], v[192:195], v[110:113]
	v_mfma_f32_16x16x32_bf16 v[102:105], v[152:155], v[200:203], v[102:105]
	v_mfma_f32_16x16x32_bf16 v[94:97], v[160:163], v[200:203], v[94:97]
	v_mfma_f32_16x16x32_bf16 v[86:89], v[152:155], v[208:211], v[86:89]
	v_mfma_f32_16x16x32_bf16 v[78:81], v[160:163], v[208:211], v[78:81]
	v_mfma_f32_16x16x32_bf16 v[126:129], v[156:159], v[188:191], v[126:129]
	v_mfma_f32_16x16x32_bf16 v[122:125], v[164:167], v[188:191], v[122:125]
	v_mfma_f32_16x16x32_bf16 v[118:121], v[156:159], v[196:199], v[118:121]
	v_mfma_f32_16x16x32_bf16 v[110:113], v[164:167], v[196:199], v[110:113]
	v_mfma_f32_16x16x32_bf16 v[102:105], v[156:159], v[204:207], v[102:105]
	v_mfma_f32_16x16x32_bf16 v[94:97], v[164:167], v[204:207], v[94:97]
	v_mfma_f32_16x16x32_bf16 v[86:89], v[156:159], v[212:215], v[86:89]
	v_mfma_f32_16x16x32_bf16 v[78:81], v[164:167], v[212:215], v[78:81]
	s_setprio 0
	s_setprio 1
	.p2align 3
	v_mfma_f32_16x16x32_bf16 v[114:117], v[168:171], v[184:187], v[114:117]
	v_mfma_f32_16x16x32_bf16 v[106:109], v[176:179], v[184:187], v[106:109]
	v_mfma_f32_16x16x32_bf16 v[98:101], v[168:171], v[192:195], v[98:101]
	v_mfma_f32_16x16x32_bf16 v[90:93], v[176:179], v[192:195], v[90:93]
	v_mfma_f32_16x16x32_bf16 v[82:85], v[168:171], v[200:203], v[82:85]
	v_mfma_f32_16x16x32_bf16 v[74:77], v[176:179], v[200:203], v[74:77]
	v_mfma_f32_16x16x32_bf16 v[70:73], v[168:171], v[208:211], v[70:73]
	v_mfma_f32_16x16x32_bf16 v[66:69], v[176:179], v[208:211], v[66:69]
	v_mfma_f32_16x16x32_bf16 v[114:117], v[172:175], v[188:191], v[114:117]
	v_mfma_f32_16x16x32_bf16 v[106:109], v[180:183], v[188:191], v[106:109]
	v_mfma_f32_16x16x32_bf16 v[98:101], v[172:175], v[196:199], v[98:101]
	v_mfma_f32_16x16x32_bf16 v[90:93], v[180:183], v[196:199], v[90:93]
	v_mfma_f32_16x16x32_bf16 v[82:85], v[172:175], v[204:207], v[82:85]
	v_mfma_f32_16x16x32_bf16 v[74:77], v[180:183], v[204:207], v[74:77]
	v_mfma_f32_16x16x32_bf16 v[70:73], v[172:175], v[212:215], v[70:73]
	v_mfma_f32_16x16x32_bf16 v[66:69], v[180:183], v[212:215], v[66:69]
	s_setprio 0
	s_barrier
	s_add_i32 s24, s82, s74
	v_lshl_add_u64 v[216:217], s[70:71], 0, v[134:135]
	s_mov_b32 m0, s24
	ds_read_b128 v[184:187], v150 offset:16384
	ds_read_b128 v[188:191], v150 offset:17408
	ds_read_b128 v[192:195], v150 offset:18432
	ds_read_b128 v[196:199], v150 offset:19456
	ds_read_b128 v[200:203], v150 offset:20480
	ds_read_b128 v[204:207], v150 offset:21504
	ds_read_b128 v[208:211], v150 offset:22528
	ds_read_b128 v[212:215], v150 offset:23552
	global_load_lds_dwordx4 v[216:217], off
	s_add_i32 m0, s24, 0x2000
	s_add_u32 s34, s70, 0x80000
	v_lshl_add_u64 v[218:219], s[70:71], 0, v[130:131]
	s_addc_u32 s35, s71, 0
	s_add_i32 s24, s83, s74
	global_load_lds_dwordx4 v[218:219], off
	v_lshl_add_u64 v[220:221], s[34:35], 0, v[134:135]
	s_mov_b32 m0, s24
	v_lshl_add_u64 v[222:223], s[72:73], 0, v[132:133]
	global_load_lds_dwordx4 v[220:221], off
	v_lshl_add_u64 v[220:221], s[34:35], 0, v[130:131]
	s_add_i32 m0, s24, 0x2000
	s_nop 0
	global_load_lds_dwordx4 v[220:221], off
	v_lshl_add_u64 v[220:221], s[72:73], 0, v[136:137]
	s_mov_b32 m0, s63
	s_nop 0
	global_load_lds_dwordx4 v[220:221], off
	s_mov_b32 m0, s76
	s_nop 0
	global_load_lds_dwordx4 v[222:223], off
	s_waitcnt vmcnt(8)
	s_waitcnt lgkmcnt(0)
	s_barrier
; #define PG8_STAGEA(bufoff, gbase, voff) PG8_STAGE_X(bufoff, gbase, voff, PG8_AUX_A)
; #define PG8_LDA(dst, b, h) do { _Pragma("unroll") for (int m = 0; m < 4; ++m) _Pragma("unroll") for (int k = 0; k < 2; ++k) dst[m][k] = *(const PG8_LAS bf16x8*)(lds + PG8_SA(b, h) + aoff + m * 2048 + k * 1024); } while (0)
; #define PG8_LDB(dst, b, h) do { _Pragma("unroll") for (int n = 0; n < 2; ++n) _Pragma("unroll") for (int k = 0; k < 2; ++k) dst[n][k] = *(const PG8_LAS bf16x8*)(lds + PG8_SB(b, h) + boff + n * 2048 + k * 1024); } while (0)
; #define PG8_MMA(ai, bj, At, Bt) do { __builtin_amdgcn_s_setprio(1); _Pragma("unroll") for (int m = 0; m < 4; ++m) _Pragma("unroll") for (int n = 0; n < 2; ++n) _Pragma("unroll") for (int k = 0; k < 2; ++k) \
;         acc[ai][bj][m][n] = __builtin_amdgcn_mfma_f32_16x16x32_bf16(Bt[n][k], At[m][k], acc[ai][bj][m][n], 0, 0, 0); __builtin_amdgcn_s_setprio(0); } while (0)
; #define PG8_WAIT_V(n) asm volatile("s_waitcnt vmcnt(" #n ")" ::: "memory")
; #define PG8_WAIT_L(n) asm volatile("s_waitcnt lgkmcnt(" #n ")" ::: "memory")
; #define PG8_BAR __builtin_amdgcn_s_barrier()
; #define PG8_SCHED __builtin_amdgcn_sched_barrier(0)
; template <class Epi, class Sched, bool ALIGN_EPI = false, bool SP2 = false>
; __device__ __forceinline__ void gemm_phase(PG8_LAS unsigned char* lds, const Gemm g, const Sched& S, const Epi& E) {
;     ...
;             PG8_WAIT_V(8); PG8_WAIT_L(0); PG8_BAR; PG8_MMA(1, 0, At, B0); PG8_MMA(1, 1, At, B1); PG8_BAR; PG8_SCHED;
;             PG8_LDB(B0, 1, 0); PG8_LDB(B1, 1, 1); PG8_SCHED; PG8_LDA(At, 1, 0); PG8_STAGEA(PG8_SA(0, 1), a2 + hstep, voffA);
;             PG8_WAIT_V(8); PG8_WAIT_L(0); PG8_BAR; PG8_MMA(0, 0, At, B0); PG8_MMA(0, 1, At, B1); PG8_BAR; PG8_SCHED;
	s_setprio 1
	s_waitcnt lgkmcnt(0)
	.p2align 3
	v_mfma_f32_16x16x32_bf16 v[62:65], v[152:155], v[184:187], v[62:65]
	v_mfma_f32_16x16x32_bf16 v[58:61], v[160:163], v[184:187], v[58:61]
	v_mfma_f32_16x16x32_bf16 v[54:57], v[152:155], v[192:195], v[54:57]
	v_mfma_f32_16x16x32_bf16 v[46:49], v[160:163], v[192:195], v[46:49]
	v_mfma_f32_16x16x32_bf16 v[38:41], v[152:155], v[200:203], v[38:41]
	v_mfma_f32_16x16x32_bf16 v[30:33], v[160:163], v[200:203], v[30:33]
	v_mfma_f32_16x16x32_bf16 v[22:25], v[152:155], v[208:211], v[22:25]
	v_mfma_f32_16x16x32_bf16 v[14:17], v[160:163], v[208:211], v[14:17]
	v_mfma_f32_16x16x32_bf16 v[62:65], v[156:159], v[188:191], v[62:65]
	v_mfma_f32_16x16x32_bf16 v[58:61], v[164:167], v[188:191], v[58:61]
	v_mfma_f32_16x16x32_bf16 v[54:57], v[156:159], v[196:199], v[54:57]
	v_mfma_f32_16x16x32_bf16 v[46:49], v[164:167], v[196:199], v[46:49]
	v_mfma_f32_16x16x32_bf16 v[38:41], v[156:159], v[204:207], v[38:41]
	v_mfma_f32_16x16x32_bf16 v[30:33], v[164:167], v[204:207], v[30:33]
	v_mfma_f32_16x16x32_bf16 v[22:25], v[156:159], v[212:215], v[22:25]
	v_mfma_f32_16x16x32_bf16 v[14:17], v[164:167], v[212:215], v[14:17]
	s_setprio 0
	s_setprio 1
	.p2align 3
	v_mfma_f32_16x16x32_bf16 v[50:53], v[168:171], v[184:187], v[50:53]
	v_mfma_f32_16x16x32_bf16 v[42:45], v[176:179], v[184:187], v[42:45]
	v_mfma_f32_16x16x32_bf16 v[34:37], v[168:171], v[192:195], v[34:37]
	v_mfma_f32_16x16x32_bf16 v[26:29], v[176:179], v[192:195], v[26:29]
	v_mfma_f32_16x16x32_bf16 v[18:21], v[168:171], v[200:203], v[18:21]
	v_mfma_f32_16x16x32_bf16 v[10:13], v[176:179], v[200:203], v[10:13]
	v_mfma_f32_16x16x32_bf16 v[6:9], v[168:171], v[208:211], v[6:9]
	v_mfma_f32_16x16x32_bf16 v[2:5], v[176:179], v[208:211], v[2:5]
	v_mfma_f32_16x16x32_bf16 v[50:53], v[172:175], v[188:191], v[50:53]
	v_mfma_f32_16x16x32_bf16 v[42:45], v[180:183], v[188:191], v[42:45]
	v_mfma_f32_16x16x32_bf16 v[34:37], v[172:175], v[196:199], v[34:37]
	v_mfma_f32_16x16x32_bf16 v[26:29], v[180:183], v[196:199], v[26:29]
	v_mfma_f32_16x16x32_bf16 v[18:21], v[172:175], v[204:207], v[18:21]
	v_mfma_f32_16x16x32_bf16 v[10:13], v[180:183], v[204:207], v[10:13]
	v_mfma_f32_16x16x32_bf16 v[6:9], v[172:175], v[212:215], v[6:9]
	v_mfma_f32_16x16x32_bf16 v[2:5], v[180:183], v[212:215], v[2:5]
	s_setprio 0
	s_barrier
	s_add_i32 s24, 0, 0x18000
	v_add_u32_e32 v151, s24, v146
	s_add_i32 s25, 0, 0x1c000
	ds_read_b128 v[152:155], v151
	ds_read_b128 v[156:159], v151 offset:1024
	ds_read_b128 v[160:163], v151 offset:2048
	ds_read_b128 v[164:167], v151 offset:3072
	v_add_u32_e32 v151, s25, v146
	ds_read_b128 v[168:171], v151
	ds_read_b128 v[172:175], v151 offset:1024
	ds_read_b128 v[176:179], v151 offset:2048
	ds_read_b128 v[180:183], v151 offset:3072
	s_add_u32 s34, s72, 0x80000
	s_addc_u32 s35, s73, 0
	s_mov_b32 m0, s77
	v_lshl_add_u64 v[224:225], s[34:35], 0, v[136:137]
	ds_read_b128 v[184:187], v150 offset:32768
	ds_read_b128 v[188:191], v150 offset:33792
	ds_read_b128 v[192:195], v150 offset:34816
	ds_read_b128 v[196:199], v150 offset:35840
	ds_read_b128 v[200:203], v150 offset:36864
	ds_read_b128 v[204:207], v150 offset:37888
	ds_read_b128 v[208:211], v150 offset:38912
	ds_read_b128 v[212:215], v150 offset:39936
	global_load_lds_dwordx4 v[224:225], off
	v_lshl_add_u64 v[224:225], s[34:35], 0, v[132:133]
	s_mov_b32 m0, s78
	s_nop 0
	global_load_lds_dwordx4 v[224:225], off
	s_waitcnt vmcnt(8)
	s_waitcnt lgkmcnt(0)
	s_barrier
	s_setprio 1
	s_waitcnt lgkmcnt(0)
	.p2align 3
	v_mfma_f32_16x16x32_bf16 v[126:129], v[152:155], v[184:187], v[126:129]
	v_mfma_f32_16x16x32_bf16 v[122:125], v[160:163], v[184:187], v[122:125]
	v_mfma_f32_16x16x32_bf16 v[118:121], v[152:155], v[192:195], v[118:121]
	v_mfma_f32_16x16x32_bf16 v[110:113], v[160:163], v[192:195], v[110:113]
	v_mfma_f32_16x16x32_bf16 v[102:105], v[152:155], v[200:203], v[102:105]
	v_mfma_f32_16x16x32_bf16 v[94:97], v[160:163], v[200:203], v[94:97]
	v_mfma_f32_16x16x32_bf16 v[86:89], v[152:155], v[208:211], v[86:89]
	v_mfma_f32_16x16x32_bf16 v[78:81], v[160:163], v[208:211], v[78:81]
	v_mfma_f32_16x16x32_bf16 v[126:129], v[156:159], v[188:191], v[126:129]
	v_mfma_f32_16x16x32_bf16 v[122:125], v[164:167], v[188:191], v[122:125]
	v_mfma_f32_16x16x32_bf16 v[118:121], v[156:159], v[196:199], v[118:121]
	v_mfma_f32_16x16x32_bf16 v[110:113], v[164:167], v[196:199], v[110:113]
	v_mfma_f32_16x16x32_bf16 v[102:105], v[156:159], v[204:207], v[102:105]
	v_mfma_f32_16x16x32_bf16 v[94:97], v[164:167], v[204:207], v[94:97]
	v_mfma_f32_16x16x32_bf16 v[86:89], v[156:159], v[212:215], v[86:89]
	v_mfma_f32_16x16x32_bf16 v[78:81], v[164:167], v[212:215], v[78:81]
	s_setprio 0
	s_setprio 1
	.p2align 3
	v_mfma_f32_16x16x32_bf16 v[114:117], v[168:171], v[184:187], v[114:117]
	v_mfma_f32_16x16x32_bf16 v[106:109], v[176:179], v[184:187], v[106:109]
	v_mfma_f32_16x16x32_bf16 v[98:101], v[168:171], v[192:195], v[98:101]
	v_mfma_f32_16x16x32_bf16 v[90:93], v[176:179], v[192:195], v[90:93]
	v_mfma_f32_16x16x32_bf16 v[82:85], v[168:171], v[200:203], v[82:85]
	v_mfma_f32_16x16x32_bf16 v[74:77], v[176:179], v[200:203], v[74:77]
	v_mfma_f32_16x16x32_bf16 v[70:73], v[168:171], v[208:211], v[70:73]
	v_mfma_f32_16x16x32_bf16 v[66:69], v[176:179], v[208:211], v[66:69]
	v_mfma_f32_16x16x32_bf16 v[114:117], v[172:175], v[188:191], v[114:117]
	v_mfma_f32_16x16x32_bf16 v[106:109], v[180:183], v[188:191], v[106:109]
	v_mfma_f32_16x16x32_bf16 v[98:101], v[172:175], v[196:199], v[98:101]
	v_mfma_f32_16x16x32_bf16 v[90:93], v[180:183], v[196:199], v[90:93]
	v_mfma_f32_16x16x32_bf16 v[82:85], v[172:175], v[204:207], v[82:85]
	v_mfma_f32_16x16x32_bf16 v[74:77], v[180:183], v[204:207], v[74:77]
	v_mfma_f32_16x16x32_bf16 v[70:73], v[172:175], v[212:215], v[70:73]
	v_mfma_f32_16x16x32_bf16 v[66:69], v[180:183], v[212:215], v[66:69]
	s_setprio 0
	s_barrier
; #define PG8_STAGEA(bufoff, gbase, voff) PG8_STAGE_X(bufoff, gbase, voff, PG8_AUX_A)
; #define PG8_STAGEB(bufoff, gbase, voff) PG8_STAGE_X(bufoff, gbase, voff, PG8_AUX_B)
; #define PG8_LDA(dst, b, h) do { _Pragma("unroll") for (int m = 0; m < 4; ++m) _Pragma("unroll") for (int k = 0; k < 2; ++k) dst[m][k] = *(const PG8_LAS bf16x8*)(lds + PG8_SA(b, h) + aoff + m * 2048 + k * 1024); } while (0)
; #define PG8_MMA(ai, bj, At, Bt) do { __builtin_amdgcn_s_setprio(1); _Pragma("unroll") for (int m = 0; m < 4; ++m) _Pragma("unroll") for (int n = 0; n < 2; ++n) _Pragma("unroll") for (int k = 0; k < 2; ++k) \
;         acc[ai][bj][m][n] = __builtin_amdgcn_mfma_f32_16x16x32_bf16(Bt[n][k], At[m][k], acc[ai][bj][m][n], 0, 0, 0); __builtin_amdgcn_s_setprio(0); } while (0)
; #define PG8_WAIT_V(n) asm volatile("s_waitcnt vmcnt(" #n ")" ::: "memory")
; #define PG8_WAIT_L(n) asm volatile("s_waitcnt lgkmcnt(" #n ")" ::: "memory")
; #define PG8_BAR __builtin_amdgcn_s_barrier()
; #define PG8_SCHED __builtin_amdgcn_sched_barrier(0)
; template <class Epi, class Sched, bool ALIGN_EPI = false, bool SP2 = false>
; __device__ __forceinline__ void gemm_phase(PG8_LAS unsigned char* lds, const Gemm g, const Sched& S, const Epi& E) {
;     ...
;             PG8_LDA(At, 1, 1); PG8_STAGEB(PG8_SB(1, 0), b3, voffB); PG8_STAGEB(PG8_SB(1, 1), b3 + hstep, voffB); PG8_STAGEA(PG8_SA(1, 0), a3, voffA);
;             PG8_WAIT_V(8); PG8_WAIT_L(0); PG8_BAR; PG8_MMA(1, 0, At, B0); PG8_MMA(1, 1, At, B1); PG8_BAR; PG8_SCHED;
;     ...
;         if constexpr (ALIGN_EPI) { if (wr == 0) PG8_BAR; }
	s_add_i32 s24, s24, s74
	v_lshl_add_u64 v[216:217], v[216:217], 0, s[46:47]
	s_mov_b32 m0, s24
	ds_read_b128 v[184:187], v150 offset:49152
	ds_read_b128 v[188:191], v150 offset:50176
	ds_read_b128 v[192:195], v150 offset:51200
	ds_read_b128 v[196:199], v150 offset:52224
	ds_read_b128 v[200:203], v150 offset:53248
	ds_read_b128 v[204:207], v150 offset:54272
	ds_read_b128 v[208:211], v150 offset:55296
	ds_read_b128 v[212:215], v150 offset:56320
	global_load_lds_dwordx4 v[216:217], off
	s_add_i32 m0, s24, 0x2000
	s_add_u32 s34, s70, 0x80080
	v_lshl_add_u64 v[216:217], v[218:219], 0, s[46:47]
	s_addc_u32 s35, s71, 0
	s_add_i32 s24, s25, s74
	global_load_lds_dwordx4 v[216:217], off
	v_lshl_add_u64 v[216:217], s[34:35], 0, v[134:135]
	s_mov_b32 m0, s24
	s_nop 0
	global_load_lds_dwordx4 v[216:217], off
	v_lshl_add_u64 v[216:217], s[34:35], 0, v[130:131]
	s_add_i32 m0, s24, 0x2000
	s_nop 0
	global_load_lds_dwordx4 v[216:217], off
	v_lshl_add_u64 v[216:217], v[220:221], 0, s[46:47]
	s_mov_b32 m0, s79
	s_nop 0
	global_load_lds_dwordx4 v[216:217], off
	v_lshl_add_u64 v[216:217], v[222:223], 0, s[46:47]
	s_mov_b32 m0, s80
	s_nop 0
	global_load_lds_dwordx4 v[216:217], off
	s_waitcnt vmcnt(8)
	s_waitcnt lgkmcnt(0)
	s_barrier
	s_setprio 1
	s_waitcnt lgkmcnt(0)
	.p2align 3
	v_mfma_f32_16x16x32_bf16 v[62:65], v[152:155], v[184:187], v[62:65]
	v_mfma_f32_16x16x32_bf16 v[58:61], v[160:163], v[184:187], v[58:61]
	v_mfma_f32_16x16x32_bf16 v[54:57], v[152:155], v[192:195], v[54:57]
	v_mfma_f32_16x16x32_bf16 v[46:49], v[160:163], v[192:195], v[46:49]
	v_mfma_f32_16x16x32_bf16 v[38:41], v[152:155], v[200:203], v[38:41]
	v_mfma_f32_16x16x32_bf16 v[30:33], v[160:163], v[200:203], v[30:33]
	v_mfma_f32_16x16x32_bf16 v[22:25], v[152:155], v[208:211], v[22:25]
	v_mfma_f32_16x16x32_bf16 v[14:17], v[160:163], v[208:211], v[14:17]
	v_mfma_f32_16x16x32_bf16 v[62:65], v[156:159], v[188:191], v[62:65]
	v_mfma_f32_16x16x32_bf16 v[58:61], v[164:167], v[188:191], v[58:61]
	v_mfma_f32_16x16x32_bf16 v[54:57], v[156:159], v[196:199], v[54:57]
	v_mfma_f32_16x16x32_bf16 v[46:49], v[164:167], v[196:199], v[46:49]
	v_mfma_f32_16x16x32_bf16 v[38:41], v[156:159], v[204:207], v[38:41]
	v_mfma_f32_16x16x32_bf16 v[30:33], v[164:167], v[204:207], v[30:33]
	v_mfma_f32_16x16x32_bf16 v[22:25], v[156:159], v[212:215], v[22:25]
	v_mfma_f32_16x16x32_bf16 v[14:17], v[164:167], v[212:215], v[14:17]
	s_setprio 0
	s_setprio 1
	.p2align 3
	v_mfma_f32_16x16x32_bf16 v[50:53], v[168:171], v[184:187], v[50:53]
	v_mfma_f32_16x16x32_bf16 v[42:45], v[176:179], v[184:187], v[42:45]
	v_mfma_f32_16x16x32_bf16 v[34:37], v[168:171], v[192:195], v[34:37]
	v_mfma_f32_16x16x32_bf16 v[26:29], v[176:179], v[192:195], v[26:29]
	v_mfma_f32_16x16x32_bf16 v[18:21], v[168:171], v[200:203], v[18:21]
	v_mfma_f32_16x16x32_bf16 v[10:13], v[176:179], v[200:203], v[10:13]
	v_mfma_f32_16x16x32_bf16 v[6:9], v[168:171], v[208:211], v[6:9]
	v_mfma_f32_16x16x32_bf16 v[2:5], v[176:179], v[208:211], v[2:5]
	v_mfma_f32_16x16x32_bf16 v[50:53], v[172:175], v[188:191], v[50:53]
	v_mfma_f32_16x16x32_bf16 v[42:45], v[180:183], v[188:191], v[42:45]
	v_mfma_f32_16x16x32_bf16 v[34:37], v[172:175], v[196:199], v[34:37]
	v_mfma_f32_16x16x32_bf16 v[26:29], v[180:183], v[196:199], v[26:29]
	v_mfma_f32_16x16x32_bf16 v[18:21], v[172:175], v[204:207], v[18:21]
	v_mfma_f32_16x16x32_bf16 v[10:13], v[180:183], v[204:207], v[10:13]
	v_mfma_f32_16x16x32_bf16 v[6:9], v[172:175], v[212:215], v[6:9]
	v_mfma_f32_16x16x32_bf16 v[2:5], v[180:183], v[212:215], v[2:5]
	s_setprio 0
	s_barrier
	s_add_u32 s68, s68, 0x100
	s_addc_u32 s69, s69, 0
	s_mov_b32 s70, s91
	s_cbranch_vccz .LBB0_750
	s_and_b64 vcc, exec, s[48:49]
	s_cbranch_vccz .LBB0_753
	s_barrier

; #define PG8_STAGEA(bufoff, gbase, voff) PG8_STAGE_X(bufoff, gbase, voff, PG8_AUX_A)
; #define PG8_STAGEB(bufoff, gbase, voff) PG8_STAGE_X(bufoff, gbase, voff, PG8_AUX_B)
; #define PG8_LDA(dst, b, h) do { _Pragma("unroll") for (int m = 0; m < 4; ++m) _Pragma("unroll") for (int k = 0; k < 2; ++k) dst[m][k] = *(const PG8_LAS bf16x8*)(lds + PG8_SA(b, h) + aoff + m * 2048 + k * 1024); } while (0)
; #define PG8_LDB(dst, b, h) do { _Pragma("unroll") for (int n = 0; n < 2; ++n) _Pragma("unroll") for (int k = 0; k < 2; ++k) dst[n][k] = *(const PG8_LAS bf16x8*)(lds + PG8_SB(b, h) + boff + n * 2048 + k * 1024); } while (0)
; #define PG8_MMA(ai, bj, At, Bt) do { __builtin_amdgcn_s_setprio(1); _Pragma("unroll") for (int m = 0; m < 4; ++m) _Pragma("unroll") for (int n = 0; n < 2; ++n) _Pragma("unroll") for (int k = 0; k < 2; ++k) \
;         acc[ai][bj][m][n] = __builtin_amdgcn_mfma_f32_16x16x32_bf16(Bt[n][k], At[m][k], acc[ai][bj][m][n], 0, 0, 0); __builtin_amdgcn_s_setprio(0); } while (0)
; #define PG8_WAIT_V(n) asm volatile("s_waitcnt vmcnt(" #n ")" ::: "memory")
; #define PG8_WAIT_L(n) asm volatile("s_waitcnt lgkmcnt(" #n ")" ::: "memory")
; template <class Epi, class Sched, bool ALIGN_EPI = false, bool SP2 = false>
; __device__ __forceinline__ void gemm_phase(PG8_LAS unsigned char* lds, const Gemm g, const Sched& S, const Epi& E) {
;     ...
;             const char* sA1 = (t + 1 >= ns) ? cA2 : cA; const char* sA2 = (t + 2 >= ns) ? cA2 : cA; const char* sB2 = (t + 2 >= ns) ? cB2 : cB;
;             const char* a1 = sA1 + (size_t)(t + 1) * kstep;
;             const char* a2 = last ? nA : sA2 + (size_t)(t + 2) * kstep; const char* b2 = last ? nB : sB2 + (size_t)(t + 2) * kstep;
;             const char* a3 = a2 + kstep; const char* b3 = b2 + kstep;
;             if (last && has_next) S.a_ready(nxt);
;             if constexpr (SP2) {
;             PG8_LDB(B0, 0, 0); PG8_LDB(B1, 0, 1); PG8_SCHED; PG8_LDA(At, 0, 0); PG8_STAGEA(PG8_SA(1, 1), a1 + hstep, voffA);
;             PG8_WAIT_V(8); PG8_WAIT_L(0); PG8_BAR; PG8_MMA(0, 0, At, B0); PG8_MMA(0, 1, At, B1); PG8_BAR; PG8_SCHED;
;             PG8_LDA(At, 0, 1); PG8_STAGEB(PG8_SB(0, 0), b2, voffB); PG8_STAGEB(PG8_SB(0, 1), b2 + hstep, voffB); PG8_STAGEA(PG8_SA(0, 0), a2, voffA);
;             PG8_WAIT_V(8); PG8_WAIT_L(0); PG8_BAR; PG8_MMA(1, 0, At, B0); PG8_MMA(1, 1, At, B1); PG8_BAR; PG8_SCHED;
.LBB0_766:
	ds_read_b128 v[152:155], v148
	ds_read_b128 v[156:159], v148 offset:1024
	ds_read_b128 v[160:163], v148 offset:2048
	ds_read_b128 v[164:167], v148 offset:3072
	ds_read_b128 v[168:171], v149
	ds_read_b128 v[172:175], v149 offset:1024
	ds_read_b128 v[176:179], v149 offset:2048
	ds_read_b128 v[180:183], v149 offset:3072
	ds_read_b128 v[184:187], v150
	ds_read_b128 v[188:191], v150 offset:1024
	ds_read_b128 v[192:195], v150 offset:2048
	ds_read_b128 v[196:199], v150 offset:3072
	ds_read_b128 v[200:203], v150 offset:4096
	ds_read_b128 v[204:207], v150 offset:5120
	ds_read_b128 v[208:211], v150 offset:6144
	ds_read_b128 v[212:215], v150 offset:7168
	s_add_i32 s91, s70, 2
	s_cmp_gt_u32 s91, 29
	s_cselect_b64 s[72:73], -1, 0
	s_and_b64 vcc, s[72:73], exec
	s_cselect_b32 s29, s4, s66
	s_cselect_b32 s24, s3, s65
	s_cselect_b32 s25, s2, s64
	s_cselect_b32 s28, s5, s67
	s_add_u32 s29, s29, s68
	s_addc_u32 s28, s28, s69
	s_add_u32 s29, s29, 0xfff80080
	s_addc_u32 s28, s28, -1
	s_add_u32 s25, s25, s68
	s_addc_u32 s24, s24, s69
	s_add_u32 s25, s25, 0xfff80080
	s_addc_u32 s24, s24, -1
	s_cmp_eq_u32 s70, 28
	s_cselect_b32 s70, s90, s25
	s_cselect_b32 s73, s55, s28
	s_cselect_b32 s72, s87, s29
	s_cselect_b32 s71, s53, s24
	v_lshl_add_u64 v[216:217], v[142:143], 0, s[68:69]
	s_add_i32 m0, s63, 0xc000
	global_load_lds_dwordx4 v[216:217], off
	v_lshl_add_u64 v[216:217], v[144:145], 0, s[68:69]
	s_add_i32 m0, s63, 0xe000
	s_nop 0
	global_load_lds_dwordx4 v[216:217], off
	s_waitcnt vmcnt(8)
	s_waitcnt lgkmcnt(0)
	s_barrier
	s_setprio 1
	s_waitcnt lgkmcnt(0)
	.p2align 3
	v_mfma_f32_16x16x32_bf16 v[126:129], v[152:155], v[184:187], v[126:129]
	v_mfma_f32_16x16x32_bf16 v[122:125], v[160:163], v[184:187], v[122:125]
	v_mfma_f32_16x16x32_bf16 v[118:121], v[152:155], v[192:195], v[118:121]
	v_mfma_f32_16x16x32_bf16 v[110:113], v[160:163], v[192:195], v[110:113]
	v_mfma_f32_16x16x32_bf16 v[102:105], v[152:155], v[200:203], v[102:105]
	v_mfma_f32_16x16x32_bf16 v[94:97], v[160:163], v[200:203], v[94:97]
	v_mfma_f32_16x16x32_bf16 v[86:89], v[152:155], v[208:211], v[86:89]
	v_mfma_f32_16x16x32_bf16 v[78:81], v[160:163], v[208:211], v[78:81]
	v_mfma_f32_16x16x32_bf16 v[126:129], v[156:159], v[188:191], v[126:129]
	v_mfma_f32_16x16x32_bf16 v[122:125], v[164:167], v[188:191], v[122:125]
	v_mfma_f32_16x16x32_bf16 v[118:121], v[156:159], v[196:199], v[118:121]
	v_mfma_f32_16x16x32_bf16 v[110:113], v[164:167], v[196:199], v[110:113]
	v_mfma_f32_16x16x32_bf16 v[102:105], v[156:159], v[204:207], v[102:105]
	v_mfma_f32_16x16x32_bf16 v[94:97], v[164:167], v[204:207], v[94:97]
	v_mfma_f32_16x16x32_bf16 v[86:89], v[156:159], v[212:215], v[86:89]
	v_mfma_f32_16x16x32_bf16 v[78:81], v[164:167], v[212:215], v[78:81]
	s_setprio 0
	s_setprio 1
	.p2align 3
	v_mfma_f32_16x16x32_bf16 v[114:117], v[168:171], v[184:187], v[114:117]
	v_mfma_f32_16x16x32_bf16 v[106:109], v[176:179], v[184:187], v[106:109]
	v_mfma_f32_16x16x32_bf16 v[98:101], v[168:171], v[192:195], v[98:101]
	v_mfma_f32_16x16x32_bf16 v[90:93], v[176:179], v[192:195], v[90:93]
	v_mfma_f32_16x16x32_bf16 v[82:85], v[168:171], v[200:203], v[82:85]
	v_mfma_f32_16x16x32_bf16 v[74:77], v[176:179], v[200:203], v[74:77]
	v_mfma_f32_16x16x32_bf16 v[70:73], v[168:171], v[208:211], v[70:73]
	v_mfma_f32_16x16x32_bf16 v[66:69], v[176:179], v[208:211], v[66:69]
	v_mfma_f32_16x16x32_bf16 v[114:117], v[172:175], v[188:191], v[114:117]
	v_mfma_f32_16x16x32_bf16 v[106:109], v[180:183], v[188:191], v[106:109]
	v_mfma_f32_16x16x32_bf16 v[98:101], v[172:175], v[196:199], v[98:101]
	v_mfma_f32_16x16x32_bf16 v[90:93], v[180:183], v[196:199], v[90:93]
	v_mfma_f32_16x16x32_bf16 v[82:85], v[172:175], v[204:207], v[82:85]
	v_mfma_f32_16x16x32_bf16 v[74:77], v[180:183], v[204:207], v[74:77]
	v_mfma_f32_16x16x32_bf16 v[70:73], v[172:175], v[212:215], v[70:73]
	v_mfma_f32_16x16x32_bf16 v[66:69], v[180:183], v[212:215], v[66:69]
	s_setprio 0
	s_barrier
	s_add_i32 s24, s81, s23
	v_lshl_add_u64 v[216:217], s[70:71], 0, v[134:135]
	s_mov_b32 m0, s24
	ds_read_b128 v[184:187], v150 offset:16384
	ds_read_b128 v[188:191], v150 offset:17408
	ds_read_b128 v[192:195], v150 offset:18432
	ds_read_b128 v[196:199], v150 offset:19456
	ds_read_b128 v[200:203], v150 offset:20480
	ds_read_b128 v[204:207], v150 offset:21504
	ds_read_b128 v[208:211], v150 offset:22528
	ds_read_b128 v[212:215], v150 offset:23552
	global_load_lds_dwordx4 v[216:217], off
	s_add_i32 m0, s24, 0x2000
	s_add_u32 s92, s70, 0x80000
	v_lshl_add_u64 v[218:219], s[70:71], 0, v[130:131]
	s_addc_u32 s93, s71, 0
	s_add_i32 s24, s82, s23
	global_load_lds_dwordx4 v[218:219], off
	v_lshl_add_u64 v[220:221], s[92:93], 0, v[134:135]
	s_mov_b32 m0, s24
	v_lshl_add_u64 v[222:223], s[72:73], 0, v[132:133]
	global_load_lds_dwordx4 v[220:221], off
	v_lshl_add_u64 v[220:221], s[92:93], 0, v[130:131]
	s_add_i32 m0, s24, 0x2000
	s_nop 0
	global_load_lds_dwordx4 v[220:221], off
	v_lshl_add_u64 v[220:221], s[72:73], 0, v[136:137]
	s_mov_b32 m0, s63
	s_nop 0
	global_load_lds_dwordx4 v[220:221], off
	s_mov_b32 m0, s75
	s_nop 0
	global_load_lds_dwordx4 v[222:223], off
	s_waitcnt vmcnt(8)
	s_waitcnt lgkmcnt(0)
	s_barrier
; #define PG8_STAGEA(bufoff, gbase, voff) PG8_STAGE_X(bufoff, gbase, voff, PG8_AUX_A)
; #define PG8_LDA(dst, b, h) do { _Pragma("unroll") for (int m = 0; m < 4; ++m) _Pragma("unroll") for (int k = 0; k < 2; ++k) dst[m][k] = *(const PG8_LAS bf16x8*)(lds + PG8_SA(b, h) + aoff + m * 2048 + k * 1024); } while (0)
; #define PG8_LDB(dst, b, h) do { _Pragma("unroll") for (int n = 0; n < 2; ++n) _Pragma("unroll") for (int k = 0; k < 2; ++k) dst[n][k] = *(const PG8_LAS bf16x8*)(lds + PG8_SB(b, h) + boff + n * 2048 + k * 1024); } while (0)
; #define PG8_MMA(ai, bj, At, Bt) do { __builtin_amdgcn_s_setprio(1); _Pragma("unroll") for (int m = 0; m < 4; ++m) _Pragma("unroll") for (int n = 0; n < 2; ++n) _Pragma("unroll") for (int k = 0; k < 2; ++k) \
;         acc[ai][bj][m][n] = __builtin_amdgcn_mfma_f32_16x16x32_bf16(Bt[n][k], At[m][k], acc[ai][bj][m][n], 0, 0, 0); __builtin_amdgcn_s_setprio(0); } while (0)
; #define PG8_WAIT_V(n) asm volatile("s_waitcnt vmcnt(" #n ")" ::: "memory")
; #define PG8_WAIT_L(n) asm volatile("s_waitcnt lgkmcnt(" #n ")" ::: "memory")
; #define PG8_BAR __builtin_amdgcn_s_barrier()
; #define PG8_SCHED __builtin_amdgcn_sched_barrier(0)
; template <class Epi, class Sched, bool ALIGN_EPI = false, bool SP2 = false>
; __device__ __forceinline__ void gemm_phase(PG8_LAS unsigned char* lds, const Gemm g, const Sched& S, const Epi& E) {
;     ...
;             PG8_WAIT_V(8); PG8_WAIT_L(0); PG8_BAR; PG8_MMA(1, 0, At, B0); PG8_MMA(1, 1, At, B1); PG8_BAR; PG8_SCHED;
;             PG8_LDB(B0, 1, 0); PG8_LDB(B1, 1, 1); PG8_SCHED; PG8_LDA(At, 1, 0); PG8_STAGEA(PG8_SA(0, 1), a2 + hstep, voffA);
;             PG8_WAIT_V(8); PG8_WAIT_L(0); PG8_BAR; PG8_MMA(0, 0, At, B0); PG8_MMA(0, 1, At, B1); PG8_BAR; PG8_SCHED;
	s_setprio 1
	s_waitcnt lgkmcnt(0)
	.p2align 3
	v_mfma_f32_16x16x32_bf16 v[62:65], v[152:155], v[184:187], v[62:65]
	v_mfma_f32_16x16x32_bf16 v[58:61], v[160:163], v[184:187], v[58:61]
	v_mfma_f32_16x16x32_bf16 v[54:57], v[152:155], v[192:195], v[54:57]
	v_mfma_f32_16x16x32_bf16 v[46:49], v[160:163], v[192:195], v[46:49]
	v_mfma_f32_16x16x32_bf16 v[38:41], v[152:155], v[200:203], v[38:41]
	v_mfma_f32_16x16x32_bf16 v[30:33], v[160:163], v[200:203], v[30:33]
	v_mfma_f32_16x16x32_bf16 v[22:25], v[152:155], v[208:211], v[22:25]
	v_mfma_f32_16x16x32_bf16 v[14:17], v[160:163], v[208:211], v[14:17]
	v_mfma_f32_16x16x32_bf16 v[62:65], v[156:159], v[188:191], v[62:65]
	v_mfma_f32_16x16x32_bf16 v[58:61], v[164:167], v[188:191], v[58:61]
	v_mfma_f32_16x16x32_bf16 v[54:57], v[156:159], v[196:199], v[54:57]
	v_mfma_f32_16x16x32_bf16 v[46:49], v[164:167], v[196:199], v[46:49]
	v_mfma_f32_16x16x32_bf16 v[38:41], v[156:159], v[204:207], v[38:41]
	v_mfma_f32_16x16x32_bf16 v[30:33], v[164:167], v[204:207], v[30:33]
	v_mfma_f32_16x16x32_bf16 v[22:25], v[156:159], v[212:215], v[22:25]
	v_mfma_f32_16x16x32_bf16 v[14:17], v[164:167], v[212:215], v[14:17]
	s_setprio 0
	s_setprio 1
	.p2align 3
	v_mfma_f32_16x16x32_bf16 v[50:53], v[168:171], v[184:187], v[50:53]
	v_mfma_f32_16x16x32_bf16 v[42:45], v[176:179], v[184:187], v[42:45]
	v_mfma_f32_16x16x32_bf16 v[34:37], v[168:171], v[192:195], v[34:37]
	v_mfma_f32_16x16x32_bf16 v[26:29], v[176:179], v[192:195], v[26:29]
	v_mfma_f32_16x16x32_bf16 v[18:21], v[168:171], v[200:203], v[18:21]
	v_mfma_f32_16x16x32_bf16 v[10:13], v[176:179], v[200:203], v[10:13]
	v_mfma_f32_16x16x32_bf16 v[6:9], v[168:171], v[208:211], v[6:9]
	v_mfma_f32_16x16x32_bf16 v[2:5], v[176:179], v[208:211], v[2:5]
	v_mfma_f32_16x16x32_bf16 v[50:53], v[172:175], v[188:191], v[50:53]
	v_mfma_f32_16x16x32_bf16 v[42:45], v[180:183], v[188:191], v[42:45]
	v_mfma_f32_16x16x32_bf16 v[34:37], v[172:175], v[196:199], v[34:37]
	v_mfma_f32_16x16x32_bf16 v[26:29], v[180:183], v[196:199], v[26:29]
	v_mfma_f32_16x16x32_bf16 v[18:21], v[172:175], v[204:207], v[18:21]
	v_mfma_f32_16x16x32_bf16 v[10:13], v[180:183], v[204:207], v[10:13]
	v_mfma_f32_16x16x32_bf16 v[6:9], v[172:175], v[212:215], v[6:9]
	v_mfma_f32_16x16x32_bf16 v[2:5], v[180:183], v[212:215], v[2:5]
	s_setprio 0
	s_barrier
	s_add_i32 s24, 0, 0x18000
	v_add_u32_e32 v151, s24, v146
	s_add_i32 s25, 0, 0x1c000
	ds_read_b128 v[152:155], v151
	ds_read_b128 v[156:159], v151 offset:1024
	ds_read_b128 v[160:163], v151 offset:2048
	ds_read_b128 v[164:167], v151 offset:3072
	v_add_u32_e32 v151, s25, v146
	ds_read_b128 v[168:171], v151
	ds_read_b128 v[172:175], v151 offset:1024
	ds_read_b128 v[176:179], v151 offset:2048
	ds_read_b128 v[180:183], v151 offset:3072
	s_add_u32 s72, s72, 0x80000
	s_addc_u32 s73, s73, 0
	s_mov_b32 m0, s76
	v_lshl_add_u64 v[224:225], s[72:73], 0, v[136:137]
	ds_read_b128 v[184:187], v150 offset:32768
	ds_read_b128 v[188:191], v150 offset:33792
	ds_read_b128 v[192:195], v150 offset:34816
	ds_read_b128 v[196:199], v150 offset:35840
	ds_read_b128 v[200:203], v150 offset:36864
	ds_read_b128 v[204:207], v150 offset:37888
	ds_read_b128 v[208:211], v150 offset:38912
	ds_read_b128 v[212:215], v150 offset:39936
	global_load_lds_dwordx4 v[224:225], off
	v_lshl_add_u64 v[224:225], s[72:73], 0, v[132:133]
	s_mov_b32 m0, s77
	s_nop 0
	global_load_lds_dwordx4 v[224:225], off
	s_waitcnt vmcnt(8)
	s_waitcnt lgkmcnt(0)
	s_barrier
	s_setprio 1
	s_waitcnt lgkmcnt(0)
	.p2align 3
	v_mfma_f32_16x16x32_bf16 v[126:129], v[152:155], v[184:187], v[126:129]
	v_mfma_f32_16x16x32_bf16 v[122:125], v[160:163], v[184:187], v[122:125]
	v_mfma_f32_16x16x32_bf16 v[118:121], v[152:155], v[192:195], v[118:121]
	v_mfma_f32_16x16x32_bf16 v[110:113], v[160:163], v[192:195], v[110:113]
	v_mfma_f32_16x16x32_bf16 v[102:105], v[152:155], v[200:203], v[102:105]
	v_mfma_f32_16x16x32_bf16 v[94:97], v[160:163], v[200:203], v[94:97]
	v_mfma_f32_16x16x32_bf16 v[86:89], v[152:155], v[208:211], v[86:89]
	v_mfma_f32_16x16x32_bf16 v[78:81], v[160:163], v[208:211], v[78:81]
	v_mfma_f32_16x16x32_bf16 v[126:129], v[156:159], v[188:191], v[126:129]
	v_mfma_f32_16x16x32_bf16 v[122:125], v[164:167], v[188:191], v[122:125]
	v_mfma_f32_16x16x32_bf16 v[118:121], v[156:159], v[196:199], v[118:121]
	v_mfma_f32_16x16x32_bf16 v[110:113], v[164:167], v[196:199], v[110:113]
	v_mfma_f32_16x16x32_bf16 v[102:105], v[156:159], v[204:207], v[102:105]
	v_mfma_f32_16x16x32_bf16 v[94:97], v[164:167], v[204:207], v[94:97]
	v_mfma_f32_16x16x32_bf16 v[86:89], v[156:159], v[212:215], v[86:89]
	v_mfma_f32_16x16x32_bf16 v[78:81], v[164:167], v[212:215], v[78:81]
	s_setprio 0
	s_setprio 1
	.p2align 3
	v_mfma_f32_16x16x32_bf16 v[114:117], v[168:171], v[184:187], v[114:117]
	v_mfma_f32_16x16x32_bf16 v[106:109], v[176:179], v[184:187], v[106:109]
	v_mfma_f32_16x16x32_bf16 v[98:101], v[168:171], v[192:195], v[98:101]
	v_mfma_f32_16x16x32_bf16 v[90:93], v[176:179], v[192:195], v[90:93]
	v_mfma_f32_16x16x32_bf16 v[82:85], v[168:171], v[200:203], v[82:85]
	v_mfma_f32_16x16x32_bf16 v[74:77], v[176:179], v[200:203], v[74:77]
	v_mfma_f32_16x16x32_bf16 v[70:73], v[168:171], v[208:211], v[70:73]
	v_mfma_f32_16x16x32_bf16 v[66:69], v[176:179], v[208:211], v[66:69]
	v_mfma_f32_16x16x32_bf16 v[114:117], v[172:175], v[188:191], v[114:117]
	v_mfma_f32_16x16x32_bf16 v[106:109], v[180:183], v[188:191], v[106:109]
	v_mfma_f32_16x16x32_bf16 v[98:101], v[172:175], v[196:199], v[98:101]
	v_mfma_f32_16x16x32_bf16 v[90:93], v[180:183], v[196:199], v[90:93]
	v_mfma_f32_16x16x32_bf16 v[82:85], v[172:175], v[204:207], v[82:85]
	v_mfma_f32_16x16x32_bf16 v[74:77], v[180:183], v[204:207], v[74:77]
	v_mfma_f32_16x16x32_bf16 v[70:73], v[172:175], v[212:215], v[70:73]
	v_mfma_f32_16x16x32_bf16 v[66:69], v[180:183], v[212:215], v[66:69]
	s_setprio 0
	s_barrier
; #define PG8_STAGEA(bufoff, gbase, voff) PG8_STAGE_X(bufoff, gbase, voff, PG8_AUX_A)
; #define PG8_STAGEB(bufoff, gbase, voff) PG8_STAGE_X(bufoff, gbase, voff, PG8_AUX_B)
; #define PG8_LDA(dst, b, h) do { _Pragma("unroll") for (int m = 0; m < 4; ++m) _Pragma("unroll") for (int k = 0; k < 2; ++k) dst[m][k] = *(const PG8_LAS bf16x8*)(lds + PG8_SA(b, h) + aoff + m * 2048 + k * 1024); } while (0)
; #define PG8_MMA(ai, bj, At, Bt) do { __builtin_amdgcn_s_setprio(1); _Pragma("unroll") for (int m = 0; m < 4; ++m) _Pragma("unroll") for (int n = 0; n < 2; ++n) _Pragma("unroll") for (int k = 0; k < 2; ++k) \
;         acc[ai][bj][m][n] = __builtin_amdgcn_mfma_f32_16x16x32_bf16(Bt[n][k], At[m][k], acc[ai][bj][m][n], 0, 0, 0); __builtin_amdgcn_s_setprio(0); } while (0)
; #define PG8_WAIT_V(n) asm volatile("s_waitcnt vmcnt(" #n ")" ::: "memory")
; #define PG8_WAIT_L(n) asm volatile("s_waitcnt lgkmcnt(" #n ")" ::: "memory")
; #define PG8_BAR __builtin_amdgcn_s_barrier()
; #define PG8_SCHED __builtin_amdgcn_sched_barrier(0)
; template <class Epi, class Sched, bool ALIGN_EPI = false, bool SP2 = false>
; __device__ __forceinline__ void gemm_phase(PG8_LAS unsigned char* lds, const Gemm g, const Sched& S, const Epi& E) {
;     ...
;             PG8_LDA(At, 1, 1); PG8_STAGEB(PG8_SB(1, 0), b3, voffB); PG8_STAGEB(PG8_SB(1, 1), b3 + hstep, voffB); PG8_STAGEA(PG8_SA(1, 0), a3, voffA);
;             PG8_WAIT_V(8); PG8_WAIT_L(0); PG8_BAR; PG8_MMA(1, 0, At, B0); PG8_MMA(1, 1, At, B1); PG8_BAR; PG8_SCHED;
;     ...
;         if constexpr (ALIGN_EPI) { if (wr == 0) PG8_BAR; }
	s_add_i32 s24, s24, s23
	v_lshl_add_u64 v[216:217], v[216:217], 0, s[36:37]
	s_mov_b32 m0, s24
	ds_read_b128 v[184:187], v150 offset:49152
	ds_read_b128 v[188:191], v150 offset:50176
	ds_read_b128 v[192:195], v150 offset:51200
	ds_read_b128 v[196:199], v150 offset:52224
	ds_read_b128 v[200:203], v150 offset:53248
	ds_read_b128 v[204:207], v150 offset:54272
	ds_read_b128 v[208:211], v150 offset:55296
	ds_read_b128 v[212:215], v150 offset:56320
	global_load_lds_dwordx4 v[216:217], off
	s_add_i32 m0, s24, 0x2000
	s_add_u32 s70, s70, 0x80080
	v_lshl_add_u64 v[216:217], v[218:219], 0, s[36:37]
	s_addc_u32 s71, s71, 0
	s_add_i32 s24, s25, s23
	global_load_lds_dwordx4 v[216:217], off
	v_lshl_add_u64 v[216:217], s[70:71], 0, v[134:135]
	s_mov_b32 m0, s24
	s_nop 0
	global_load_lds_dwordx4 v[216:217], off
	v_lshl_add_u64 v[216:217], s[70:71], 0, v[130:131]
	s_add_i32 m0, s24, 0x2000
	s_nop 0
	global_load_lds_dwordx4 v[216:217], off
	v_lshl_add_u64 v[216:217], v[220:221], 0, s[36:37]
	s_mov_b32 m0, s79
	s_nop 0
	global_load_lds_dwordx4 v[216:217], off
	v_lshl_add_u64 v[216:217], v[222:223], 0, s[36:37]
	s_mov_b32 m0, s80
	s_nop 0
	global_load_lds_dwordx4 v[216:217], off
	s_waitcnt vmcnt(8)
	s_waitcnt lgkmcnt(0)
	s_barrier
	s_setprio 1
	s_waitcnt lgkmcnt(0)
	.p2align 3
	v_mfma_f32_16x16x32_bf16 v[62:65], v[152:155], v[184:187], v[62:65]
	v_mfma_f32_16x16x32_bf16 v[58:61], v[160:163], v[184:187], v[58:61]
	v_mfma_f32_16x16x32_bf16 v[54:57], v[152:155], v[192:195], v[54:57]
	v_mfma_f32_16x16x32_bf16 v[46:49], v[160:163], v[192:195], v[46:49]
	v_mfma_f32_16x16x32_bf16 v[38:41], v[152:155], v[200:203], v[38:41]
	v_mfma_f32_16x16x32_bf16 v[30:33], v[160:163], v[200:203], v[30:33]
	v_mfma_f32_16x16x32_bf16 v[22:25], v[152:155], v[208:211], v[22:25]
	v_mfma_f32_16x16x32_bf16 v[14:17], v[160:163], v[208:211], v[14:17]
	v_mfma_f32_16x16x32_bf16 v[62:65], v[156:159], v[188:191], v[62:65]
	v_mfma_f32_16x16x32_bf16 v[58:61], v[164:167], v[188:191], v[58:61]
	v_mfma_f32_16x16x32_bf16 v[54:57], v[156:159], v[196:199], v[54:57]
	v_mfma_f32_16x16x32_bf16 v[46:49], v[164:167], v[196:199], v[46:49]
	v_mfma_f32_16x16x32_bf16 v[38:41], v[156:159], v[204:207], v[38:41]
	v_mfma_f32_16x16x32_bf16 v[30:33], v[164:167], v[204:207], v[30:33]
	v_mfma_f32_16x16x32_bf16 v[22:25], v[156:159], v[212:215], v[22:25]
	v_mfma_f32_16x16x32_bf16 v[14:17], v[164:167], v[212:215], v[14:17]
	s_setprio 0
	s_setprio 1
	.p2align 3
	v_mfma_f32_16x16x32_bf16 v[50:53], v[168:171], v[184:187], v[50:53]
	v_mfma_f32_16x16x32_bf16 v[42:45], v[176:179], v[184:187], v[42:45]
	v_mfma_f32_16x16x32_bf16 v[34:37], v[168:171], v[192:195], v[34:37]
	v_mfma_f32_16x16x32_bf16 v[26:29], v[176:179], v[192:195], v[26:29]
	v_mfma_f32_16x16x32_bf16 v[18:21], v[168:171], v[200:203], v[18:21]
	v_mfma_f32_16x16x32_bf16 v[10:13], v[176:179], v[200:203], v[10:13]
	v_mfma_f32_16x16x32_bf16 v[6:9], v[168:171], v[208:211], v[6:9]
	v_mfma_f32_16x16x32_bf16 v[2:5], v[176:179], v[208:211], v[2:5]
	v_mfma_f32_16x16x32_bf16 v[50:53], v[172:175], v[188:191], v[50:53]
	v_mfma_f32_16x16x32_bf16 v[42:45], v[180:183], v[188:191], v[42:45]
	v_mfma_f32_16x16x32_bf16 v[34:37], v[172:175], v[196:199], v[34:37]
	v_mfma_f32_16x16x32_bf16 v[26:29], v[180:183], v[196:199], v[26:29]
	v_mfma_f32_16x16x32_bf16 v[18:21], v[172:175], v[204:207], v[18:21]
	v_mfma_f32_16x16x32_bf16 v[10:13], v[180:183], v[204:207], v[10:13]
	v_mfma_f32_16x16x32_bf16 v[6:9], v[172:175], v[212:215], v[6:9]
	v_mfma_f32_16x16x32_bf16 v[2:5], v[180:183], v[212:215], v[2:5]
	s_setprio 0
	s_barrier
	s_add_u32 s68, s68, 0x100
	s_addc_u32 s69, s69, 0
	s_mov_b32 s70, s91
	s_cbranch_vccz .LBB0_766
	s_and_b64 vcc, exec, s[46:47]
	s_cbranch_vccz .LBB0_769
	s_barrier

; #define PG8_STAGEA(bufoff, gbase, voff) PG8_STAGE_X(bufoff, gbase, voff, PG8_AUX_A)
; #define PG8_STAGEB(bufoff, gbase, voff) PG8_STAGE_X(bufoff, gbase, voff, PG8_AUX_B)
; #define PG8_LDA(dst, b, h) do { _Pragma("unroll") for (int m = 0; m < 4; ++m) _Pragma("unroll") for (int k = 0; k < 2; ++k) dst[m][k] = *(const PG8_LAS bf16x8*)(lds + PG8_SA(b, h) + aoff + m * 2048 + k * 1024); } while (0)
; #define PG8_LDB(dst, b, h) do { _Pragma("unroll") for (int n = 0; n < 2; ++n) _Pragma("unroll") for (int k = 0; k < 2; ++k) dst[n][k] = *(const PG8_LAS bf16x8*)(lds + PG8_SB(b, h) + boff + n * 2048 + k * 1024); } while (0)
; #define PG8_MMA(ai, bj, At, Bt) do { __builtin_amdgcn_s_setprio(1); _Pragma("unroll") for (int m = 0; m < 4; ++m) _Pragma("unroll") for (int n = 0; n < 2; ++n) _Pragma("unroll") for (int k = 0; k < 2; ++k) \
;         acc[ai][bj][m][n] = __builtin_amdgcn_mfma_f32_16x16x32_bf16(Bt[n][k], At[m][k], acc[ai][bj][m][n], 0, 0, 0); __builtin_amdgcn_s_setprio(0); } while (0)
; #define PG8_WAIT_V(n) asm volatile("s_waitcnt vmcnt(" #n ")" ::: "memory")
; #define PG8_WAIT_L(n) asm volatile("s_waitcnt lgkmcnt(" #n ")" ::: "memory")
; template <class Epi, class Sched, bool ALIGN_EPI = false, bool SP2 = false>
; __device__ __forceinline__ void gemm_phase(PG8_LAS unsigned char* lds, const Gemm g, const Sched& S, const Epi& E) {
;     ...
;             const char* sA1 = (t + 1 >= ns) ? cA2 : cA; const char* sA2 = (t + 2 >= ns) ? cA2 : cA; const char* sB2 = (t + 2 >= ns) ? cB2 : cB;
;             const char* a1 = sA1 + (size_t)(t + 1) * kstep;
;             const char* a2 = last ? nA : sA2 + (size_t)(t + 2) * kstep; const char* b2 = last ? nB : sB2 + (size_t)(t + 2) * kstep;
;             const char* a3 = a2 + kstep; const char* b3 = b2 + kstep;
;             if (last && has_next) S.a_ready(nxt);
;             if constexpr (SP2) {
;             PG8_LDB(B0, 0, 0); PG8_LDB(B1, 0, 1); PG8_SCHED; PG8_LDA(At, 0, 0); PG8_STAGEA(PG8_SA(1, 1), a1 + hstep, voffA);
;             PG8_WAIT_V(8); PG8_WAIT_L(0); PG8_BAR; PG8_MMA(0, 0, At, B0); PG8_MMA(0, 1, At, B1); PG8_BAR; PG8_SCHED;
;             PG8_LDA(At, 0, 1); PG8_STAGEB(PG8_SB(0, 0), b2, voffB); PG8_STAGEB(PG8_SB(0, 1), b2 + hstep, voffB); PG8_STAGEA(PG8_SA(0, 0), a2, voffA);
;             PG8_WAIT_V(8); PG8_WAIT_L(0); PG8_BAR; PG8_MMA(1, 0, At, B0); PG8_MMA(1, 1, At, B1); PG8_BAR; PG8_SCHED;
.LBB0_920:
	ds_read_b128 v[82:85], v164
	ds_read_b128 v[90:93], v164 offset:1024
	ds_read_b128 v[94:97], v164 offset:2048
	ds_read_b128 v[158:161], v164 offset:3072
	ds_read_b128 v[168:171], v165
	ds_read_b128 v[172:175], v165 offset:1024
	ds_read_b128 v[176:179], v165 offset:2048
	ds_read_b128 v[180:183], v165 offset:3072
	ds_read_b128 v[184:187], v166
	ds_read_b128 v[188:191], v166 offset:1024
	ds_read_b128 v[192:195], v166 offset:2048
	ds_read_b128 v[196:199], v166 offset:3072
	ds_read_b128 v[200:203], v166 offset:4096
	ds_read_b128 v[204:207], v166 offset:5120
	ds_read_b128 v[208:211], v166 offset:6144
	ds_read_b128 v[212:215], v166 offset:7168
	s_add_i32 s87, s66, 2
	s_cmp_lt_u32 s87, 6
	s_cselect_b32 s29, s62, s40
	s_cselect_b32 s24, s61, s37
	s_cselect_b32 s25, s60, s36
	s_cselect_b32 s28, s63, s41
	s_add_u32 s29, s29, s64
	s_addc_u32 s28, s28, s65
	s_add_u32 s29, s29, 0xfffe0080
	s_addc_u32 s28, s28, -1
	s_add_u32 s25, s25, s64
	s_addc_u32 s24, s24, s65
	s_add_u32 s25, s25, 0xfffe0080
	s_addc_u32 s24, s24, -1
	s_cmp_eq_u32 s66, 4
	s_cselect_b32 s73, s51, s28
	s_cselect_b32 s72, s57, s29
	s_cselect_b32 s75, s49, s24
	s_cselect_b32 s74, s86, s25
	s_add_i32 s25, s84, s23
	s_add_i32 m0, s26, 0xc000
	s_add_i32 s24, s26, 0xe000
	s_add_i32 s28, s25, 0x2000
	s_add_u32 s76, s74, 0x20000
	s_addc_u32 s77, s75, 0
	s_add_i32 s29, s85, s23
	s_add_i32 s92, s29, 0x2000
	s_add_i32 s93, 0, 0x18000
	s_add_i32 s94, 0, 0x1c000
	s_add_u32 s70, s72, 0x20000
	s_addc_u32 s71, s73, 0
	s_add_i32 s90, s93, s23
	s_add_i32 s88, s90, 0x2000
	s_add_u32 s68, s74, 0x20080
	s_addc_u32 s69, s75, 0
	s_add_i32 s89, s94, s23
	s_add_i32 s91, s89, 0x2000
	s_add_u32 s66, s64, 0x100
	s_addc_u32 s67, s65, 0
	s_cmp_gt_u32 s87, 5
	v_lshl_add_u64 v[216:217], v[70:71], 0, s[64:65]
	global_load_lds_dwordx4 v[216:217], off
	v_lshl_add_u64 v[216:217], v[72:73], 0, s[64:65]
	s_mov_b32 m0, s24
	s_nop 0
	global_load_lds_dwordx4 v[216:217], off
	s_waitcnt vmcnt(8)
	s_waitcnt lgkmcnt(0)
	s_barrier
	s_setprio 1
	s_waitcnt lgkmcnt(0)
	.p2align 3
	v_mfma_f32_16x16x32_bf16 v[142:145], v[82:85], v[184:187], v[142:145]
	v_mfma_f32_16x16x32_bf16 v[138:141], v[94:97], v[184:187], v[138:141]
	v_mfma_f32_16x16x32_bf16 v[126:129], v[82:85], v[192:195], v[126:129]
	v_mfma_f32_16x16x32_bf16 v[122:125], v[94:97], v[192:195], v[122:125]
	v_mfma_f32_16x16x32_bf16 v[110:113], v[82:85], v[200:203], v[110:113]
	v_mfma_f32_16x16x32_bf16 v[106:109], v[94:97], v[200:203], v[106:109]
	v_mfma_f32_16x16x32_bf16 v[86:89], v[82:85], v[208:211], v[86:89]
	v_mfma_f32_16x16x32_bf16 v[78:81], v[94:97], v[208:211], v[78:81]
	v_mfma_f32_16x16x32_bf16 v[142:145], v[90:93], v[188:191], v[142:145]
	v_mfma_f32_16x16x32_bf16 v[138:141], v[158:161], v[188:191], v[138:141]
	v_mfma_f32_16x16x32_bf16 v[126:129], v[90:93], v[196:199], v[126:129]
	v_mfma_f32_16x16x32_bf16 v[122:125], v[158:161], v[196:199], v[122:125]
	v_mfma_f32_16x16x32_bf16 v[110:113], v[90:93], v[204:207], v[110:113]
	v_mfma_f32_16x16x32_bf16 v[106:109], v[158:161], v[204:207], v[106:109]
	v_mfma_f32_16x16x32_bf16 v[86:89], v[90:93], v[212:215], v[86:89]
	v_mfma_f32_16x16x32_bf16 v[78:81], v[158:161], v[212:215], v[78:81]
	s_setprio 0
	s_setprio 1
	.p2align 3
	v_mfma_f32_16x16x32_bf16 v[134:137], v[168:171], v[184:187], v[134:137]
	v_mfma_f32_16x16x32_bf16 v[130:133], v[176:179], v[184:187], v[130:133]
	v_mfma_f32_16x16x32_bf16 v[118:121], v[168:171], v[192:195], v[118:121]
	v_mfma_f32_16x16x32_bf16 v[114:117], v[176:179], v[192:195], v[114:117]
	v_mfma_f32_16x16x32_bf16 v[102:105], v[168:171], v[200:203], v[102:105]
	v_mfma_f32_16x16x32_bf16 v[98:101], v[176:179], v[200:203], v[98:101]
	v_mfma_f32_16x16x32_bf16 v[74:77], v[168:171], v[208:211], v[74:77]
	v_mfma_f32_16x16x32_bf16 v[66:69], v[176:179], v[208:211], v[66:69]
	v_mfma_f32_16x16x32_bf16 v[134:137], v[172:175], v[188:191], v[134:137]
	v_mfma_f32_16x16x32_bf16 v[130:133], v[180:183], v[188:191], v[130:133]
	v_mfma_f32_16x16x32_bf16 v[118:121], v[172:175], v[196:199], v[118:121]
	v_mfma_f32_16x16x32_bf16 v[114:117], v[180:183], v[196:199], v[114:117]
	v_mfma_f32_16x16x32_bf16 v[102:105], v[172:175], v[204:207], v[102:105]
	v_mfma_f32_16x16x32_bf16 v[98:101], v[180:183], v[204:207], v[98:101]
	v_mfma_f32_16x16x32_bf16 v[74:77], v[172:175], v[212:215], v[74:77]
	v_mfma_f32_16x16x32_bf16 v[66:69], v[180:183], v[212:215], v[66:69]
	s_setprio 0
	s_barrier
	s_mov_b32 m0, s25
	v_lshl_add_u64 v[216:217], s[74:75], 0, v[146:147]
	ds_read_b128 v[184:187], v166 offset:16384
	ds_read_b128 v[188:191], v166 offset:17408
	ds_read_b128 v[192:195], v166 offset:18432
	ds_read_b128 v[196:199], v166 offset:19456
	ds_read_b128 v[200:203], v166 offset:20480
	ds_read_b128 v[204:207], v166 offset:21504
	ds_read_b128 v[208:211], v166 offset:22528
	ds_read_b128 v[212:215], v166 offset:23552
	global_load_lds_dwordx4 v[216:217], off
	v_lshl_add_u64 v[218:219], s[74:75], 0, v[148:149]
	s_mov_b32 m0, s28
	v_lshl_add_u64 v[220:221], s[76:77], 0, v[146:147]
	global_load_lds_dwordx4 v[218:219], off
	s_mov_b32 m0, s29
	v_lshl_add_u64 v[222:223], s[72:73], 0, v[148:149]
	global_load_lds_dwordx4 v[220:221], off
	v_lshl_add_u64 v[220:221], s[76:77], 0, v[148:149]
	s_mov_b32 m0, s92
	s_nop 0
	global_load_lds_dwordx4 v[220:221], off
	v_lshl_add_u64 v[220:221], s[72:73], 0, v[146:147]
	s_mov_b32 m0, s26
	s_nop 0
	global_load_lds_dwordx4 v[220:221], off
	s_mov_b32 m0, s27
	s_nop 0
	global_load_lds_dwordx4 v[222:223], off
	s_waitcnt vmcnt(8)
	s_waitcnt lgkmcnt(0)
	s_barrier
; #define PG8_STAGEA(bufoff, gbase, voff) PG8_STAGE_X(bufoff, gbase, voff, PG8_AUX_A)
; #define PG8_LDA(dst, b, h) do { _Pragma("unroll") for (int m = 0; m < 4; ++m) _Pragma("unroll") for (int k = 0; k < 2; ++k) dst[m][k] = *(const PG8_LAS bf16x8*)(lds + PG8_SA(b, h) + aoff + m * 2048 + k * 1024); } while (0)
; #define PG8_LDB(dst, b, h) do { _Pragma("unroll") for (int n = 0; n < 2; ++n) _Pragma("unroll") for (int k = 0; k < 2; ++k) dst[n][k] = *(const PG8_LAS bf16x8*)(lds + PG8_SB(b, h) + boff + n * 2048 + k * 1024); } while (0)
; #define PG8_MMA(ai, bj, At, Bt) do { __builtin_amdgcn_s_setprio(1); _Pragma("unroll") for (int m = 0; m < 4; ++m) _Pragma("unroll") for (int n = 0; n < 2; ++n) _Pragma("unroll") for (int k = 0; k < 2; ++k) \
;         acc[ai][bj][m][n] = __builtin_amdgcn_mfma_f32_16x16x32_bf16(Bt[n][k], At[m][k], acc[ai][bj][m][n], 0, 0, 0); __builtin_amdgcn_s_setprio(0); } while (0)
; #define PG8_WAIT_V(n) asm volatile("s_waitcnt vmcnt(" #n ")" ::: "memory")
; #define PG8_WAIT_L(n) asm volatile("s_waitcnt lgkmcnt(" #n ")" ::: "memory")
; #define PG8_BAR __builtin_amdgcn_s_barrier()
; #define PG8_SCHED __builtin_amdgcn_sched_barrier(0)
; template <class Epi, class Sched, bool ALIGN_EPI = false, bool SP2 = false>
; __device__ __forceinline__ void gemm_phase(PG8_LAS unsigned char* lds, const Gemm g, const Sched& S, const Epi& E) {
;     ...
;             PG8_WAIT_V(8); PG8_WAIT_L(0); PG8_BAR; PG8_MMA(1, 0, At, B0); PG8_MMA(1, 1, At, B1); PG8_BAR; PG8_SCHED;
;             PG8_LDB(B0, 1, 0); PG8_LDB(B1, 1, 1); PG8_SCHED; PG8_LDA(At, 1, 0); PG8_STAGEA(PG8_SA(0, 1), a2 + hstep, voffA);
;             PG8_WAIT_V(8); PG8_WAIT_L(0); PG8_BAR; PG8_MMA(0, 0, At, B0); PG8_MMA(0, 1, At, B1); PG8_BAR; PG8_SCHED;
	s_setprio 1
	s_waitcnt lgkmcnt(0)
	.p2align 3
	v_mfma_f32_16x16x32_bf16 v[62:65], v[82:85], v[184:187], v[62:65]
	v_mfma_f32_16x16x32_bf16 v[58:61], v[94:97], v[184:187], v[58:61]
	v_mfma_f32_16x16x32_bf16 v[46:49], v[82:85], v[192:195], v[46:49]
	v_mfma_f32_16x16x32_bf16 v[42:45], v[94:97], v[192:195], v[42:45]
	v_mfma_f32_16x16x32_bf16 v[30:33], v[82:85], v[200:203], v[30:33]
	v_mfma_f32_16x16x32_bf16 v[26:29], v[94:97], v[200:203], v[26:29]
	v_mfma_f32_16x16x32_bf16 v[14:17], v[82:85], v[208:211], v[14:17]
	v_mfma_f32_16x16x32_bf16 v[10:13], v[94:97], v[208:211], v[10:13]
	v_mfma_f32_16x16x32_bf16 v[62:65], v[90:93], v[188:191], v[62:65]
	v_mfma_f32_16x16x32_bf16 v[58:61], v[158:161], v[188:191], v[58:61]
	v_mfma_f32_16x16x32_bf16 v[46:49], v[90:93], v[196:199], v[46:49]
	v_mfma_f32_16x16x32_bf16 v[42:45], v[158:161], v[196:199], v[42:45]
	v_mfma_f32_16x16x32_bf16 v[30:33], v[90:93], v[204:207], v[30:33]
	v_mfma_f32_16x16x32_bf16 v[26:29], v[158:161], v[204:207], v[26:29]
	v_mfma_f32_16x16x32_bf16 v[14:17], v[90:93], v[212:215], v[14:17]
	v_mfma_f32_16x16x32_bf16 v[10:13], v[158:161], v[212:215], v[10:13]
	s_setprio 0
	s_setprio 1
	.p2align 3
	v_mfma_f32_16x16x32_bf16 v[54:57], v[168:171], v[184:187], v[54:57]
	v_mfma_f32_16x16x32_bf16 v[50:53], v[176:179], v[184:187], v[50:53]
	v_mfma_f32_16x16x32_bf16 v[38:41], v[168:171], v[192:195], v[38:41]
	v_mfma_f32_16x16x32_bf16 v[34:37], v[176:179], v[192:195], v[34:37]
	v_mfma_f32_16x16x32_bf16 v[22:25], v[168:171], v[200:203], v[22:25]
	v_mfma_f32_16x16x32_bf16 v[18:21], v[176:179], v[200:203], v[18:21]
	v_mfma_f32_16x16x32_bf16 v[6:9], v[168:171], v[208:211], v[6:9]
	v_mfma_f32_16x16x32_bf16 v[2:5], v[176:179], v[208:211], v[2:5]
	v_mfma_f32_16x16x32_bf16 v[54:57], v[172:175], v[188:191], v[54:57]
	v_mfma_f32_16x16x32_bf16 v[50:53], v[180:183], v[188:191], v[50:53]
	v_mfma_f32_16x16x32_bf16 v[38:41], v[172:175], v[196:199], v[38:41]
	v_mfma_f32_16x16x32_bf16 v[34:37], v[180:183], v[196:199], v[34:37]
	v_mfma_f32_16x16x32_bf16 v[22:25], v[172:175], v[204:207], v[22:25]
	v_mfma_f32_16x16x32_bf16 v[18:21], v[180:183], v[204:207], v[18:21]
	v_mfma_f32_16x16x32_bf16 v[6:9], v[172:175], v[212:215], v[6:9]
	v_mfma_f32_16x16x32_bf16 v[2:5], v[180:183], v[212:215], v[2:5]
	s_setprio 0
	s_barrier
	v_add_u32_e32 v158, s93, v162
	v_add_u32_e32 v180, s94, v162
	ds_read_b128 v[82:85], v158
	ds_read_b128 v[90:93], v158 offset:1024
	ds_read_b128 v[94:97], v158 offset:2048
	ds_read_b128 v[158:161], v158 offset:3072
	ds_read_b128 v[168:171], v180
	ds_read_b128 v[172:175], v180 offset:1024
	ds_read_b128 v[176:179], v180 offset:2048
	ds_read_b128 v[180:183], v180 offset:3072
	s_mov_b32 m0, s33
	v_lshl_add_u64 v[224:225], s[70:71], 0, v[146:147]
	ds_read_b128 v[184:187], v166 offset:32768
	ds_read_b128 v[188:191], v166 offset:33792
	ds_read_b128 v[192:195], v166 offset:34816
	ds_read_b128 v[196:199], v166 offset:35840
	ds_read_b128 v[200:203], v166 offset:36864
	ds_read_b128 v[204:207], v166 offset:37888
	ds_read_b128 v[208:211], v166 offset:38912
	ds_read_b128 v[212:215], v166 offset:39936
	global_load_lds_dwordx4 v[224:225], off
	v_lshl_add_u64 v[224:225], s[70:71], 0, v[148:149]
	s_mov_b32 m0, s59
	s_nop 0
	global_load_lds_dwordx4 v[224:225], off
	s_waitcnt vmcnt(8)
	s_waitcnt lgkmcnt(0)
	s_barrier
	s_setprio 1
	s_waitcnt lgkmcnt(0)
	.p2align 3
	v_mfma_f32_16x16x32_bf16 v[142:145], v[82:85], v[184:187], v[142:145]
	v_mfma_f32_16x16x32_bf16 v[138:141], v[94:97], v[184:187], v[138:141]
	v_mfma_f32_16x16x32_bf16 v[126:129], v[82:85], v[192:195], v[126:129]
	v_mfma_f32_16x16x32_bf16 v[122:125], v[94:97], v[192:195], v[122:125]
	v_mfma_f32_16x16x32_bf16 v[110:113], v[82:85], v[200:203], v[110:113]
	v_mfma_f32_16x16x32_bf16 v[106:109], v[94:97], v[200:203], v[106:109]
	v_mfma_f32_16x16x32_bf16 v[86:89], v[82:85], v[208:211], v[86:89]
	v_mfma_f32_16x16x32_bf16 v[78:81], v[94:97], v[208:211], v[78:81]
	v_mfma_f32_16x16x32_bf16 v[142:145], v[90:93], v[188:191], v[142:145]
	v_mfma_f32_16x16x32_bf16 v[138:141], v[158:161], v[188:191], v[138:141]
	v_mfma_f32_16x16x32_bf16 v[126:129], v[90:93], v[196:199], v[126:129]
	v_mfma_f32_16x16x32_bf16 v[122:125], v[158:161], v[196:199], v[122:125]
	v_mfma_f32_16x16x32_bf16 v[110:113], v[90:93], v[204:207], v[110:113]
	v_mfma_f32_16x16x32_bf16 v[106:109], v[158:161], v[204:207], v[106:109]
	v_mfma_f32_16x16x32_bf16 v[86:89], v[90:93], v[212:215], v[86:89]
	v_mfma_f32_16x16x32_bf16 v[78:81], v[158:161], v[212:215], v[78:81]
	s_setprio 0
	s_setprio 1
	.p2align 3
	v_mfma_f32_16x16x32_bf16 v[134:137], v[168:171], v[184:187], v[134:137]
	v_mfma_f32_16x16x32_bf16 v[130:133], v[176:179], v[184:187], v[130:133]
	v_mfma_f32_16x16x32_bf16 v[118:121], v[168:171], v[192:195], v[118:121]
	v_mfma_f32_16x16x32_bf16 v[114:117], v[176:179], v[192:195], v[114:117]
	v_mfma_f32_16x16x32_bf16 v[102:105], v[168:171], v[200:203], v[102:105]
	v_mfma_f32_16x16x32_bf16 v[98:101], v[176:179], v[200:203], v[98:101]
	v_mfma_f32_16x16x32_bf16 v[74:77], v[168:171], v[208:211], v[74:77]
	v_mfma_f32_16x16x32_bf16 v[66:69], v[176:179], v[208:211], v[66:69]
	v_mfma_f32_16x16x32_bf16 v[134:137], v[172:175], v[188:191], v[134:137]
	v_mfma_f32_16x16x32_bf16 v[130:133], v[180:183], v[188:191], v[130:133]
	v_mfma_f32_16x16x32_bf16 v[118:121], v[172:175], v[196:199], v[118:121]
	v_mfma_f32_16x16x32_bf16 v[114:117], v[180:183], v[196:199], v[114:117]
	v_mfma_f32_16x16x32_bf16 v[102:105], v[172:175], v[204:207], v[102:105]
	v_mfma_f32_16x16x32_bf16 v[98:101], v[180:183], v[204:207], v[98:101]
	v_mfma_f32_16x16x32_bf16 v[74:77], v[172:175], v[212:215], v[74:77]
	v_mfma_f32_16x16x32_bf16 v[66:69], v[180:183], v[212:215], v[66:69]
	s_setprio 0
	s_barrier
; #define PG8_STAGEA(bufoff, gbase, voff) PG8_STAGE_X(bufoff, gbase, voff, PG8_AUX_A)
; #define PG8_STAGEB(bufoff, gbase, voff) PG8_STAGE_X(bufoff, gbase, voff, PG8_AUX_B)
; #define PG8_LDA(dst, b, h) do { _Pragma("unroll") for (int m = 0; m < 4; ++m) _Pragma("unroll") for (int k = 0; k < 2; ++k) dst[m][k] = *(const PG8_LAS bf16x8*)(lds + PG8_SA(b, h) + aoff + m * 2048 + k * 1024); } while (0)
; #define PG8_MMA(ai, bj, At, Bt) do { __builtin_amdgcn_s_setprio(1); _Pragma("unroll") for (int m = 0; m < 4; ++m) _Pragma("unroll") for (int n = 0; n < 2; ++n) _Pragma("unroll") for (int k = 0; k < 2; ++k) \
;         acc[ai][bj][m][n] = __builtin_amdgcn_mfma_f32_16x16x32_bf16(Bt[n][k], At[m][k], acc[ai][bj][m][n], 0, 0, 0); __builtin_amdgcn_s_setprio(0); } while (0)
; #define PG8_WAIT_V(n) asm volatile("s_waitcnt vmcnt(" #n ")" ::: "memory")
; #define PG8_WAIT_L(n) asm volatile("s_waitcnt lgkmcnt(" #n ")" ::: "memory")
; #define PG8_BAR __builtin_amdgcn_s_barrier()
; #define PG8_SCHED __builtin_amdgcn_sched_barrier(0)
; template <class Epi, class Sched, bool ALIGN_EPI = false, bool SP2 = false>
; __device__ __forceinline__ void gemm_phase(PG8_LAS unsigned char* lds, const Gemm g, const Sched& S, const Epi& E) {
;     ...
;             PG8_LDA(At, 1, 1); PG8_STAGEB(PG8_SB(1, 0), b3, voffB); PG8_STAGEB(PG8_SB(1, 1), b3 + hstep, voffB); PG8_STAGEA(PG8_SA(1, 0), a3, voffA);
;             PG8_WAIT_V(8); PG8_WAIT_L(0); PG8_BAR; PG8_MMA(1, 0, At, B0); PG8_MMA(1, 1, At, B1); PG8_BAR; PG8_SCHED;
;     ...
;         }
;         if constexpr (ALIGN_EPI) { if (wr == 0) PG8_BAR; }
	s_mov_b32 m0, s90
	v_lshl_add_u64 v[216:217], v[216:217], 0, s[44:45]
	ds_read_b128 v[184:187], v166 offset:49152
	ds_read_b128 v[188:191], v166 offset:50176
	ds_read_b128 v[192:195], v166 offset:51200
	ds_read_b128 v[196:199], v166 offset:52224
	ds_read_b128 v[200:203], v166 offset:53248
	ds_read_b128 v[204:207], v166 offset:54272
	ds_read_b128 v[208:211], v166 offset:55296
	ds_read_b128 v[212:215], v166 offset:56320
	global_load_lds_dwordx4 v[216:217], off
	v_lshl_add_u64 v[216:217], v[218:219], 0, s[44:45]
	s_mov_b32 m0, s88
	s_nop 0
	global_load_lds_dwordx4 v[216:217], off
	v_lshl_add_u64 v[216:217], s[68:69], 0, v[146:147]
	s_mov_b32 m0, s89
	s_nop 0
	global_load_lds_dwordx4 v[216:217], off
	v_lshl_add_u64 v[216:217], s[68:69], 0, v[148:149]
	s_mov_b32 m0, s91
	s_nop 0
	global_load_lds_dwordx4 v[216:217], off
	v_lshl_add_u64 v[216:217], v[220:221], 0, s[44:45]
	s_mov_b32 m0, s79
	s_nop 0
	global_load_lds_dwordx4 v[216:217], off
	v_lshl_add_u64 v[216:217], v[222:223], 0, s[44:45]
	s_mov_b32 m0, s80
	s_nop 0
	global_load_lds_dwordx4 v[216:217], off
	s_waitcnt vmcnt(8)
	s_waitcnt lgkmcnt(0)
	s_barrier
	s_setprio 1
	s_waitcnt lgkmcnt(0)
	.p2align 3
	v_mfma_f32_16x16x32_bf16 v[62:65], v[82:85], v[184:187], v[62:65]
	v_mfma_f32_16x16x32_bf16 v[58:61], v[94:97], v[184:187], v[58:61]
	v_mfma_f32_16x16x32_bf16 v[46:49], v[82:85], v[192:195], v[46:49]
	v_mfma_f32_16x16x32_bf16 v[42:45], v[94:97], v[192:195], v[42:45]
	v_mfma_f32_16x16x32_bf16 v[30:33], v[82:85], v[200:203], v[30:33]
	v_mfma_f32_16x16x32_bf16 v[26:29], v[94:97], v[200:203], v[26:29]
	v_mfma_f32_16x16x32_bf16 v[14:17], v[82:85], v[208:211], v[14:17]
	v_mfma_f32_16x16x32_bf16 v[10:13], v[94:97], v[208:211], v[10:13]
	v_mfma_f32_16x16x32_bf16 v[62:65], v[90:93], v[188:191], v[62:65]
	v_mfma_f32_16x16x32_bf16 v[58:61], v[158:161], v[188:191], v[58:61]
	v_mfma_f32_16x16x32_bf16 v[46:49], v[90:93], v[196:199], v[46:49]
	v_mfma_f32_16x16x32_bf16 v[42:45], v[158:161], v[196:199], v[42:45]
	v_mfma_f32_16x16x32_bf16 v[30:33], v[90:93], v[204:207], v[30:33]
	v_mfma_f32_16x16x32_bf16 v[26:29], v[158:161], v[204:207], v[26:29]
	v_mfma_f32_16x16x32_bf16 v[14:17], v[90:93], v[212:215], v[14:17]
	v_mfma_f32_16x16x32_bf16 v[10:13], v[158:161], v[212:215], v[10:13]
	s_setprio 0
	s_setprio 1
	.p2align 3
	v_mfma_f32_16x16x32_bf16 v[54:57], v[168:171], v[184:187], v[54:57]
	v_mfma_f32_16x16x32_bf16 v[50:53], v[176:179], v[184:187], v[50:53]
	v_mfma_f32_16x16x32_bf16 v[38:41], v[168:171], v[192:195], v[38:41]
	v_mfma_f32_16x16x32_bf16 v[34:37], v[176:179], v[192:195], v[34:37]
	v_mfma_f32_16x16x32_bf16 v[22:25], v[168:171], v[200:203], v[22:25]
	v_mfma_f32_16x16x32_bf16 v[18:21], v[176:179], v[200:203], v[18:21]
	v_mfma_f32_16x16x32_bf16 v[6:9], v[168:171], v[208:211], v[6:9]
	v_mfma_f32_16x16x32_bf16 v[2:5], v[176:179], v[208:211], v[2:5]
	v_mfma_f32_16x16x32_bf16 v[54:57], v[172:175], v[188:191], v[54:57]
	v_mfma_f32_16x16x32_bf16 v[50:53], v[180:183], v[188:191], v[50:53]
	v_mfma_f32_16x16x32_bf16 v[38:41], v[172:175], v[196:199], v[38:41]
	v_mfma_f32_16x16x32_bf16 v[34:37], v[180:183], v[196:199], v[34:37]
	v_mfma_f32_16x16x32_bf16 v[22:25], v[172:175], v[204:207], v[22:25]
	v_mfma_f32_16x16x32_bf16 v[18:21], v[180:183], v[204:207], v[18:21]
	v_mfma_f32_16x16x32_bf16 v[6:9], v[172:175], v[212:215], v[6:9]
	v_mfma_f32_16x16x32_bf16 v[2:5], v[180:183], v[212:215], v[2:5]
	s_setprio 0
	s_barrier
	s_mov_b64 s[64:65], s[66:67]
	s_mov_b32 s66, s87
	s_cbranch_scc0 .LBB0_920
	s_and_b64 vcc, exec, s[46:47]
	s_cbranch_vccz .LBB0_923
	s_barrier

; #define PG8_STAGEA(bufoff, gbase, voff) PG8_STAGE_X(bufoff, gbase, voff, PG8_AUX_A)
; #define PG8_STAGEB(bufoff, gbase, voff) PG8_STAGE_X(bufoff, gbase, voff, PG8_AUX_B)
; #define PG8_LDA(dst, b, h) do { _Pragma("unroll") for (int m = 0; m < 4; ++m) _Pragma("unroll") for (int k = 0; k < 2; ++k) dst[m][k] = *(const PG8_LAS bf16x8*)(lds + PG8_SA(b, h) + aoff + m * 2048 + k * 1024); } while (0)
; #define PG8_LDB(dst, b, h) do { _Pragma("unroll") for (int n = 0; n < 2; ++n) _Pragma("unroll") for (int k = 0; k < 2; ++k) dst[n][k] = *(const PG8_LAS bf16x8*)(lds + PG8_SB(b, h) + boff + n * 2048 + k * 1024); } while (0)
; #define PG8_MMA(ai, bj, At, Bt) do { __builtin_amdgcn_s_setprio(1); _Pragma("unroll") for (int m = 0; m < 4; ++m) _Pragma("unroll") for (int n = 0; n < 2; ++n) _Pragma("unroll") for (int k = 0; k < 2; ++k) \
;         acc[ai][bj][m][n] = __builtin_amdgcn_mfma_f32_16x16x32_bf16(Bt[n][k], At[m][k], acc[ai][bj][m][n], 0, 0, 0); __builtin_amdgcn_s_setprio(0); } while (0)
; #define PG8_WAIT_V(n) asm volatile("s_waitcnt vmcnt(" #n ")" ::: "memory")
; #define PG8_WAIT_L(n) asm volatile("s_waitcnt lgkmcnt(" #n ")" ::: "memory")
; template <class Epi, class Sched, bool ALIGN_EPI = false, bool SP2 = false>
; __device__ __forceinline__ void gemm_phase(PG8_LAS unsigned char* lds, const Gemm g, const Sched& S, const Epi& E) {
;     ...
;             const bool last = (t == nt - 2);
;             if constexpr (HasMid<Epi>::value) { if (t == ns) E.mid(acc, cur, wr, wc, fr, fq); }
;             const char* sA1 = (t + 1 >= ns) ? cA2 : cA; const char* sA2 = (t + 2 >= ns) ? cA2 : cA; const char* sB2 = (t + 2 >= ns) ? cB2 : cB;
;             const char* a1 = sA1 + (size_t)(t + 1) * kstep;
;             const char* a2 = last ? nA : sA2 + (size_t)(t + 2) * kstep; const char* b2 = last ? nB : sB2 + (size_t)(t + 2) * kstep;
;             const char* a3 = a2 + kstep; const char* b3 = b2 + kstep;
;             if (last && has_next) S.a_ready(nxt);
;             if constexpr (SP2) {
;             PG8_LDB(B0, 0, 0); PG8_LDB(B1, 0, 1); PG8_SCHED; PG8_LDA(At, 0, 0); PG8_STAGEA(PG8_SA(1, 1), a1 + hstep, voffA);
;             PG8_WAIT_V(8); PG8_WAIT_L(0); PG8_BAR; PG8_MMA(0, 0, At, B0); PG8_MMA(0, 1, At, B1); PG8_BAR; PG8_SCHED;
;             PG8_LDA(At, 0, 1); PG8_STAGEB(PG8_SB(0, 0), b2, voffB); PG8_STAGEB(PG8_SB(0, 1), b2 + hstep, voffB); PG8_STAGEA(PG8_SA(0, 0), a2, voffA);
.LBB0_1007:
	ds_read_b128 v[158:161], v152
	ds_read_b128 v[162:165], v152 offset:1024
	ds_read_b128 v[166:169], v152 offset:2048
	ds_read_b128 v[170:173], v152 offset:3072
	ds_read_b128 v[174:177], v153
	ds_read_b128 v[178:181], v153 offset:1024
	ds_read_b128 v[182:185], v153 offset:2048
	ds_read_b128 v[186:189], v153 offset:3072
	ds_read_b128 v[190:193], v154
	ds_read_b128 v[194:197], v154 offset:1024
	ds_read_b128 v[198:201], v154 offset:2048
	ds_read_b128 v[202:205], v154 offset:3072
	ds_read_b128 v[206:209], v154 offset:4096
	ds_read_b128 v[210:213], v154 offset:5120
	ds_read_b128 v[214:217], v154 offset:6144
	ds_read_b128 v[218:221], v154 offset:7168
	s_add_i32 s76, s58, 2
	s_cmp_gt_u32 s76, 29
	s_cselect_b64 s[60:61], -1, 0
	s_and_b64 vcc, s[60:61], exec
	s_cselect_b32 s29, s34, s54
	s_cselect_b32 s24, s27, s53
	s_cselect_b32 s25, s26, s52
	s_cselect_b32 s28, s35, s55
	s_add_u32 s29, s29, s56
	s_addc_u32 s28, s28, s57
	s_add_u32 s29, s29, 0xfff80080
	s_addc_u32 s28, s28, -1
	s_add_u32 s25, s25, s56
	s_addc_u32 s24, s24, s57
	s_add_u32 s25, s25, 0xfff80080
	s_addc_u32 s24, s24, -1
	s_cmp_eq_u32 s58, 28
	s_cselect_b32 s58, s75, s25
	s_cselect_b32 s61, s47, s28
	s_cselect_b32 s60, s74, s29
	s_cselect_b32 s59, s45, s24
	v_lshl_add_u64 v[222:223], v[146:147], 0, s[56:57]
	s_add_i32 m0, s33, 0xc000
	global_load_lds_dwordx4 v[222:223], off
	v_lshl_add_u64 v[222:223], v[148:149], 0, s[56:57]
	s_add_i32 m0, s33, 0xe000
	s_nop 0
	global_load_lds_dwordx4 v[222:223], off
	s_waitcnt vmcnt(8)
	s_waitcnt lgkmcnt(0)
	s_barrier
	s_setprio 1
	s_waitcnt lgkmcnt(0)
	.p2align 3
	v_mfma_f32_16x16x32_bf16 v[118:121], v[158:161], v[190:193], v[118:121]
	v_mfma_f32_16x16x32_bf16 v[114:117], v[166:169], v[190:193], v[114:117]
	v_mfma_f32_16x16x32_bf16 v[102:105], v[158:161], v[198:201], v[102:105]
	v_mfma_f32_16x16x32_bf16 v[98:101], v[166:169], v[198:201], v[98:101]
	v_mfma_f32_16x16x32_bf16 v[86:89], v[158:161], v[206:209], v[86:89]
	v_mfma_f32_16x16x32_bf16 v[82:85], v[166:169], v[206:209], v[82:85]
	v_mfma_f32_16x16x32_bf16 v[70:73], v[158:161], v[214:217], v[70:73]
	v_mfma_f32_16x16x32_bf16 v[66:69], v[166:169], v[214:217], v[66:69]
	v_mfma_f32_16x16x32_bf16 v[118:121], v[162:165], v[194:197], v[118:121]
	v_mfma_f32_16x16x32_bf16 v[114:117], v[170:173], v[194:197], v[114:117]
	v_mfma_f32_16x16x32_bf16 v[102:105], v[162:165], v[202:205], v[102:105]
	v_mfma_f32_16x16x32_bf16 v[98:101], v[170:173], v[202:205], v[98:101]
	v_mfma_f32_16x16x32_bf16 v[86:89], v[162:165], v[210:213], v[86:89]
	v_mfma_f32_16x16x32_bf16 v[82:85], v[170:173], v[210:213], v[82:85]
	v_mfma_f32_16x16x32_bf16 v[70:73], v[162:165], v[218:221], v[70:73]
	v_mfma_f32_16x16x32_bf16 v[66:69], v[170:173], v[218:221], v[66:69]
	s_setprio 0
	s_setprio 1
	.p2align 3
	v_mfma_f32_16x16x32_bf16 v[126:129], v[174:177], v[190:193], v[126:129]
	v_mfma_f32_16x16x32_bf16 v[122:125], v[182:185], v[190:193], v[122:125]
	v_mfma_f32_16x16x32_bf16 v[110:113], v[174:177], v[198:201], v[110:113]
	v_mfma_f32_16x16x32_bf16 v[106:109], v[182:185], v[198:201], v[106:109]
	v_mfma_f32_16x16x32_bf16 v[94:97], v[174:177], v[206:209], v[94:97]
	v_mfma_f32_16x16x32_bf16 v[90:93], v[182:185], v[206:209], v[90:93]
	v_mfma_f32_16x16x32_bf16 v[78:81], v[174:177], v[214:217], v[78:81]
	v_mfma_f32_16x16x32_bf16 v[74:77], v[182:185], v[214:217], v[74:77]
	v_mfma_f32_16x16x32_bf16 v[126:129], v[178:181], v[194:197], v[126:129]
	v_mfma_f32_16x16x32_bf16 v[122:125], v[186:189], v[194:197], v[122:125]
	v_mfma_f32_16x16x32_bf16 v[110:113], v[178:181], v[202:205], v[110:113]
	v_mfma_f32_16x16x32_bf16 v[106:109], v[186:189], v[202:205], v[106:109]
	v_mfma_f32_16x16x32_bf16 v[94:97], v[178:181], v[210:213], v[94:97]
	v_mfma_f32_16x16x32_bf16 v[90:93], v[186:189], v[210:213], v[90:93]
	v_mfma_f32_16x16x32_bf16 v[78:81], v[178:181], v[218:221], v[78:81]
	v_mfma_f32_16x16x32_bf16 v[74:77], v[186:189], v[218:221], v[74:77]
	s_setprio 0
	s_barrier
	s_add_i32 s24, s70, s11
	v_lshl_add_u64 v[222:223], s[58:59], 0, v[134:135]
	s_mov_b32 m0, s24
	ds_read_b128 v[190:193], v154 offset:16384
	ds_read_b128 v[194:197], v154 offset:17408
	ds_read_b128 v[198:201], v154 offset:18432
	ds_read_b128 v[202:205], v154 offset:19456
	ds_read_b128 v[206:209], v154 offset:20480
	ds_read_b128 v[210:213], v154 offset:21504
	ds_read_b128 v[214:217], v154 offset:22528
	ds_read_b128 v[218:221], v154 offset:23552
	global_load_lds_dwordx4 v[222:223], off
	s_add_i32 m0, s24, 0x2000
	s_add_u32 s78, s58, 0x80000
	v_lshl_add_u64 v[224:225], s[58:59], 0, v[130:131]
	s_addc_u32 s79, s59, 0
	s_add_i32 s24, s71, s11
	global_load_lds_dwordx4 v[224:225], off
	v_lshl_add_u64 v[226:227], s[78:79], 0, v[134:135]
	s_mov_b32 m0, s24
	v_lshl_add_u64 v[228:229], s[60:61], 0, v[132:133]
	global_load_lds_dwordx4 v[226:227], off
	v_lshl_add_u64 v[226:227], s[78:79], 0, v[130:131]
	s_add_i32 m0, s24, 0x2000
	s_nop 0
	global_load_lds_dwordx4 v[226:227], off
	v_lshl_add_u64 v[226:227], s[60:61], 0, v[136:137]
	s_mov_b32 m0, s33
	s_nop 0
	global_load_lds_dwordx4 v[226:227], off
	s_mov_b32 m0, s62
	s_nop 0
	global_load_lds_dwordx4 v[228:229], off
	s_waitcnt vmcnt(8)
	s_waitcnt lgkmcnt(0)
	s_barrier
; #define PG8_STAGEA(bufoff, gbase, voff) PG8_STAGE_X(bufoff, gbase, voff, PG8_AUX_A)
; #define PG8_LDA(dst, b, h) do { _Pragma("unroll") for (int m = 0; m < 4; ++m) _Pragma("unroll") for (int k = 0; k < 2; ++k) dst[m][k] = *(const PG8_LAS bf16x8*)(lds + PG8_SA(b, h) + aoff + m * 2048 + k * 1024); } while (0)
; #define PG8_LDB(dst, b, h) do { _Pragma("unroll") for (int n = 0; n < 2; ++n) _Pragma("unroll") for (int k = 0; k < 2; ++k) dst[n][k] = *(const PG8_LAS bf16x8*)(lds + PG8_SB(b, h) + boff + n * 2048 + k * 1024); } while (0)
; #define PG8_MMA(ai, bj, At, Bt) do { __builtin_amdgcn_s_setprio(1); _Pragma("unroll") for (int m = 0; m < 4; ++m) _Pragma("unroll") for (int n = 0; n < 2; ++n) _Pragma("unroll") for (int k = 0; k < 2; ++k) \
;         acc[ai][bj][m][n] = __builtin_amdgcn_mfma_f32_16x16x32_bf16(Bt[n][k], At[m][k], acc[ai][bj][m][n], 0, 0, 0); __builtin_amdgcn_s_setprio(0); } while (0)
; #define PG8_WAIT_V(n) asm volatile("s_waitcnt vmcnt(" #n ")" ::: "memory")
; #define PG8_WAIT_L(n) asm volatile("s_waitcnt lgkmcnt(" #n ")" ::: "memory")
; #define PG8_BAR __builtin_amdgcn_s_barrier()
; #define PG8_SCHED __builtin_amdgcn_sched_barrier(0)
; template <class Epi, class Sched, bool ALIGN_EPI = false, bool SP2 = false>
; __device__ __forceinline__ void gemm_phase(PG8_LAS unsigned char* lds, const Gemm g, const Sched& S, const Epi& E) {
;     ...
;             PG8_WAIT_V(8); PG8_WAIT_L(0); PG8_BAR; PG8_MMA(1, 0, At, B0); PG8_MMA(1, 1, At, B1); PG8_BAR; PG8_SCHED;
;             PG8_LDB(B0, 1, 0); PG8_LDB(B1, 1, 1); PG8_SCHED; PG8_LDA(At, 1, 0); PG8_STAGEA(PG8_SA(0, 1), a2 + hstep, voffA);
;             PG8_WAIT_V(8); PG8_WAIT_L(0); PG8_BAR; PG8_MMA(0, 0, At, B0); PG8_MMA(0, 1, At, B1); PG8_BAR; PG8_SCHED;
	s_setprio 1
	s_waitcnt lgkmcnt(0)
	.p2align 3
	v_mfma_f32_16x16x32_bf16 v[54:57], v[158:161], v[190:193], v[54:57]
	v_mfma_f32_16x16x32_bf16 v[50:53], v[166:169], v[190:193], v[50:53]
	v_mfma_f32_16x16x32_bf16 v[38:41], v[158:161], v[198:201], v[38:41]
	v_mfma_f32_16x16x32_bf16 v[34:37], v[166:169], v[198:201], v[34:37]
	v_mfma_f32_16x16x32_bf16 v[22:25], v[158:161], v[206:209], v[22:25]
	v_mfma_f32_16x16x32_bf16 v[18:21], v[166:169], v[206:209], v[18:21]
	v_mfma_f32_16x16x32_bf16 v[6:9], v[158:161], v[214:217], v[6:9]
	v_mfma_f32_16x16x32_bf16 v[2:5], v[166:169], v[214:217], v[2:5]
	v_mfma_f32_16x16x32_bf16 v[54:57], v[162:165], v[194:197], v[54:57]
	v_mfma_f32_16x16x32_bf16 v[50:53], v[170:173], v[194:197], v[50:53]
	v_mfma_f32_16x16x32_bf16 v[38:41], v[162:165], v[202:205], v[38:41]
	v_mfma_f32_16x16x32_bf16 v[34:37], v[170:173], v[202:205], v[34:37]
	v_mfma_f32_16x16x32_bf16 v[22:25], v[162:165], v[210:213], v[22:25]
	v_mfma_f32_16x16x32_bf16 v[18:21], v[170:173], v[210:213], v[18:21]
	v_mfma_f32_16x16x32_bf16 v[6:9], v[162:165], v[218:221], v[6:9]
	v_mfma_f32_16x16x32_bf16 v[2:5], v[170:173], v[218:221], v[2:5]
	s_setprio 0
	s_setprio 1
	.p2align 3
	v_mfma_f32_16x16x32_bf16 v[62:65], v[174:177], v[190:193], v[62:65]
	v_mfma_f32_16x16x32_bf16 v[58:61], v[182:185], v[190:193], v[58:61]
	v_mfma_f32_16x16x32_bf16 v[46:49], v[174:177], v[198:201], v[46:49]
	v_mfma_f32_16x16x32_bf16 v[42:45], v[182:185], v[198:201], v[42:45]
	v_mfma_f32_16x16x32_bf16 v[30:33], v[174:177], v[206:209], v[30:33]
	v_mfma_f32_16x16x32_bf16 v[26:29], v[182:185], v[206:209], v[26:29]
	v_mfma_f32_16x16x32_bf16 v[14:17], v[174:177], v[214:217], v[14:17]
	v_mfma_f32_16x16x32_bf16 v[10:13], v[182:185], v[214:217], v[10:13]
	v_mfma_f32_16x16x32_bf16 v[62:65], v[178:181], v[194:197], v[62:65]
	v_mfma_f32_16x16x32_bf16 v[58:61], v[186:189], v[194:197], v[58:61]
	v_mfma_f32_16x16x32_bf16 v[46:49], v[178:181], v[202:205], v[46:49]
	v_mfma_f32_16x16x32_bf16 v[42:45], v[186:189], v[202:205], v[42:45]
	v_mfma_f32_16x16x32_bf16 v[30:33], v[178:181], v[210:213], v[30:33]
	v_mfma_f32_16x16x32_bf16 v[26:29], v[186:189], v[210:213], v[26:29]
	v_mfma_f32_16x16x32_bf16 v[14:17], v[178:181], v[218:221], v[14:17]
	v_mfma_f32_16x16x32_bf16 v[10:13], v[186:189], v[218:221], v[10:13]
	s_setprio 0
	s_barrier
	s_add_i32 s24, 0, 0x18000
	v_add_u32_e32 v157, s24, v150
	s_add_i32 s25, 0, 0x1c000
	ds_read_b128 v[158:161], v157
	ds_read_b128 v[162:165], v157 offset:1024
	ds_read_b128 v[166:169], v157 offset:2048
	ds_read_b128 v[170:173], v157 offset:3072
	v_add_u32_e32 v157, s25, v150
	ds_read_b128 v[174:177], v157
	ds_read_b128 v[178:181], v157 offset:1024
	ds_read_b128 v[182:185], v157 offset:2048
	ds_read_b128 v[186:189], v157 offset:3072
	s_add_u32 s60, s60, 0x80000
	s_addc_u32 s61, s61, 0
	s_mov_b32 m0, s63
	v_lshl_add_u64 v[230:231], s[60:61], 0, v[136:137]
	ds_read_b128 v[190:193], v154 offset:32768
	ds_read_b128 v[194:197], v154 offset:33792
	ds_read_b128 v[198:201], v154 offset:34816
	ds_read_b128 v[202:205], v154 offset:35840
	ds_read_b128 v[206:209], v154 offset:36864
	ds_read_b128 v[210:213], v154 offset:37888
	ds_read_b128 v[214:217], v154 offset:38912
	ds_read_b128 v[218:221], v154 offset:39936
	global_load_lds_dwordx4 v[230:231], off
	v_lshl_add_u64 v[230:231], s[60:61], 0, v[132:133]
	s_mov_b32 m0, s64
	s_nop 0
	global_load_lds_dwordx4 v[230:231], off
	s_waitcnt vmcnt(8)
	s_waitcnt lgkmcnt(0)
	s_barrier
	s_setprio 1
	s_waitcnt lgkmcnt(0)
	.p2align 3
	v_mfma_f32_16x16x32_bf16 v[118:121], v[158:161], v[190:193], v[118:121]
	v_mfma_f32_16x16x32_bf16 v[114:117], v[166:169], v[190:193], v[114:117]
	v_mfma_f32_16x16x32_bf16 v[102:105], v[158:161], v[198:201], v[102:105]
	v_mfma_f32_16x16x32_bf16 v[98:101], v[166:169], v[198:201], v[98:101]
	v_mfma_f32_16x16x32_bf16 v[86:89], v[158:161], v[206:209], v[86:89]
	v_mfma_f32_16x16x32_bf16 v[82:85], v[166:169], v[206:209], v[82:85]
	v_mfma_f32_16x16x32_bf16 v[70:73], v[158:161], v[214:217], v[70:73]
	v_mfma_f32_16x16x32_bf16 v[66:69], v[166:169], v[214:217], v[66:69]
	v_mfma_f32_16x16x32_bf16 v[118:121], v[162:165], v[194:197], v[118:121]
	v_mfma_f32_16x16x32_bf16 v[114:117], v[170:173], v[194:197], v[114:117]
	v_mfma_f32_16x16x32_bf16 v[102:105], v[162:165], v[202:205], v[102:105]
	v_mfma_f32_16x16x32_bf16 v[98:101], v[170:173], v[202:205], v[98:101]
	v_mfma_f32_16x16x32_bf16 v[86:89], v[162:165], v[210:213], v[86:89]
	v_mfma_f32_16x16x32_bf16 v[82:85], v[170:173], v[210:213], v[82:85]
	v_mfma_f32_16x16x32_bf16 v[70:73], v[162:165], v[218:221], v[70:73]
	v_mfma_f32_16x16x32_bf16 v[66:69], v[170:173], v[218:221], v[66:69]
	s_setprio 0
	s_setprio 1
	.p2align 3
	v_mfma_f32_16x16x32_bf16 v[126:129], v[174:177], v[190:193], v[126:129]
	v_mfma_f32_16x16x32_bf16 v[122:125], v[182:185], v[190:193], v[122:125]
	v_mfma_f32_16x16x32_bf16 v[110:113], v[174:177], v[198:201], v[110:113]
	v_mfma_f32_16x16x32_bf16 v[106:109], v[182:185], v[198:201], v[106:109]
	v_mfma_f32_16x16x32_bf16 v[94:97], v[174:177], v[206:209], v[94:97]
	v_mfma_f32_16x16x32_bf16 v[90:93], v[182:185], v[206:209], v[90:93]
	v_mfma_f32_16x16x32_bf16 v[78:81], v[174:177], v[214:217], v[78:81]
	v_mfma_f32_16x16x32_bf16 v[74:77], v[182:185], v[214:217], v[74:77]
	v_mfma_f32_16x16x32_bf16 v[126:129], v[178:181], v[194:197], v[126:129]
	v_mfma_f32_16x16x32_bf16 v[122:125], v[186:189], v[194:197], v[122:125]
	v_mfma_f32_16x16x32_bf16 v[110:113], v[178:181], v[202:205], v[110:113]
	v_mfma_f32_16x16x32_bf16 v[106:109], v[186:189], v[202:205], v[106:109]
	v_mfma_f32_16x16x32_bf16 v[94:97], v[178:181], v[210:213], v[94:97]
	v_mfma_f32_16x16x32_bf16 v[90:93], v[186:189], v[210:213], v[90:93]
	v_mfma_f32_16x16x32_bf16 v[78:81], v[178:181], v[218:221], v[78:81]
	v_mfma_f32_16x16x32_bf16 v[74:77], v[186:189], v[218:221], v[74:77]
	s_setprio 0
	s_barrier
; #define PG8_STAGEA(bufoff, gbase, voff) PG8_STAGE_X(bufoff, gbase, voff, PG8_AUX_A)
; #define PG8_STAGEB(bufoff, gbase, voff) PG8_STAGE_X(bufoff, gbase, voff, PG8_AUX_B)
; #define PG8_LDA(dst, b, h) do { _Pragma("unroll") for (int m = 0; m < 4; ++m) _Pragma("unroll") for (int k = 0; k < 2; ++k) dst[m][k] = *(const PG8_LAS bf16x8*)(lds + PG8_SA(b, h) + aoff + m * 2048 + k * 1024); } while (0)
; #define PG8_MMA(ai, bj, At, Bt) do { __builtin_amdgcn_s_setprio(1); _Pragma("unroll") for (int m = 0; m < 4; ++m) _Pragma("unroll") for (int n = 0; n < 2; ++n) _Pragma("unroll") for (int k = 0; k < 2; ++k) \
;         acc[ai][bj][m][n] = __builtin_amdgcn_mfma_f32_16x16x32_bf16(Bt[n][k], At[m][k], acc[ai][bj][m][n], 0, 0, 0); __builtin_amdgcn_s_setprio(0); } while (0)
; #define PG8_WAIT_V(n) asm volatile("s_waitcnt vmcnt(" #n ")" ::: "memory")
; #define PG8_WAIT_L(n) asm volatile("s_waitcnt lgkmcnt(" #n ")" ::: "memory")
; #define PG8_BAR __builtin_amdgcn_s_barrier()
; #define PG8_SCHED __builtin_amdgcn_sched_barrier(0)
; template <class Epi, class Sched, bool ALIGN_EPI = false, bool SP2 = false>
; __device__ __forceinline__ void gemm_phase(PG8_LAS unsigned char* lds, const Gemm g, const Sched& S, const Epi& E) {
;     ...
;             PG8_LDA(At, 1, 1); PG8_STAGEB(PG8_SB(1, 0), b3, voffB); PG8_STAGEB(PG8_SB(1, 1), b3 + hstep, voffB); PG8_STAGEA(PG8_SA(1, 0), a3, voffA);
;             PG8_WAIT_V(8); PG8_WAIT_L(0); PG8_BAR; PG8_MMA(1, 0, At, B0); PG8_MMA(1, 1, At, B1); PG8_BAR; PG8_SCHED;
	s_add_i32 s24, s24, s11
	v_lshl_add_u64 v[222:223], v[222:223], 0, s[40:41]
	s_mov_b32 m0, s24
	ds_read_b128 v[190:193], v154 offset:49152
	ds_read_b128 v[194:197], v154 offset:50176
	ds_read_b128 v[198:201], v154 offset:51200
	ds_read_b128 v[202:205], v154 offset:52224
	ds_read_b128 v[206:209], v154 offset:53248
	ds_read_b128 v[210:213], v154 offset:54272
	ds_read_b128 v[214:217], v154 offset:55296
	ds_read_b128 v[218:221], v154 offset:56320
	global_load_lds_dwordx4 v[222:223], off
	s_add_i32 m0, s24, 0x2000
	s_add_u32 s58, s58, 0x80080
	v_lshl_add_u64 v[222:223], v[224:225], 0, s[40:41]
	s_addc_u32 s59, s59, 0
	s_add_i32 s24, s25, s11
	global_load_lds_dwordx4 v[222:223], off
	v_lshl_add_u64 v[222:223], s[58:59], 0, v[134:135]
	s_mov_b32 m0, s24
	s_nop 0
	global_load_lds_dwordx4 v[222:223], off
	v_lshl_add_u64 v[222:223], s[58:59], 0, v[130:131]
	s_add_i32 m0, s24, 0x2000
	s_nop 0
	global_load_lds_dwordx4 v[222:223], off
	v_lshl_add_u64 v[222:223], v[226:227], 0, s[40:41]
	s_mov_b32 m0, s67
	s_nop 0
	global_load_lds_dwordx4 v[222:223], off
	v_lshl_add_u64 v[222:223], v[228:229], 0, s[40:41]
	s_mov_b32 m0, s68
	s_nop 0
	global_load_lds_dwordx4 v[222:223], off
	s_waitcnt vmcnt(8)
	s_waitcnt lgkmcnt(0)
	s_barrier
	s_setprio 1
	s_waitcnt lgkmcnt(0)
	.p2align 3
	v_mfma_f32_16x16x32_bf16 v[54:57], v[158:161], v[190:193], v[54:57]
	v_mfma_f32_16x16x32_bf16 v[50:53], v[166:169], v[190:193], v[50:53]
	v_mfma_f32_16x16x32_bf16 v[38:41], v[158:161], v[198:201], v[38:41]
	v_mfma_f32_16x16x32_bf16 v[34:37], v[166:169], v[198:201], v[34:37]
	v_mfma_f32_16x16x32_bf16 v[22:25], v[158:161], v[206:209], v[22:25]
	v_mfma_f32_16x16x32_bf16 v[18:21], v[166:169], v[206:209], v[18:21]
	v_mfma_f32_16x16x32_bf16 v[6:9], v[158:161], v[214:217], v[6:9]
	v_mfma_f32_16x16x32_bf16 v[2:5], v[166:169], v[214:217], v[2:5]
	v_mfma_f32_16x16x32_bf16 v[54:57], v[162:165], v[194:197], v[54:57]
	v_mfma_f32_16x16x32_bf16 v[50:53], v[170:173], v[194:197], v[50:53]
	v_mfma_f32_16x16x32_bf16 v[38:41], v[162:165], v[202:205], v[38:41]
	v_mfma_f32_16x16x32_bf16 v[34:37], v[170:173], v[202:205], v[34:37]
	v_mfma_f32_16x16x32_bf16 v[22:25], v[162:165], v[210:213], v[22:25]
	v_mfma_f32_16x16x32_bf16 v[18:21], v[170:173], v[210:213], v[18:21]
	v_mfma_f32_16x16x32_bf16 v[6:9], v[162:165], v[218:221], v[6:9]
	v_mfma_f32_16x16x32_bf16 v[2:5], v[170:173], v[218:221], v[2:5]
	s_setprio 0
	s_setprio 1
	.p2align 3
	v_mfma_f32_16x16x32_bf16 v[62:65], v[174:177], v[190:193], v[62:65]
	v_mfma_f32_16x16x32_bf16 v[58:61], v[182:185], v[190:193], v[58:61]
	v_mfma_f32_16x16x32_bf16 v[46:49], v[174:177], v[198:201], v[46:49]
	v_mfma_f32_16x16x32_bf16 v[42:45], v[182:185], v[198:201], v[42:45]
	v_mfma_f32_16x16x32_bf16 v[30:33], v[174:177], v[206:209], v[30:33]
	v_mfma_f32_16x16x32_bf16 v[26:29], v[182:185], v[206:209], v[26:29]
	v_mfma_f32_16x16x32_bf16 v[14:17], v[174:177], v[214:217], v[14:17]
	v_mfma_f32_16x16x32_bf16 v[10:13], v[182:185], v[214:217], v[10:13]
	v_mfma_f32_16x16x32_bf16 v[62:65], v[178:181], v[194:197], v[62:65]
	v_mfma_f32_16x16x32_bf16 v[58:61], v[186:189], v[194:197], v[58:61]
	v_mfma_f32_16x16x32_bf16 v[46:49], v[178:181], v[202:205], v[46:49]
	v_mfma_f32_16x16x32_bf16 v[42:45], v[186:189], v[202:205], v[42:45]
	v_mfma_f32_16x16x32_bf16 v[30:33], v[178:181], v[210:213], v[30:33]
	v_mfma_f32_16x16x32_bf16 v[26:29], v[186:189], v[210:213], v[26:29]
	v_mfma_f32_16x16x32_bf16 v[14:17], v[178:181], v[218:221], v[14:17]
	v_mfma_f32_16x16x32_bf16 v[10:13], v[186:189], v[218:221], v[10:13]
	s_setprio 0
	s_barrier
	s_add_u32 s56, s56, 0x100
	s_addc_u32 s57, s57, 0
	s_mov_b32 s58, s76
	s_cbranch_vccz .LBB0_1007
	s_and_b64 vcc, exec, s[42:43]
	s_cbranch_vccz .LBB0_1010
	s_barrier

; #define PG8_STAGEA(bufoff, gbase, voff) PG8_STAGE_X(bufoff, gbase, voff, PG8_AUX_A)
; #define PG8_STAGEB(bufoff, gbase, voff) PG8_STAGE_X(bufoff, gbase, voff, PG8_AUX_B)
; #define PG8_LDA(dst, b, h) do { _Pragma("unroll") for (int m = 0; m < 4; ++m) _Pragma("unroll") for (int k = 0; k < 2; ++k) dst[m][k] = *(const PG8_LAS bf16x8*)(lds + PG8_SA(b, h) + aoff + m * 2048 + k * 1024); } while (0)
; #define PG8_LDB(dst, b, h) do { _Pragma("unroll") for (int n = 0; n < 2; ++n) _Pragma("unroll") for (int k = 0; k < 2; ++k) dst[n][k] = *(const PG8_LAS bf16x8*)(lds + PG8_SB(b, h) + boff + n * 2048 + k * 1024); } while (0)
; #define PG8_MMA(ai, bj, At, Bt) do { __builtin_amdgcn_s_setprio(1); _Pragma("unroll") for (int m = 0; m < 4; ++m) _Pragma("unroll") for (int n = 0; n < 2; ++n) _Pragma("unroll") for (int k = 0; k < 2; ++k) \
;         acc[ai][bj][m][n] = __builtin_amdgcn_mfma_f32_16x16x32_bf16(Bt[n][k], At[m][k], acc[ai][bj][m][n], 0, 0, 0); __builtin_amdgcn_s_setprio(0); } while (0)
; #define PG8_WAIT_V(n) asm volatile("s_waitcnt vmcnt(" #n ")" ::: "memory")
; #define PG8_WAIT_L(n) asm volatile("s_waitcnt lgkmcnt(" #n ")" ::: "memory")
; template <class Epi, class Sched, bool ALIGN_EPI = false, bool SP2 = false>
; __device__ __forceinline__ void gemm_phase(PG8_LAS unsigned char* lds, const Gemm g, const Sched& S, const Epi& E) {
;     ...
;             const bool last = (t == nt - 2);
;             if constexpr (HasMid<Epi>::value) { if (t == ns) E.mid(acc, cur, wr, wc, fr, fq); }
;             const char* sA1 = (t + 1 >= ns) ? cA2 : cA; const char* sA2 = (t + 2 >= ns) ? cA2 : cA; const char* sB2 = (t + 2 >= ns) ? cB2 : cB;
;             const char* a1 = sA1 + (size_t)(t + 1) * kstep;
;             const char* a2 = last ? nA : sA2 + (size_t)(t + 2) * kstep; const char* b2 = last ? nB : sB2 + (size_t)(t + 2) * kstep;
;             const char* a3 = a2 + kstep; const char* b3 = b2 + kstep;
;             if (last && has_next) S.a_ready(nxt);
;             if constexpr (SP2) {
;             PG8_LDB(B0, 0, 0); PG8_LDB(B1, 0, 1); PG8_SCHED; PG8_LDA(At, 0, 0); PG8_STAGEA(PG8_SA(1, 1), a1 + hstep, voffA);
;             PG8_WAIT_V(8); PG8_WAIT_L(0); PG8_BAR; PG8_MMA(0, 0, At, B0); PG8_MMA(0, 1, At, B1); PG8_BAR; PG8_SCHED;
;             PG8_LDA(At, 0, 1); PG8_STAGEB(PG8_SB(0, 0), b2, voffB); PG8_STAGEB(PG8_SB(0, 1), b2 + hstep, voffB); PG8_STAGEA(PG8_SA(0, 0), a2, voffA);
.LBB0_1090:
	ds_read_b128 v[154:157], v150
	ds_read_b128 v[158:161], v150 offset:1024
	ds_read_b128 v[162:165], v150 offset:2048
	ds_read_b128 v[166:169], v150 offset:3072
	ds_read_b128 v[170:173], v151
	ds_read_b128 v[174:177], v151 offset:1024
	ds_read_b128 v[178:181], v151 offset:2048
	ds_read_b128 v[182:185], v151 offset:3072
	ds_read_b128 v[186:189], v152
	ds_read_b128 v[190:193], v152 offset:1024
	ds_read_b128 v[194:197], v152 offset:2048
	ds_read_b128 v[198:201], v152 offset:3072
	ds_read_b128 v[202:205], v152 offset:4096
	ds_read_b128 v[206:209], v152 offset:5120
	ds_read_b128 v[210:213], v152 offset:6144
	ds_read_b128 v[214:217], v152 offset:7168
	s_add_i32 s75, s54, 2
	s_cmpk_gt_u32 s75, 0x55
	s_cselect_b64 s[56:57], -1, 0
	s_and_b64 vcc, s[56:57], exec
	s_cselect_b32 s56, s24, s50
	s_cselect_b32 s28, s9, s49
	s_cselect_b32 s29, s8, s48
	s_cselect_b32 s55, s25, s51
	s_add_u32 s56, s56, s52
	s_addc_u32 s55, s55, s53
	s_add_u32 s56, s56, 0xffea0080
	s_addc_u32 s55, s55, -1
	s_add_u32 s29, s29, s52
	s_addc_u32 s28, s28, s53
	s_add_u32 s29, s29, 0xffea0080
	s_addc_u32 s28, s28, -1
	s_cmpk_eq_i32 s54, 0x54
	s_cselect_b32 s54, s46, s29
	s_cselect_b32 s57, s5, s55
	s_cselect_b32 s56, s4, s56
	s_cselect_b32 s55, s47, s28
	v_lshl_add_u64 v[146:147], v[142:143], 0, s[52:53]
	s_add_i32 m0, s23, 0xc000
	global_load_lds_dwordx4 v[146:147], off
	v_lshl_add_u64 v[146:147], v[144:145], 0, s[52:53]
	s_add_i32 m0, s23, 0xe000
	s_nop 0
	global_load_lds_dwordx4 v[146:147], off
	s_waitcnt vmcnt(8)
	s_waitcnt lgkmcnt(0)
	s_barrier
	s_setprio 1
	s_waitcnt lgkmcnt(0)
	.p2align 3
	v_mfma_f32_16x16x32_bf16 v[126:129], v[154:157], v[186:189], v[126:129]
	v_mfma_f32_16x16x32_bf16 v[122:125], v[162:165], v[186:189], v[122:125]
	v_mfma_f32_16x16x32_bf16 v[114:117], v[154:157], v[194:197], v[114:117]
	v_mfma_f32_16x16x32_bf16 v[106:109], v[162:165], v[194:197], v[106:109]
	v_mfma_f32_16x16x32_bf16 v[94:97], v[154:157], v[202:205], v[94:97]
	v_mfma_f32_16x16x32_bf16 v[90:93], v[162:165], v[202:205], v[90:93]
	v_mfma_f32_16x16x32_bf16 v[78:81], v[154:157], v[210:213], v[78:81]
	v_mfma_f32_16x16x32_bf16 v[74:77], v[162:165], v[210:213], v[74:77]
	v_mfma_f32_16x16x32_bf16 v[126:129], v[158:161], v[190:193], v[126:129]
	v_mfma_f32_16x16x32_bf16 v[122:125], v[166:169], v[190:193], v[122:125]
	v_mfma_f32_16x16x32_bf16 v[114:117], v[158:161], v[198:201], v[114:117]
	v_mfma_f32_16x16x32_bf16 v[106:109], v[166:169], v[198:201], v[106:109]
	v_mfma_f32_16x16x32_bf16 v[94:97], v[158:161], v[206:209], v[94:97]
	v_mfma_f32_16x16x32_bf16 v[90:93], v[166:169], v[206:209], v[90:93]
	v_mfma_f32_16x16x32_bf16 v[78:81], v[158:161], v[214:217], v[78:81]
	v_mfma_f32_16x16x32_bf16 v[74:77], v[166:169], v[214:217], v[74:77]
	s_setprio 0
	s_setprio 1
	.p2align 3
	v_mfma_f32_16x16x32_bf16 v[118:121], v[170:173], v[186:189], v[118:121]
	v_mfma_f32_16x16x32_bf16 v[110:113], v[178:181], v[186:189], v[110:113]
	v_mfma_f32_16x16x32_bf16 v[102:105], v[170:173], v[194:197], v[102:105]
	v_mfma_f32_16x16x32_bf16 v[98:101], v[178:181], v[194:197], v[98:101]
	v_mfma_f32_16x16x32_bf16 v[86:89], v[170:173], v[202:205], v[86:89]
	v_mfma_f32_16x16x32_bf16 v[82:85], v[178:181], v[202:205], v[82:85]
	v_mfma_f32_16x16x32_bf16 v[70:73], v[170:173], v[210:213], v[70:73]
	v_mfma_f32_16x16x32_bf16 v[66:69], v[178:181], v[210:213], v[66:69]
	v_mfma_f32_16x16x32_bf16 v[118:121], v[174:177], v[190:193], v[118:121]
	v_mfma_f32_16x16x32_bf16 v[110:113], v[182:185], v[190:193], v[110:113]
	v_mfma_f32_16x16x32_bf16 v[102:105], v[174:177], v[198:201], v[102:105]
	v_mfma_f32_16x16x32_bf16 v[98:101], v[182:185], v[198:201], v[98:101]
	v_mfma_f32_16x16x32_bf16 v[86:89], v[174:177], v[206:209], v[86:89]
	v_mfma_f32_16x16x32_bf16 v[82:85], v[182:185], v[206:209], v[82:85]
	v_mfma_f32_16x16x32_bf16 v[70:73], v[174:177], v[214:217], v[70:73]
	v_mfma_f32_16x16x32_bf16 v[66:69], v[182:185], v[214:217], v[66:69]
	s_setprio 0
	s_barrier
	s_add_i32 s28, s65, s21
	v_lshl_add_u64 v[146:147], s[54:55], 0, v[130:131]
	s_mov_b32 m0, s28
	ds_read_b128 v[186:189], v152 offset:16384
	ds_read_b128 v[190:193], v152 offset:17408
	ds_read_b128 v[194:197], v152 offset:18432
	ds_read_b128 v[198:201], v152 offset:19456
	ds_read_b128 v[202:205], v152 offset:20480
	ds_read_b128 v[206:209], v152 offset:21504
	ds_read_b128 v[210:213], v152 offset:22528
	ds_read_b128 v[214:217], v152 offset:23552
	global_load_lds_dwordx4 v[146:147], off
	s_add_i32 m0, s28, 0x2000
	s_add_u32 s76, s54, 0x160000
	v_lshl_add_u64 v[218:219], s[54:55], 0, v[132:133]
	s_addc_u32 s77, s55, 0
	s_add_i32 s28, s66, s21
	global_load_lds_dwordx4 v[218:219], off
	v_lshl_add_u64 v[220:221], s[76:77], 0, v[130:131]
	s_mov_b32 m0, s28
	v_lshl_add_u64 v[222:223], s[56:57], 0, v[132:133]
	global_load_lds_dwordx4 v[220:221], off
	v_lshl_add_u64 v[220:221], s[76:77], 0, v[132:133]
	s_add_i32 m0, s28, 0x2000
	s_nop 0
	global_load_lds_dwordx4 v[220:221], off
	v_lshl_add_u64 v[220:221], s[56:57], 0, v[130:131]
	s_mov_b32 m0, s23
	s_nop 0
	global_load_lds_dwordx4 v[220:221], off
	s_mov_b32 m0, s33
	s_nop 0
	global_load_lds_dwordx4 v[222:223], off
	s_waitcnt vmcnt(8)
	s_waitcnt lgkmcnt(0)
	s_barrier
; #define PG8_STAGEA(bufoff, gbase, voff) PG8_STAGE_X(bufoff, gbase, voff, PG8_AUX_A)
; #define PG8_LDA(dst, b, h) do { _Pragma("unroll") for (int m = 0; m < 4; ++m) _Pragma("unroll") for (int k = 0; k < 2; ++k) dst[m][k] = *(const PG8_LAS bf16x8*)(lds + PG8_SA(b, h) + aoff + m * 2048 + k * 1024); } while (0)
; #define PG8_LDB(dst, b, h) do { _Pragma("unroll") for (int n = 0; n < 2; ++n) _Pragma("unroll") for (int k = 0; k < 2; ++k) dst[n][k] = *(const PG8_LAS bf16x8*)(lds + PG8_SB(b, h) + boff + n * 2048 + k * 1024); } while (0)
; #define PG8_MMA(ai, bj, At, Bt) do { __builtin_amdgcn_s_setprio(1); _Pragma("unroll") for (int m = 0; m < 4; ++m) _Pragma("unroll") for (int n = 0; n < 2; ++n) _Pragma("unroll") for (int k = 0; k < 2; ++k) \
;         acc[ai][bj][m][n] = __builtin_amdgcn_mfma_f32_16x16x32_bf16(Bt[n][k], At[m][k], acc[ai][bj][m][n], 0, 0, 0); __builtin_amdgcn_s_setprio(0); } while (0)
; #define PG8_WAIT_V(n) asm volatile("s_waitcnt vmcnt(" #n ")" ::: "memory")
; #define PG8_WAIT_L(n) asm volatile("s_waitcnt lgkmcnt(" #n ")" ::: "memory")
; #define PG8_BAR __builtin_amdgcn_s_barrier()
; #define PG8_SCHED __builtin_amdgcn_sched_barrier(0)
; template <class Epi, class Sched, bool ALIGN_EPI = false, bool SP2 = false>
; __device__ __forceinline__ void gemm_phase(PG8_LAS unsigned char* lds, const Gemm g, const Sched& S, const Epi& E) {
;     ...
;             PG8_WAIT_V(8); PG8_WAIT_L(0); PG8_BAR; PG8_MMA(1, 0, At, B0); PG8_MMA(1, 1, At, B1); PG8_BAR; PG8_SCHED;
;             PG8_LDB(B0, 1, 0); PG8_LDB(B1, 1, 1); PG8_SCHED; PG8_LDA(At, 1, 0); PG8_STAGEA(PG8_SA(0, 1), a2 + hstep, voffA);
;             PG8_WAIT_V(8); PG8_WAIT_L(0); PG8_BAR; PG8_MMA(0, 0, At, B0); PG8_MMA(0, 1, At, B1); PG8_BAR; PG8_SCHED;
	s_setprio 1
	s_waitcnt lgkmcnt(0)
	.p2align 3
	v_mfma_f32_16x16x32_bf16 v[62:65], v[154:157], v[186:189], v[62:65]
	v_mfma_f32_16x16x32_bf16 v[58:61], v[162:165], v[186:189], v[58:61]
	v_mfma_f32_16x16x32_bf16 v[46:49], v[154:157], v[194:197], v[46:49]
	v_mfma_f32_16x16x32_bf16 v[42:45], v[162:165], v[194:197], v[42:45]
	v_mfma_f32_16x16x32_bf16 v[30:33], v[154:157], v[202:205], v[30:33]
	v_mfma_f32_16x16x32_bf16 v[26:29], v[162:165], v[202:205], v[26:29]
	v_mfma_f32_16x16x32_bf16 v[14:17], v[154:157], v[210:213], v[14:17]
	v_mfma_f32_16x16x32_bf16 v[10:13], v[162:165], v[210:213], v[10:13]
	v_mfma_f32_16x16x32_bf16 v[62:65], v[158:161], v[190:193], v[62:65]
	v_mfma_f32_16x16x32_bf16 v[58:61], v[166:169], v[190:193], v[58:61]
	v_mfma_f32_16x16x32_bf16 v[46:49], v[158:161], v[198:201], v[46:49]
	v_mfma_f32_16x16x32_bf16 v[42:45], v[166:169], v[198:201], v[42:45]
	v_mfma_f32_16x16x32_bf16 v[30:33], v[158:161], v[206:209], v[30:33]
	v_mfma_f32_16x16x32_bf16 v[26:29], v[166:169], v[206:209], v[26:29]
	v_mfma_f32_16x16x32_bf16 v[14:17], v[158:161], v[214:217], v[14:17]
	v_mfma_f32_16x16x32_bf16 v[10:13], v[166:169], v[214:217], v[10:13]
	s_setprio 0
	s_setprio 1
	.p2align 3
	v_mfma_f32_16x16x32_bf16 v[54:57], v[170:173], v[186:189], v[54:57]
	v_mfma_f32_16x16x32_bf16 v[50:53], v[178:181], v[186:189], v[50:53]
	v_mfma_f32_16x16x32_bf16 v[38:41], v[170:173], v[194:197], v[38:41]
	v_mfma_f32_16x16x32_bf16 v[34:37], v[178:181], v[194:197], v[34:37]
	v_mfma_f32_16x16x32_bf16 v[22:25], v[170:173], v[202:205], v[22:25]
	v_mfma_f32_16x16x32_bf16 v[18:21], v[178:181], v[202:205], v[18:21]
	v_mfma_f32_16x16x32_bf16 v[6:9], v[170:173], v[210:213], v[6:9]
	v_mfma_f32_16x16x32_bf16 v[2:5], v[178:181], v[210:213], v[2:5]
	v_mfma_f32_16x16x32_bf16 v[54:57], v[174:177], v[190:193], v[54:57]
	v_mfma_f32_16x16x32_bf16 v[50:53], v[182:185], v[190:193], v[50:53]
	v_mfma_f32_16x16x32_bf16 v[38:41], v[174:177], v[198:201], v[38:41]
	v_mfma_f32_16x16x32_bf16 v[34:37], v[182:185], v[198:201], v[34:37]
	v_mfma_f32_16x16x32_bf16 v[22:25], v[174:177], v[206:209], v[22:25]
	v_mfma_f32_16x16x32_bf16 v[18:21], v[182:185], v[206:209], v[18:21]
	v_mfma_f32_16x16x32_bf16 v[6:9], v[174:177], v[214:217], v[6:9]
	v_mfma_f32_16x16x32_bf16 v[2:5], v[182:185], v[214:217], v[2:5]
	s_setprio 0
	s_barrier
	s_add_i32 s28, 0, 0x18000
	v_add_u32_e32 v153, s28, v148
	s_add_i32 s29, 0, 0x1c000
	ds_read_b128 v[154:157], v153
	ds_read_b128 v[158:161], v153 offset:1024
	ds_read_b128 v[162:165], v153 offset:2048
	ds_read_b128 v[166:169], v153 offset:3072
	v_add_u32_e32 v153, s29, v148
	ds_read_b128 v[170:173], v153
	ds_read_b128 v[174:177], v153 offset:1024
	ds_read_b128 v[178:181], v153 offset:2048
	ds_read_b128 v[182:185], v153 offset:3072
	s_add_u32 s56, s56, 0x160000
	s_addc_u32 s57, s57, 0
	s_mov_b32 m0, s58
	v_lshl_add_u64 v[224:225], s[56:57], 0, v[130:131]
	ds_read_b128 v[186:189], v152 offset:32768
	ds_read_b128 v[190:193], v152 offset:33792
	ds_read_b128 v[194:197], v152 offset:34816
	ds_read_b128 v[198:201], v152 offset:35840
	ds_read_b128 v[202:205], v152 offset:36864
	ds_read_b128 v[206:209], v152 offset:37888
	ds_read_b128 v[210:213], v152 offset:38912
	ds_read_b128 v[214:217], v152 offset:39936
	global_load_lds_dwordx4 v[224:225], off
	v_lshl_add_u64 v[224:225], s[56:57], 0, v[132:133]
	s_mov_b32 m0, s59
	s_nop 0
	global_load_lds_dwordx4 v[224:225], off
	s_waitcnt vmcnt(8)
	s_waitcnt lgkmcnt(0)
	s_barrier
	s_setprio 1
	s_waitcnt lgkmcnt(0)
	.p2align 3
	v_mfma_f32_16x16x32_bf16 v[126:129], v[154:157], v[186:189], v[126:129]
	v_mfma_f32_16x16x32_bf16 v[122:125], v[162:165], v[186:189], v[122:125]
	v_mfma_f32_16x16x32_bf16 v[114:117], v[154:157], v[194:197], v[114:117]
	v_mfma_f32_16x16x32_bf16 v[106:109], v[162:165], v[194:197], v[106:109]
	v_mfma_f32_16x16x32_bf16 v[94:97], v[154:157], v[202:205], v[94:97]
	v_mfma_f32_16x16x32_bf16 v[90:93], v[162:165], v[202:205], v[90:93]
	v_mfma_f32_16x16x32_bf16 v[78:81], v[154:157], v[210:213], v[78:81]
	v_mfma_f32_16x16x32_bf16 v[74:77], v[162:165], v[210:213], v[74:77]
	v_mfma_f32_16x16x32_bf16 v[126:129], v[158:161], v[190:193], v[126:129]
	v_mfma_f32_16x16x32_bf16 v[122:125], v[166:169], v[190:193], v[122:125]
	v_mfma_f32_16x16x32_bf16 v[114:117], v[158:161], v[198:201], v[114:117]
	v_mfma_f32_16x16x32_bf16 v[106:109], v[166:169], v[198:201], v[106:109]
	v_mfma_f32_16x16x32_bf16 v[94:97], v[158:161], v[206:209], v[94:97]
	v_mfma_f32_16x16x32_bf16 v[90:93], v[166:169], v[206:209], v[90:93]
	v_mfma_f32_16x16x32_bf16 v[78:81], v[158:161], v[214:217], v[78:81]
	v_mfma_f32_16x16x32_bf16 v[74:77], v[166:169], v[214:217], v[74:77]
	s_setprio 0
	s_setprio 1
	.p2align 3
	v_mfma_f32_16x16x32_bf16 v[118:121], v[170:173], v[186:189], v[118:121]
	v_mfma_f32_16x16x32_bf16 v[110:113], v[178:181], v[186:189], v[110:113]
	v_mfma_f32_16x16x32_bf16 v[102:105], v[170:173], v[194:197], v[102:105]
	v_mfma_f32_16x16x32_bf16 v[98:101], v[178:181], v[194:197], v[98:101]
	v_mfma_f32_16x16x32_bf16 v[86:89], v[170:173], v[202:205], v[86:89]
	v_mfma_f32_16x16x32_bf16 v[82:85], v[178:181], v[202:205], v[82:85]
	v_mfma_f32_16x16x32_bf16 v[70:73], v[170:173], v[210:213], v[70:73]
	v_mfma_f32_16x16x32_bf16 v[66:69], v[178:181], v[210:213], v[66:69]
	v_mfma_f32_16x16x32_bf16 v[118:121], v[174:177], v[190:193], v[118:121]
	v_mfma_f32_16x16x32_bf16 v[110:113], v[182:185], v[190:193], v[110:113]
	v_mfma_f32_16x16x32_bf16 v[102:105], v[174:177], v[198:201], v[102:105]
	v_mfma_f32_16x16x32_bf16 v[98:101], v[182:185], v[198:201], v[98:101]
	v_mfma_f32_16x16x32_bf16 v[86:89], v[174:177], v[206:209], v[86:89]
	v_mfma_f32_16x16x32_bf16 v[82:85], v[182:185], v[206:209], v[82:85]
	v_mfma_f32_16x16x32_bf16 v[70:73], v[174:177], v[214:217], v[70:73]
	v_mfma_f32_16x16x32_bf16 v[66:69], v[182:185], v[214:217], v[66:69]
	s_setprio 0
	s_barrier
; #define PG8_STAGEA(bufoff, gbase, voff) PG8_STAGE_X(bufoff, gbase, voff, PG8_AUX_A)
; #define PG8_STAGEB(bufoff, gbase, voff) PG8_STAGE_X(bufoff, gbase, voff, PG8_AUX_B)
; #define PG8_LDA(dst, b, h) do { _Pragma("unroll") for (int m = 0; m < 4; ++m) _Pragma("unroll") for (int k = 0; k < 2; ++k) dst[m][k] = *(const PG8_LAS bf16x8*)(lds + PG8_SA(b, h) + aoff + m * 2048 + k * 1024); } while (0)
; #define PG8_MMA(ai, bj, At, Bt) do { __builtin_amdgcn_s_setprio(1); _Pragma("unroll") for (int m = 0; m < 4; ++m) _Pragma("unroll") for (int n = 0; n < 2; ++n) _Pragma("unroll") for (int k = 0; k < 2; ++k) \
;         acc[ai][bj][m][n] = __builtin_amdgcn_mfma_f32_16x16x32_bf16(Bt[n][k], At[m][k], acc[ai][bj][m][n], 0, 0, 0); __builtin_amdgcn_s_setprio(0); } while (0)
; #define PG8_WAIT_V(n) asm volatile("s_waitcnt vmcnt(" #n ")" ::: "memory")
; #define PG8_WAIT_L(n) asm volatile("s_waitcnt lgkmcnt(" #n ")" ::: "memory")
; #define PG8_BAR __builtin_amdgcn_s_barrier()
; #define PG8_SCHED __builtin_amdgcn_sched_barrier(0)
; template <class Epi, class Sched, bool ALIGN_EPI = false, bool SP2 = false>
; __device__ __forceinline__ void gemm_phase(PG8_LAS unsigned char* lds, const Gemm g, const Sched& S, const Epi& E) {
;     ...
;             PG8_LDA(At, 1, 1); PG8_STAGEB(PG8_SB(1, 0), b3, voffB); PG8_STAGEB(PG8_SB(1, 1), b3 + hstep, voffB); PG8_STAGEA(PG8_SA(1, 0), a3, voffA);
;             PG8_WAIT_V(8); PG8_WAIT_L(0); PG8_BAR; PG8_MMA(1, 0, At, B0); PG8_MMA(1, 1, At, B1); PG8_BAR; PG8_SCHED;
	s_add_i32 s28, s28, s21
	v_lshl_add_u64 v[146:147], v[146:147], 0, s[34:35]
	s_mov_b32 m0, s28
	ds_read_b128 v[186:189], v152 offset:49152
	ds_read_b128 v[190:193], v152 offset:50176
	ds_read_b128 v[194:197], v152 offset:51200
	ds_read_b128 v[198:201], v152 offset:52224
	ds_read_b128 v[202:205], v152 offset:53248
	ds_read_b128 v[206:209], v152 offset:54272
	ds_read_b128 v[210:213], v152 offset:55296
	ds_read_b128 v[214:217], v152 offset:56320
	global_load_lds_dwordx4 v[146:147], off
	s_add_i32 m0, s28, 0x2000
	s_add_u32 s54, s54, 0x160080
	v_lshl_add_u64 v[146:147], v[218:219], 0, s[34:35]
	s_addc_u32 s55, s55, 0
	s_add_i32 s28, s29, s21
	global_load_lds_dwordx4 v[146:147], off
	v_lshl_add_u64 v[146:147], s[54:55], 0, v[130:131]
	s_mov_b32 m0, s28
	s_nop 0
	global_load_lds_dwordx4 v[146:147], off
	v_lshl_add_u64 v[146:147], s[54:55], 0, v[132:133]
	s_add_i32 m0, s28, 0x2000
	s_nop 0
	global_load_lds_dwordx4 v[146:147], off
	v_lshl_add_u64 v[146:147], v[220:221], 0, s[34:35]
	s_mov_b32 m0, s61
	s_nop 0
	global_load_lds_dwordx4 v[146:147], off
	v_lshl_add_u64 v[146:147], v[222:223], 0, s[34:35]
	s_mov_b32 m0, s62
	s_nop 0
	global_load_lds_dwordx4 v[146:147], off
	s_waitcnt vmcnt(8)
	s_waitcnt lgkmcnt(0)
	s_barrier
	s_setprio 1
	s_waitcnt lgkmcnt(0)
	.p2align 3
	v_mfma_f32_16x16x32_bf16 v[62:65], v[154:157], v[186:189], v[62:65]
	v_mfma_f32_16x16x32_bf16 v[58:61], v[162:165], v[186:189], v[58:61]
	v_mfma_f32_16x16x32_bf16 v[46:49], v[154:157], v[194:197], v[46:49]
	v_mfma_f32_16x16x32_bf16 v[42:45], v[162:165], v[194:197], v[42:45]
	v_mfma_f32_16x16x32_bf16 v[30:33], v[154:157], v[202:205], v[30:33]
	v_mfma_f32_16x16x32_bf16 v[26:29], v[162:165], v[202:205], v[26:29]
	v_mfma_f32_16x16x32_bf16 v[14:17], v[154:157], v[210:213], v[14:17]
	v_mfma_f32_16x16x32_bf16 v[10:13], v[162:165], v[210:213], v[10:13]
	v_mfma_f32_16x16x32_bf16 v[62:65], v[158:161], v[190:193], v[62:65]
	v_mfma_f32_16x16x32_bf16 v[58:61], v[166:169], v[190:193], v[58:61]
	v_mfma_f32_16x16x32_bf16 v[46:49], v[158:161], v[198:201], v[46:49]
	v_mfma_f32_16x16x32_bf16 v[42:45], v[166:169], v[198:201], v[42:45]
	v_mfma_f32_16x16x32_bf16 v[30:33], v[158:161], v[206:209], v[30:33]
	v_mfma_f32_16x16x32_bf16 v[26:29], v[166:169], v[206:209], v[26:29]
	v_mfma_f32_16x16x32_bf16 v[14:17], v[158:161], v[214:217], v[14:17]
	v_mfma_f32_16x16x32_bf16 v[10:13], v[166:169], v[214:217], v[10:13]
	s_setprio 0
	s_setprio 1
	.p2align 3
	v_mfma_f32_16x16x32_bf16 v[54:57], v[170:173], v[186:189], v[54:57]
	v_mfma_f32_16x16x32_bf16 v[50:53], v[178:181], v[186:189], v[50:53]
	v_mfma_f32_16x16x32_bf16 v[38:41], v[170:173], v[194:197], v[38:41]
	v_mfma_f32_16x16x32_bf16 v[34:37], v[178:181], v[194:197], v[34:37]
	v_mfma_f32_16x16x32_bf16 v[22:25], v[170:173], v[202:205], v[22:25]
	v_mfma_f32_16x16x32_bf16 v[18:21], v[178:181], v[202:205], v[18:21]
	v_mfma_f32_16x16x32_bf16 v[6:9], v[170:173], v[210:213], v[6:9]
	v_mfma_f32_16x16x32_bf16 v[2:5], v[178:181], v[210:213], v[2:5]
	v_mfma_f32_16x16x32_bf16 v[54:57], v[174:177], v[190:193], v[54:57]
	v_mfma_f32_16x16x32_bf16 v[50:53], v[182:185], v[190:193], v[50:53]
	v_mfma_f32_16x16x32_bf16 v[38:41], v[174:177], v[198:201], v[38:41]
	v_mfma_f32_16x16x32_bf16 v[34:37], v[182:185], v[198:201], v[34:37]
	v_mfma_f32_16x16x32_bf16 v[22:25], v[174:177], v[206:209], v[22:25]
	v_mfma_f32_16x16x32_bf16 v[18:21], v[182:185], v[206:209], v[18:21]
	v_mfma_f32_16x16x32_bf16 v[6:9], v[174:177], v[214:217], v[6:9]
	v_mfma_f32_16x16x32_bf16 v[2:5], v[182:185], v[214:217], v[2:5]
	s_setprio 0
	s_barrier
	s_add_u32 s52, s52, 0x100
	s_addc_u32 s53, s53, 0
	s_mov_b32 s54, s75
	s_cbranch_vccz .LBB0_1090
	s_and_b64 vcc, exec, s[36:37]
	s_cbranch_vccz .LBB0_1093
	s_barrier
